# staggered attention halves (V triple-buffered), modulation GEMV 8-stage load pipeline, hyena tap loop 4-stage load pipeline
# speedup vs baseline: 1.0499x; 1.0332x over previous
.LBB0_287:
	s_or_b64 exec, exec, s[6:7]
	s_mul_hi_i32 s6, s19, 0x2aaaaaab
	s_lshr_b32 s7, s6, 31
	s_ashr_i32 s6, s6, 4
	s_add_i32 s6, s6, s7
	s_mul_i32 s7, s6, 0x60
	s_sub_i32 s7, s19, s7
	v_ashrrev_i32_e32 v5, 6, v4
	v_and_b32_e32 v2, 63, v4
	v_lshl_or_b32 v6, s7, 6, v2
	s_ashr_i32 s7, s6, 31
	v_lshlrev_b32_e32 v8, 9, v5
	s_lshl_b64 s[8:9], s[6:7], 11
	v_ashrrev_i32_e32 v9, 31, v8
	v_lshl_add_u64 v[8:9], s[8:9], 0, v[8:9]
	v_mov_b64_e32 v[10:11], s[30:31]
	v_mad_u64_u32 v[10:11], s[8:9], v8, s97, v[10:11]
	v_mad_i32_i24 v11, v9, s97, v11
	v_ashrrev_i32_e32 v7, 31, v6
	v_lshl_add_u64 v[8:9], v[6:7], 2, v[10:11]
	v_mov_b32_e32 v10, 0
	v_lshl_add_u32 v14, v5, 11, s33
	s_mov_b64 s[8:9], 0
	v_mov_b32_e32 v11, v10
	v_mov_b32_e32 v12, v10
	v_mov_b32_e32 v13, v10
	v_mov_b32_e32 v15, v10
	v_readfirstlane_b32 s8, v8
	v_readfirstlane_b32 s9, v9
	v_lshlrev_b32_e32 v8, 2, v2
	s_nop 4
	global_load_dword v88, v8, s[8:9]
	s_add_u32 s8, s8, 0x6000
	s_addc_u32 s9, s9, 0
	global_load_dword v89, v8, s[8:9]
	s_add_u32 s8, s8, 0x6000
	s_addc_u32 s9, s9, 0
	global_load_dword v90, v8, s[8:9]
	s_add_u32 s8, s8, 0x6000
	s_addc_u32 s9, s9, 0
	global_load_dword v91, v8, s[8:9]
	s_add_u32 s8, s8, 0x6000
	s_addc_u32 s9, s9, 0
	global_load_dword v92, v8, s[8:9]
	s_add_u32 s8, s8, 0x6000
	s_addc_u32 s9, s9, 0
	global_load_dword v93, v8, s[8:9]
	s_add_u32 s8, s8, 0x6000
	s_addc_u32 s9, s9, 0
	global_load_dword v94, v8, s[8:9]
	s_add_u32 s8, s8, 0x6000
	s_addc_u32 s9, s9, 0
	global_load_dword v95, v8, s[8:9]
	s_add_u32 s8, s8, 0x6000
	s_addc_u32 s9, s9, 0
	global_load_dword v96, v8, s[8:9]
	s_add_u32 s8, s8, 0x6000
	s_addc_u32 s9, s9, 0
	global_load_dword v97, v8, s[8:9]
	s_add_u32 s8, s8, 0x6000
	s_addc_u32 s9, s9, 0
	global_load_dword v98, v8, s[8:9]
	s_add_u32 s8, s8, 0x6000
	s_addc_u32 s9, s9, 0
	global_load_dword v99, v8, s[8:9]
	s_add_u32 s8, s8, 0x6000
	s_addc_u32 s9, s9, 0
	global_load_dword v100, v8, s[8:9]
	s_add_u32 s8, s8, 0x6000
	s_addc_u32 s9, s9, 0
	global_load_dword v101, v8, s[8:9]
	s_add_u32 s8, s8, 0x6000
	s_addc_u32 s9, s9, 0
	global_load_dword v102, v8, s[8:9]
	s_add_u32 s8, s8, 0x6000
	s_addc_u32 s9, s9, 0
	global_load_dword v103, v8, s[8:9]
	s_add_u32 s8, s8, 0x6000
	s_addc_u32 s9, s9, 0
	global_load_dword v104, v8, s[8:9]
	s_add_u32 s8, s8, 0x6000
	s_addc_u32 s9, s9, 0
	global_load_dword v105, v8, s[8:9]
	s_add_u32 s8, s8, 0x6000
	s_addc_u32 s9, s9, 0
	global_load_dword v106, v8, s[8:9]
	s_add_u32 s8, s8, 0x6000
	s_addc_u32 s9, s9, 0
	global_load_dword v107, v8, s[8:9]
	s_add_u32 s8, s8, 0x6000
	s_addc_u32 s9, s9, 0
	global_load_dword v108, v8, s[8:9]
	s_add_u32 s8, s8, 0x6000
	s_addc_u32 s9, s9, 0
	global_load_dword v109, v8, s[8:9]
	s_add_u32 s8, s8, 0x6000
	s_addc_u32 s9, s9, 0
	global_load_dword v110, v8, s[8:9]
	s_add_u32 s8, s8, 0x6000
	s_addc_u32 s9, s9, 0
	global_load_dword v111, v8, s[8:9]
	s_add_u32 s8, s8, 0x6000
	s_addc_u32 s9, s9, 0
	global_load_dword v112, v8, s[8:9]
	s_add_u32 s8, s8, 0x6000
	s_addc_u32 s9, s9, 0
	global_load_dword v113, v8, s[8:9]
	s_add_u32 s8, s8, 0x6000
	s_addc_u32 s9, s9, 0
	global_load_dword v114, v8, s[8:9]
	s_add_u32 s8, s8, 0x6000
	s_addc_u32 s9, s9, 0
	global_load_dword v115, v8, s[8:9]
	s_add_u32 s8, s8, 0x6000
	s_addc_u32 s9, s9, 0
	global_load_dword v116, v8, s[8:9]
	s_add_u32 s8, s8, 0x6000
	s_addc_u32 s9, s9, 0
	global_load_dword v117, v8, s[8:9]
	s_add_u32 s8, s8, 0x6000
	s_addc_u32 s9, s9, 0
	global_load_dword v118, v8, s[8:9]
	s_add_u32 s8, s8, 0x6000
	s_addc_u32 s9, s9, 0
	global_load_dword v119, v8, s[8:9]
	s_add_u32 s8, s8, 0x6000
	s_addc_u32 s9, s9, 0
	global_load_dword v120, v8, s[8:9]
	s_add_u32 s8, s8, 0x6000
	s_addc_u32 s9, s9, 0
	global_load_dword v121, v8, s[8:9]
	s_add_u32 s8, s8, 0x6000
	s_addc_u32 s9, s9, 0
	global_load_dword v122, v8, s[8:9]
	s_add_u32 s8, s8, 0x6000
	s_addc_u32 s9, s9, 0
	global_load_dword v123, v8, s[8:9]
	s_add_u32 s8, s8, 0x6000
	s_addc_u32 s9, s9, 0
	global_load_dword v124, v8, s[8:9]
	s_add_u32 s8, s8, 0x6000
	s_addc_u32 s9, s9, 0
	global_load_dword v125, v8, s[8:9]
	s_add_u32 s8, s8, 0x6000
	s_addc_u32 s9, s9, 0
	global_load_dword v126, v8, s[8:9]
	s_add_u32 s8, s8, 0x6000
	s_addc_u32 s9, s9, 0
	global_load_dword v127, v8, s[8:9]
	s_add_u32 s8, s8, 0x6000
	s_addc_u32 s9, s9, 0
	global_load_dword v128, v8, s[8:9]
	s_add_u32 s8, s8, 0x6000
	s_addc_u32 s9, s9, 0
	global_load_dword v129, v8, s[8:9]
	s_add_u32 s8, s8, 0x6000
	s_addc_u32 s9, s9, 0
	global_load_dword v130, v8, s[8:9]
	s_add_u32 s8, s8, 0x6000
	s_addc_u32 s9, s9, 0
	global_load_dword v131, v8, s[8:9]
	s_add_u32 s8, s8, 0x6000
	s_addc_u32 s9, s9, 0
	global_load_dword v132, v8, s[8:9]
	s_add_u32 s8, s8, 0x6000
	s_addc_u32 s9, s9, 0
	global_load_dword v133, v8, s[8:9]
	s_add_u32 s8, s8, 0x6000
	s_addc_u32 s9, s9, 0
	global_load_dword v134, v8, s[8:9]
	s_add_u32 s8, s8, 0x6000
	s_addc_u32 s9, s9, 0
	global_load_dword v135, v8, s[8:9]
	s_add_u32 s8, s8, 0x6000
	s_addc_u32 s9, s9, 0
	global_load_dword v136, v8, s[8:9]
	s_add_u32 s8, s8, 0x6000
	s_addc_u32 s9, s9, 0
	global_load_dword v137, v8, s[8:9]
	s_add_u32 s8, s8, 0x6000
	s_addc_u32 s9, s9, 0
	global_load_dword v138, v8, s[8:9]
	s_add_u32 s8, s8, 0x6000
	s_addc_u32 s9, s9, 0
	global_load_dword v139, v8, s[8:9]
	s_add_u32 s8, s8, 0x6000
	s_addc_u32 s9, s9, 0
	global_load_dword v140, v8, s[8:9]
	s_add_u32 s8, s8, 0x6000
	s_addc_u32 s9, s9, 0
	global_load_dword v141, v8, s[8:9]
	s_add_u32 s8, s8, 0x6000
	s_addc_u32 s9, s9, 0
	global_load_dword v142, v8, s[8:9]
	s_add_u32 s8, s8, 0x6000
	s_addc_u32 s9, s9, 0
	global_load_dword v143, v8, s[8:9]
	s_add_u32 s8, s8, 0x6000
	s_addc_u32 s9, s9, 0
	ds_read_b128 v[168:171], v14 offset:0
	ds_read_b128 v[172:175], v14 offset:16
	ds_read_b128 v[176:179], v14 offset:8192
	ds_read_b128 v[180:183], v14 offset:8208
	ds_read_b128 v[184:187], v14 offset:16384
	ds_read_b128 v[188:191], v14 offset:16400
	ds_read_b128 v[192:195], v14 offset:24576
	ds_read_b128 v[196:199], v14 offset:24592
	ds_read_b128 v[200:203], v14 offset:32768
	ds_read_b128 v[204:207], v14 offset:32784
	s_mov_b32 s7, 0
.Lmod_loop:
	s_waitcnt vmcnt(48)
	global_load_dword v144, v8, s[8:9]
	s_add_u32 s8, s8, 0x6000
	s_addc_u32 s9, s9, 0
	global_load_dword v145, v8, s[8:9]
	s_add_u32 s8, s8, 0x6000
	s_addc_u32 s9, s9, 0
	global_load_dword v146, v8, s[8:9]
	s_add_u32 s8, s8, 0x6000
	s_addc_u32 s9, s9, 0
	global_load_dword v147, v8, s[8:9]
	s_add_u32 s8, s8, 0x6000
	s_addc_u32 s9, s9, 0
	global_load_dword v148, v8, s[8:9]
	s_add_u32 s8, s8, 0x6000
	s_addc_u32 s9, s9, 0
	global_load_dword v149, v8, s[8:9]
	s_add_u32 s8, s8, 0x6000
	s_addc_u32 s9, s9, 0
	global_load_dword v150, v8, s[8:9]
	s_add_u32 s8, s8, 0x6000
	s_addc_u32 s9, s9, 0
	global_load_dword v151, v8, s[8:9]
	s_add_u32 s8, s8, 0x6000
	s_addc_u32 s9, s9, 0
	s_waitcnt lgkmcnt(0)
	ds_read_b128 v[208:211], v14 offset:32
	ds_read_b128 v[212:215], v14 offset:48
	ds_read_b128 v[216:219], v14 offset:8224
	ds_read_b128 v[220:223], v14 offset:8240
	ds_read_b128 v[224:227], v14 offset:16416
	ds_read_b128 v[228:231], v14 offset:16432
	ds_read_b128 v[232:235], v14 offset:24608
	ds_read_b128 v[236:239], v14 offset:24624
	ds_read_b128 v[240:243], v14 offset:32800
	ds_read_b128 v[244:247], v14 offset:32816
	v_fmac_f32_e32 v10, v88, v168
	v_fmac_f32_e32 v11, v88, v176
	v_fmac_f32_e32 v12, v88, v184
	v_fmac_f32_e32 v13, v88, v192
	v_fmac_f32_e32 v15, v88, v200
	v_fmac_f32_e32 v10, v89, v169
	v_fmac_f32_e32 v11, v89, v177
	v_fmac_f32_e32 v12, v89, v185
	v_fmac_f32_e32 v13, v89, v193
	v_fmac_f32_e32 v15, v89, v201
	v_fmac_f32_e32 v10, v90, v170
	v_fmac_f32_e32 v11, v90, v178
	v_fmac_f32_e32 v12, v90, v186
	v_fmac_f32_e32 v13, v90, v194
	v_fmac_f32_e32 v15, v90, v202
	v_fmac_f32_e32 v10, v91, v171
	v_fmac_f32_e32 v11, v91, v179
	v_fmac_f32_e32 v12, v91, v187
	v_fmac_f32_e32 v13, v91, v195
	v_fmac_f32_e32 v15, v91, v203
	v_fmac_f32_e32 v10, v92, v172
	v_fmac_f32_e32 v11, v92, v180
	v_fmac_f32_e32 v12, v92, v188
	v_fmac_f32_e32 v13, v92, v196
	v_fmac_f32_e32 v15, v92, v204
	v_fmac_f32_e32 v10, v93, v173
	v_fmac_f32_e32 v11, v93, v181
	v_fmac_f32_e32 v12, v93, v189
	v_fmac_f32_e32 v13, v93, v197
	v_fmac_f32_e32 v15, v93, v205
	v_fmac_f32_e32 v10, v94, v174
	v_fmac_f32_e32 v11, v94, v182
	v_fmac_f32_e32 v12, v94, v190
	v_fmac_f32_e32 v13, v94, v198
	v_fmac_f32_e32 v15, v94, v206
	v_fmac_f32_e32 v10, v95, v175
	v_fmac_f32_e32 v11, v95, v183
	v_fmac_f32_e32 v12, v95, v191
	v_fmac_f32_e32 v13, v95, v199
	v_fmac_f32_e32 v15, v95, v207
	s_waitcnt vmcnt(48)
	global_load_dword v88, v8, s[8:9]
	s_add_u32 s8, s8, 0x6000
	s_addc_u32 s9, s9, 0
	global_load_dword v89, v8, s[8:9]
	s_add_u32 s8, s8, 0x6000
	s_addc_u32 s9, s9, 0
	global_load_dword v90, v8, s[8:9]
	s_add_u32 s8, s8, 0x6000
	s_addc_u32 s9, s9, 0
	global_load_dword v91, v8, s[8:9]
	s_add_u32 s8, s8, 0x6000
	s_addc_u32 s9, s9, 0
	global_load_dword v92, v8, s[8:9]
	s_add_u32 s8, s8, 0x6000
	s_addc_u32 s9, s9, 0
	global_load_dword v93, v8, s[8:9]
	s_add_u32 s8, s8, 0x6000
	s_addc_u32 s9, s9, 0
	global_load_dword v94, v8, s[8:9]
	s_add_u32 s8, s8, 0x6000
	s_addc_u32 s9, s9, 0
	global_load_dword v95, v8, s[8:9]
	s_add_u32 s8, s8, 0x6000
	s_addc_u32 s9, s9, 0
	s_waitcnt lgkmcnt(0)
	ds_read_b128 v[168:171], v14 offset:64
	ds_read_b128 v[172:175], v14 offset:80
	ds_read_b128 v[176:179], v14 offset:8256
	ds_read_b128 v[180:183], v14 offset:8272
	ds_read_b128 v[184:187], v14 offset:16448
	ds_read_b128 v[188:191], v14 offset:16464
	ds_read_b128 v[192:195], v14 offset:24640
	ds_read_b128 v[196:199], v14 offset:24656
	ds_read_b128 v[200:203], v14 offset:32832
	ds_read_b128 v[204:207], v14 offset:32848
	v_fmac_f32_e32 v10, v96, v208
	v_fmac_f32_e32 v11, v96, v216
	v_fmac_f32_e32 v12, v96, v224
	v_fmac_f32_e32 v13, v96, v232
	v_fmac_f32_e32 v15, v96, v240
	v_fmac_f32_e32 v10, v97, v209
	v_fmac_f32_e32 v11, v97, v217
	v_fmac_f32_e32 v12, v97, v225
	v_fmac_f32_e32 v13, v97, v233
	v_fmac_f32_e32 v15, v97, v241
	v_fmac_f32_e32 v10, v98, v210
	v_fmac_f32_e32 v11, v98, v218
	v_fmac_f32_e32 v12, v98, v226
	v_fmac_f32_e32 v13, v98, v234
	v_fmac_f32_e32 v15, v98, v242
	v_fmac_f32_e32 v10, v99, v211
	v_fmac_f32_e32 v11, v99, v219
	v_fmac_f32_e32 v12, v99, v227
	v_fmac_f32_e32 v13, v99, v235
	v_fmac_f32_e32 v15, v99, v243
	v_fmac_f32_e32 v10, v100, v212
	v_fmac_f32_e32 v11, v100, v220
	v_fmac_f32_e32 v12, v100, v228
	v_fmac_f32_e32 v13, v100, v236
	v_fmac_f32_e32 v15, v100, v244
	v_fmac_f32_e32 v10, v101, v213
	v_fmac_f32_e32 v11, v101, v221
	v_fmac_f32_e32 v12, v101, v229
	v_fmac_f32_e32 v13, v101, v237
	v_fmac_f32_e32 v15, v101, v245
	v_fmac_f32_e32 v10, v102, v214
	v_fmac_f32_e32 v11, v102, v222
	v_fmac_f32_e32 v12, v102, v230
	v_fmac_f32_e32 v13, v102, v238
	v_fmac_f32_e32 v15, v102, v246
	v_fmac_f32_e32 v10, v103, v215
	v_fmac_f32_e32 v11, v103, v223
	v_fmac_f32_e32 v12, v103, v231
	v_fmac_f32_e32 v13, v103, v239
	v_fmac_f32_e32 v15, v103, v247
	s_waitcnt vmcnt(48)
	global_load_dword v96, v8, s[8:9]
	s_add_u32 s8, s8, 0x6000
	s_addc_u32 s9, s9, 0
	global_load_dword v97, v8, s[8:9]
	s_add_u32 s8, s8, 0x6000
	s_addc_u32 s9, s9, 0
	global_load_dword v98, v8, s[8:9]
	s_add_u32 s8, s8, 0x6000
	s_addc_u32 s9, s9, 0
	global_load_dword v99, v8, s[8:9]
	s_add_u32 s8, s8, 0x6000
	s_addc_u32 s9, s9, 0
	global_load_dword v100, v8, s[8:9]
	s_add_u32 s8, s8, 0x6000
	s_addc_u32 s9, s9, 0
	global_load_dword v101, v8, s[8:9]
	s_add_u32 s8, s8, 0x6000
	s_addc_u32 s9, s9, 0
	global_load_dword v102, v8, s[8:9]
	s_add_u32 s8, s8, 0x6000
	s_addc_u32 s9, s9, 0
	global_load_dword v103, v8, s[8:9]
	s_add_u32 s8, s8, 0x6000
	s_addc_u32 s9, s9, 0
	s_waitcnt lgkmcnt(0)
	ds_read_b128 v[208:211], v14 offset:96
	ds_read_b128 v[212:215], v14 offset:112
	ds_read_b128 v[216:219], v14 offset:8288
	ds_read_b128 v[220:223], v14 offset:8304
	ds_read_b128 v[224:227], v14 offset:16480
	ds_read_b128 v[228:231], v14 offset:16496
	ds_read_b128 v[232:235], v14 offset:24672
	ds_read_b128 v[236:239], v14 offset:24688
	ds_read_b128 v[240:243], v14 offset:32864
	ds_read_b128 v[244:247], v14 offset:32880
	v_fmac_f32_e32 v10, v104, v168
	v_fmac_f32_e32 v11, v104, v176
	v_fmac_f32_e32 v12, v104, v184
	v_fmac_f32_e32 v13, v104, v192
	v_fmac_f32_e32 v15, v104, v200
	v_fmac_f32_e32 v10, v105, v169
	v_fmac_f32_e32 v11, v105, v177
	v_fmac_f32_e32 v12, v105, v185
	v_fmac_f32_e32 v13, v105, v193
	v_fmac_f32_e32 v15, v105, v201
	v_fmac_f32_e32 v10, v106, v170
	v_fmac_f32_e32 v11, v106, v178
	v_fmac_f32_e32 v12, v106, v186
	v_fmac_f32_e32 v13, v106, v194
	v_fmac_f32_e32 v15, v106, v202
	v_fmac_f32_e32 v10, v107, v171
	v_fmac_f32_e32 v11, v107, v179
	v_fmac_f32_e32 v12, v107, v187
	v_fmac_f32_e32 v13, v107, v195
	v_fmac_f32_e32 v15, v107, v203
	v_fmac_f32_e32 v10, v108, v172
	v_fmac_f32_e32 v11, v108, v180
	v_fmac_f32_e32 v12, v108, v188
	v_fmac_f32_e32 v13, v108, v196
	v_fmac_f32_e32 v15, v108, v204
	v_fmac_f32_e32 v10, v109, v173
	v_fmac_f32_e32 v11, v109, v181
	v_fmac_f32_e32 v12, v109, v189
	v_fmac_f32_e32 v13, v109, v197
	v_fmac_f32_e32 v15, v109, v205
	v_fmac_f32_e32 v10, v110, v174
	v_fmac_f32_e32 v11, v110, v182
	v_fmac_f32_e32 v12, v110, v190
	v_fmac_f32_e32 v13, v110, v198
	v_fmac_f32_e32 v15, v110, v206
	v_fmac_f32_e32 v10, v111, v175
	v_fmac_f32_e32 v11, v111, v183
	v_fmac_f32_e32 v12, v111, v191
	v_fmac_f32_e32 v13, v111, v199
	v_fmac_f32_e32 v15, v111, v207
	s_waitcnt vmcnt(48)
	global_load_dword v104, v8, s[8:9]
	s_add_u32 s8, s8, 0x6000
	s_addc_u32 s9, s9, 0
	global_load_dword v105, v8, s[8:9]
	s_add_u32 s8, s8, 0x6000
	s_addc_u32 s9, s9, 0
	global_load_dword v106, v8, s[8:9]
	s_add_u32 s8, s8, 0x6000
	s_addc_u32 s9, s9, 0
	global_load_dword v107, v8, s[8:9]
	s_add_u32 s8, s8, 0x6000
	s_addc_u32 s9, s9, 0
	global_load_dword v108, v8, s[8:9]
	s_add_u32 s8, s8, 0x6000
	s_addc_u32 s9, s9, 0
	global_load_dword v109, v8, s[8:9]
	s_add_u32 s8, s8, 0x6000
	s_addc_u32 s9, s9, 0
	global_load_dword v110, v8, s[8:9]
	s_add_u32 s8, s8, 0x6000
	s_addc_u32 s9, s9, 0
	global_load_dword v111, v8, s[8:9]
	s_add_u32 s8, s8, 0x6000
	s_addc_u32 s9, s9, 0
	s_waitcnt lgkmcnt(0)
	ds_read_b128 v[168:171], v14 offset:128
	ds_read_b128 v[172:175], v14 offset:144
	ds_read_b128 v[176:179], v14 offset:8320
	ds_read_b128 v[180:183], v14 offset:8336
	ds_read_b128 v[184:187], v14 offset:16512
	ds_read_b128 v[188:191], v14 offset:16528
	ds_read_b128 v[192:195], v14 offset:24704
	ds_read_b128 v[196:199], v14 offset:24720
	ds_read_b128 v[200:203], v14 offset:32896
	ds_read_b128 v[204:207], v14 offset:32912
	v_fmac_f32_e32 v10, v112, v208
	v_fmac_f32_e32 v11, v112, v216
	v_fmac_f32_e32 v12, v112, v224
	v_fmac_f32_e32 v13, v112, v232
	v_fmac_f32_e32 v15, v112, v240
	v_fmac_f32_e32 v10, v113, v209
	v_fmac_f32_e32 v11, v113, v217
	v_fmac_f32_e32 v12, v113, v225
	v_fmac_f32_e32 v13, v113, v233
	v_fmac_f32_e32 v15, v113, v241
	v_fmac_f32_e32 v10, v114, v210
	v_fmac_f32_e32 v11, v114, v218
	v_fmac_f32_e32 v12, v114, v226
	v_fmac_f32_e32 v13, v114, v234
	v_fmac_f32_e32 v15, v114, v242
	v_fmac_f32_e32 v10, v115, v211
	v_fmac_f32_e32 v11, v115, v219
	v_fmac_f32_e32 v12, v115, v227
	v_fmac_f32_e32 v13, v115, v235
	v_fmac_f32_e32 v15, v115, v243
	v_fmac_f32_e32 v10, v116, v212
	v_fmac_f32_e32 v11, v116, v220
	v_fmac_f32_e32 v12, v116, v228
	v_fmac_f32_e32 v13, v116, v236
	v_fmac_f32_e32 v15, v116, v244
	v_fmac_f32_e32 v10, v117, v213
	v_fmac_f32_e32 v11, v117, v221
	v_fmac_f32_e32 v12, v117, v229
	v_fmac_f32_e32 v13, v117, v237
	v_fmac_f32_e32 v15, v117, v245
	v_fmac_f32_e32 v10, v118, v214
	v_fmac_f32_e32 v11, v118, v222
	v_fmac_f32_e32 v12, v118, v230
	v_fmac_f32_e32 v13, v118, v238
	v_fmac_f32_e32 v15, v118, v246
	v_fmac_f32_e32 v10, v119, v215
	v_fmac_f32_e32 v11, v119, v223
	v_fmac_f32_e32 v12, v119, v231
	v_fmac_f32_e32 v13, v119, v239
	v_fmac_f32_e32 v15, v119, v247
	s_waitcnt vmcnt(48)
	global_load_dword v112, v8, s[8:9]
	s_add_u32 s8, s8, 0x6000
	s_addc_u32 s9, s9, 0
	global_load_dword v113, v8, s[8:9]
	s_add_u32 s8, s8, 0x6000
	s_addc_u32 s9, s9, 0
	global_load_dword v114, v8, s[8:9]
	s_add_u32 s8, s8, 0x6000
	s_addc_u32 s9, s9, 0
	global_load_dword v115, v8, s[8:9]
	s_add_u32 s8, s8, 0x6000
	s_addc_u32 s9, s9, 0
	global_load_dword v116, v8, s[8:9]
	s_add_u32 s8, s8, 0x6000
	s_addc_u32 s9, s9, 0
	global_load_dword v117, v8, s[8:9]
	s_add_u32 s8, s8, 0x6000
	s_addc_u32 s9, s9, 0
	global_load_dword v118, v8, s[8:9]
	s_add_u32 s8, s8, 0x6000
	s_addc_u32 s9, s9, 0
	global_load_dword v119, v8, s[8:9]
	s_add_u32 s8, s8, 0x6000
	s_addc_u32 s9, s9, 0
	s_waitcnt lgkmcnt(0)
	ds_read_b128 v[208:211], v14 offset:160
	ds_read_b128 v[212:215], v14 offset:176
	ds_read_b128 v[216:219], v14 offset:8352
	ds_read_b128 v[220:223], v14 offset:8368
	ds_read_b128 v[224:227], v14 offset:16544
	ds_read_b128 v[228:231], v14 offset:16560
	ds_read_b128 v[232:235], v14 offset:24736
	ds_read_b128 v[236:239], v14 offset:24752
	ds_read_b128 v[240:243], v14 offset:32928
	ds_read_b128 v[244:247], v14 offset:32944
	v_fmac_f32_e32 v10, v120, v168
	v_fmac_f32_e32 v11, v120, v176
	v_fmac_f32_e32 v12, v120, v184
	v_fmac_f32_e32 v13, v120, v192
	v_fmac_f32_e32 v15, v120, v200
	v_fmac_f32_e32 v10, v121, v169
	v_fmac_f32_e32 v11, v121, v177
	v_fmac_f32_e32 v12, v121, v185
	v_fmac_f32_e32 v13, v121, v193
	v_fmac_f32_e32 v15, v121, v201
	v_fmac_f32_e32 v10, v122, v170
	v_fmac_f32_e32 v11, v122, v178
	v_fmac_f32_e32 v12, v122, v186
	v_fmac_f32_e32 v13, v122, v194
	v_fmac_f32_e32 v15, v122, v202
	v_fmac_f32_e32 v10, v123, v171
	v_fmac_f32_e32 v11, v123, v179
	v_fmac_f32_e32 v12, v123, v187
	v_fmac_f32_e32 v13, v123, v195
	v_fmac_f32_e32 v15, v123, v203
	v_fmac_f32_e32 v10, v124, v172
	v_fmac_f32_e32 v11, v124, v180
	v_fmac_f32_e32 v12, v124, v188
	v_fmac_f32_e32 v13, v124, v196
	v_fmac_f32_e32 v15, v124, v204
	v_fmac_f32_e32 v10, v125, v173
	v_fmac_f32_e32 v11, v125, v181
	v_fmac_f32_e32 v12, v125, v189
	v_fmac_f32_e32 v13, v125, v197
	v_fmac_f32_e32 v15, v125, v205
	v_fmac_f32_e32 v10, v126, v174
	v_fmac_f32_e32 v11, v126, v182
	v_fmac_f32_e32 v12, v126, v190
	v_fmac_f32_e32 v13, v126, v198
	v_fmac_f32_e32 v15, v126, v206
	v_fmac_f32_e32 v10, v127, v175
	v_fmac_f32_e32 v11, v127, v183
	v_fmac_f32_e32 v12, v127, v191
	v_fmac_f32_e32 v13, v127, v199
	v_fmac_f32_e32 v15, v127, v207
	s_waitcnt vmcnt(48)
	global_load_dword v120, v8, s[8:9]
	s_add_u32 s8, s8, 0x6000
	s_addc_u32 s9, s9, 0
	global_load_dword v121, v8, s[8:9]
	s_add_u32 s8, s8, 0x6000
	s_addc_u32 s9, s9, 0
	global_load_dword v122, v8, s[8:9]
	s_add_u32 s8, s8, 0x6000
	s_addc_u32 s9, s9, 0
	global_load_dword v123, v8, s[8:9]
	s_add_u32 s8, s8, 0x6000
	s_addc_u32 s9, s9, 0
	global_load_dword v124, v8, s[8:9]
	s_add_u32 s8, s8, 0x6000
	s_addc_u32 s9, s9, 0
	global_load_dword v125, v8, s[8:9]
	s_add_u32 s8, s8, 0x6000
	s_addc_u32 s9, s9, 0
	global_load_dword v126, v8, s[8:9]
	s_add_u32 s8, s8, 0x6000
	s_addc_u32 s9, s9, 0
	global_load_dword v127, v8, s[8:9]
	s_add_u32 s8, s8, 0x6000
	s_addc_u32 s9, s9, 0
	s_waitcnt lgkmcnt(0)
	ds_read_b128 v[168:171], v14 offset:192
	ds_read_b128 v[172:175], v14 offset:208
	ds_read_b128 v[176:179], v14 offset:8384
	ds_read_b128 v[180:183], v14 offset:8400
	ds_read_b128 v[184:187], v14 offset:16576
	ds_read_b128 v[188:191], v14 offset:16592
	ds_read_b128 v[192:195], v14 offset:24768
	ds_read_b128 v[196:199], v14 offset:24784
	ds_read_b128 v[200:203], v14 offset:32960
	ds_read_b128 v[204:207], v14 offset:32976
	v_fmac_f32_e32 v10, v128, v208
	v_fmac_f32_e32 v11, v128, v216
	v_fmac_f32_e32 v12, v128, v224
	v_fmac_f32_e32 v13, v128, v232
	v_fmac_f32_e32 v15, v128, v240
	v_fmac_f32_e32 v10, v129, v209
	v_fmac_f32_e32 v11, v129, v217
	v_fmac_f32_e32 v12, v129, v225
	v_fmac_f32_e32 v13, v129, v233
	v_fmac_f32_e32 v15, v129, v241
	v_fmac_f32_e32 v10, v130, v210
	v_fmac_f32_e32 v11, v130, v218
	v_fmac_f32_e32 v12, v130, v226
	v_fmac_f32_e32 v13, v130, v234
	v_fmac_f32_e32 v15, v130, v242
	v_fmac_f32_e32 v10, v131, v211
	v_fmac_f32_e32 v11, v131, v219
	v_fmac_f32_e32 v12, v131, v227
	v_fmac_f32_e32 v13, v131, v235
	v_fmac_f32_e32 v15, v131, v243
	v_fmac_f32_e32 v10, v132, v212
	v_fmac_f32_e32 v11, v132, v220
	v_fmac_f32_e32 v12, v132, v228
	v_fmac_f32_e32 v13, v132, v236
	v_fmac_f32_e32 v15, v132, v244
	v_fmac_f32_e32 v10, v133, v213
	v_fmac_f32_e32 v11, v133, v221
	v_fmac_f32_e32 v12, v133, v229
	v_fmac_f32_e32 v13, v133, v237
	v_fmac_f32_e32 v15, v133, v245
	v_fmac_f32_e32 v10, v134, v214
	v_fmac_f32_e32 v11, v134, v222
	v_fmac_f32_e32 v12, v134, v230
	v_fmac_f32_e32 v13, v134, v238
	v_fmac_f32_e32 v15, v134, v246
	v_fmac_f32_e32 v10, v135, v215
	v_fmac_f32_e32 v11, v135, v223
	v_fmac_f32_e32 v12, v135, v231
	v_fmac_f32_e32 v13, v135, v239
	v_fmac_f32_e32 v15, v135, v247
	s_waitcnt vmcnt(48)
	global_load_dword v128, v8, s[8:9]
	s_add_u32 s8, s8, 0x6000
	s_addc_u32 s9, s9, 0
	global_load_dword v129, v8, s[8:9]
	s_add_u32 s8, s8, 0x6000
	s_addc_u32 s9, s9, 0
	global_load_dword v130, v8, s[8:9]
	s_add_u32 s8, s8, 0x6000
	s_addc_u32 s9, s9, 0
	global_load_dword v131, v8, s[8:9]
	s_add_u32 s8, s8, 0x6000
	s_addc_u32 s9, s9, 0
	global_load_dword v132, v8, s[8:9]
	s_add_u32 s8, s8, 0x6000
	s_addc_u32 s9, s9, 0
	global_load_dword v133, v8, s[8:9]
	s_add_u32 s8, s8, 0x6000
	s_addc_u32 s9, s9, 0
	global_load_dword v134, v8, s[8:9]
	s_add_u32 s8, s8, 0x6000
	s_addc_u32 s9, s9, 0
	global_load_dword v135, v8, s[8:9]
	s_add_u32 s8, s8, 0x6000
	s_addc_u32 s9, s9, 0
	s_waitcnt lgkmcnt(0)
	ds_read_b128 v[208:211], v14 offset:224
	ds_read_b128 v[212:215], v14 offset:240
	ds_read_b128 v[216:219], v14 offset:8416
	ds_read_b128 v[220:223], v14 offset:8432
	ds_read_b128 v[224:227], v14 offset:16608
	ds_read_b128 v[228:231], v14 offset:16624
	ds_read_b128 v[232:235], v14 offset:24800
	ds_read_b128 v[236:239], v14 offset:24816
	ds_read_b128 v[240:243], v14 offset:32992
	ds_read_b128 v[244:247], v14 offset:33008
	v_fmac_f32_e32 v10, v136, v168
	v_fmac_f32_e32 v11, v136, v176
	v_fmac_f32_e32 v12, v136, v184
	v_fmac_f32_e32 v13, v136, v192
	v_fmac_f32_e32 v15, v136, v200
	v_fmac_f32_e32 v10, v137, v169
	v_fmac_f32_e32 v11, v137, v177
	v_fmac_f32_e32 v12, v137, v185
	v_fmac_f32_e32 v13, v137, v193
	v_fmac_f32_e32 v15, v137, v201
	v_fmac_f32_e32 v10, v138, v170
	v_fmac_f32_e32 v11, v138, v178
	v_fmac_f32_e32 v12, v138, v186
	v_fmac_f32_e32 v13, v138, v194
	v_fmac_f32_e32 v15, v138, v202
	v_fmac_f32_e32 v10, v139, v171
	v_fmac_f32_e32 v11, v139, v179
	v_fmac_f32_e32 v12, v139, v187
	v_fmac_f32_e32 v13, v139, v195
	v_fmac_f32_e32 v15, v139, v203
	v_fmac_f32_e32 v10, v140, v172
	v_fmac_f32_e32 v11, v140, v180
	v_fmac_f32_e32 v12, v140, v188
	v_fmac_f32_e32 v13, v140, v196
	v_fmac_f32_e32 v15, v140, v204
	v_fmac_f32_e32 v10, v141, v173
	v_fmac_f32_e32 v11, v141, v181
	v_fmac_f32_e32 v12, v141, v189
	v_fmac_f32_e32 v13, v141, v197
	v_fmac_f32_e32 v15, v141, v205
	v_fmac_f32_e32 v10, v142, v174
	v_fmac_f32_e32 v11, v142, v182
	v_fmac_f32_e32 v12, v142, v190
	v_fmac_f32_e32 v13, v142, v198
	v_fmac_f32_e32 v15, v142, v206
	v_fmac_f32_e32 v10, v143, v175
	v_fmac_f32_e32 v11, v143, v183
	v_fmac_f32_e32 v12, v143, v191
	v_fmac_f32_e32 v13, v143, v199
	v_fmac_f32_e32 v15, v143, v207
	s_waitcnt vmcnt(48)
	global_load_dword v136, v8, s[8:9]
	s_add_u32 s8, s8, 0x6000
	s_addc_u32 s9, s9, 0
	global_load_dword v137, v8, s[8:9]
	s_add_u32 s8, s8, 0x6000
	s_addc_u32 s9, s9, 0
	global_load_dword v138, v8, s[8:9]
	s_add_u32 s8, s8, 0x6000
	s_addc_u32 s9, s9, 0
	global_load_dword v139, v8, s[8:9]
	s_add_u32 s8, s8, 0x6000
	s_addc_u32 s9, s9, 0
	global_load_dword v140, v8, s[8:9]
	s_add_u32 s8, s8, 0x6000
	s_addc_u32 s9, s9, 0
	global_load_dword v141, v8, s[8:9]
	s_add_u32 s8, s8, 0x6000
	s_addc_u32 s9, s9, 0
	global_load_dword v142, v8, s[8:9]
	s_add_u32 s8, s8, 0x6000
	s_addc_u32 s9, s9, 0
	global_load_dword v143, v8, s[8:9]
	s_add_u32 s8, s8, 0x6000
	s_addc_u32 s9, s9, 0
	s_waitcnt lgkmcnt(0)
	ds_read_b128 v[168:171], v14 offset:256
	ds_read_b128 v[172:175], v14 offset:272
	ds_read_b128 v[176:179], v14 offset:8448
	ds_read_b128 v[180:183], v14 offset:8464
	ds_read_b128 v[184:187], v14 offset:16640
	ds_read_b128 v[188:191], v14 offset:16656
	ds_read_b128 v[192:195], v14 offset:24832
	ds_read_b128 v[196:199], v14 offset:24848
	ds_read_b128 v[200:203], v14 offset:33024
	ds_read_b128 v[204:207], v14 offset:33040
	v_fmac_f32_e32 v10, v144, v208
	v_fmac_f32_e32 v11, v144, v216
	v_fmac_f32_e32 v12, v144, v224
	v_fmac_f32_e32 v13, v144, v232
	v_fmac_f32_e32 v15, v144, v240
	v_fmac_f32_e32 v10, v145, v209
	v_fmac_f32_e32 v11, v145, v217
	v_fmac_f32_e32 v12, v145, v225
	v_fmac_f32_e32 v13, v145, v233
	v_fmac_f32_e32 v15, v145, v241
	v_fmac_f32_e32 v10, v146, v210
	v_fmac_f32_e32 v11, v146, v218
	v_fmac_f32_e32 v12, v146, v226
	v_fmac_f32_e32 v13, v146, v234
	v_fmac_f32_e32 v15, v146, v242
	v_fmac_f32_e32 v10, v147, v211
	v_fmac_f32_e32 v11, v147, v219
	v_fmac_f32_e32 v12, v147, v227
	v_fmac_f32_e32 v13, v147, v235
	v_fmac_f32_e32 v15, v147, v243
	v_fmac_f32_e32 v10, v148, v212
	v_fmac_f32_e32 v11, v148, v220
	v_fmac_f32_e32 v12, v148, v228
	v_fmac_f32_e32 v13, v148, v236
	v_fmac_f32_e32 v15, v148, v244
	v_fmac_f32_e32 v10, v149, v213
	v_fmac_f32_e32 v11, v149, v221
	v_fmac_f32_e32 v12, v149, v229
	v_fmac_f32_e32 v13, v149, v237
	v_fmac_f32_e32 v15, v149, v245
	v_fmac_f32_e32 v10, v150, v214
	v_fmac_f32_e32 v11, v150, v222
	v_fmac_f32_e32 v12, v150, v230
	v_fmac_f32_e32 v13, v150, v238
	v_fmac_f32_e32 v15, v150, v246
	v_fmac_f32_e32 v10, v151, v215
	v_fmac_f32_e32 v11, v151, v223
	v_fmac_f32_e32 v12, v151, v231
	v_fmac_f32_e32 v13, v151, v239
	v_fmac_f32_e32 v15, v151, v247
	v_add_u32_e32 v14, 0x100, v14
	s_add_u32 s7, s7, 1
	s_cmp_lt_u32 s7, 7
	s_cbranch_scc1 .Lmod_loop
	s_waitcnt vmcnt(48)
	global_load_dword v144, v8, s[8:9]
	s_add_u32 s8, s8, 0x6000
	s_addc_u32 s9, s9, 0
	global_load_dword v145, v8, s[8:9]
	s_add_u32 s8, s8, 0x6000
	s_addc_u32 s9, s9, 0
	global_load_dword v146, v8, s[8:9]
	s_add_u32 s8, s8, 0x6000
	s_addc_u32 s9, s9, 0
	global_load_dword v147, v8, s[8:9]
	s_add_u32 s8, s8, 0x6000
	s_addc_u32 s9, s9, 0
	global_load_dword v148, v8, s[8:9]
	s_add_u32 s8, s8, 0x6000
	s_addc_u32 s9, s9, 0
	global_load_dword v149, v8, s[8:9]
	s_add_u32 s8, s8, 0x6000
	s_addc_u32 s9, s9, 0
	global_load_dword v150, v8, s[8:9]
	s_add_u32 s8, s8, 0x6000
	s_addc_u32 s9, s9, 0
	global_load_dword v151, v8, s[8:9]
	s_add_u32 s8, s8, 0x6000
	s_addc_u32 s9, s9, 0
	s_waitcnt lgkmcnt(0)
	ds_read_b128 v[208:211], v14 offset:32
	ds_read_b128 v[212:215], v14 offset:48
	ds_read_b128 v[216:219], v14 offset:8224
	ds_read_b128 v[220:223], v14 offset:8240
	ds_read_b128 v[224:227], v14 offset:16416
	ds_read_b128 v[228:231], v14 offset:16432
	ds_read_b128 v[232:235], v14 offset:24608
	ds_read_b128 v[236:239], v14 offset:24624
	ds_read_b128 v[240:243], v14 offset:32800
	ds_read_b128 v[244:247], v14 offset:32816
	v_fmac_f32_e32 v10, v88, v168
	v_fmac_f32_e32 v11, v88, v176
	v_fmac_f32_e32 v12, v88, v184
	v_fmac_f32_e32 v13, v88, v192
	v_fmac_f32_e32 v15, v88, v200
	v_fmac_f32_e32 v10, v89, v169
	v_fmac_f32_e32 v11, v89, v177
	v_fmac_f32_e32 v12, v89, v185
	v_fmac_f32_e32 v13, v89, v193
	v_fmac_f32_e32 v15, v89, v201
	v_fmac_f32_e32 v10, v90, v170
	v_fmac_f32_e32 v11, v90, v178
	v_fmac_f32_e32 v12, v90, v186
	v_fmac_f32_e32 v13, v90, v194
	v_fmac_f32_e32 v15, v90, v202
	v_fmac_f32_e32 v10, v91, v171
	v_fmac_f32_e32 v11, v91, v179
	v_fmac_f32_e32 v12, v91, v187
	v_fmac_f32_e32 v13, v91, v195
	v_fmac_f32_e32 v15, v91, v203
	v_fmac_f32_e32 v10, v92, v172
	v_fmac_f32_e32 v11, v92, v180
	v_fmac_f32_e32 v12, v92, v188
	v_fmac_f32_e32 v13, v92, v196
	v_fmac_f32_e32 v15, v92, v204
	v_fmac_f32_e32 v10, v93, v173
	v_fmac_f32_e32 v11, v93, v181
	v_fmac_f32_e32 v12, v93, v189
	v_fmac_f32_e32 v13, v93, v197
	v_fmac_f32_e32 v15, v93, v205
	v_fmac_f32_e32 v10, v94, v174
	v_fmac_f32_e32 v11, v94, v182
	v_fmac_f32_e32 v12, v94, v190
	v_fmac_f32_e32 v13, v94, v198
	v_fmac_f32_e32 v15, v94, v206
	v_fmac_f32_e32 v10, v95, v175
	v_fmac_f32_e32 v11, v95, v183
	v_fmac_f32_e32 v12, v95, v191
	v_fmac_f32_e32 v13, v95, v199
	v_fmac_f32_e32 v15, v95, v207
	s_waitcnt vmcnt(48)
	s_waitcnt lgkmcnt(0)
	ds_read_b128 v[168:171], v14 offset:64
	ds_read_b128 v[172:175], v14 offset:80
	ds_read_b128 v[176:179], v14 offset:8256
	ds_read_b128 v[180:183], v14 offset:8272
	ds_read_b128 v[184:187], v14 offset:16448
	ds_read_b128 v[188:191], v14 offset:16464
	ds_read_b128 v[192:195], v14 offset:24640
	ds_read_b128 v[196:199], v14 offset:24656
	ds_read_b128 v[200:203], v14 offset:32832
	ds_read_b128 v[204:207], v14 offset:32848
	v_fmac_f32_e32 v10, v96, v208
	v_fmac_f32_e32 v11, v96, v216
	v_fmac_f32_e32 v12, v96, v224
	v_fmac_f32_e32 v13, v96, v232
	v_fmac_f32_e32 v15, v96, v240
	v_fmac_f32_e32 v10, v97, v209
	v_fmac_f32_e32 v11, v97, v217
	v_fmac_f32_e32 v12, v97, v225
	v_fmac_f32_e32 v13, v97, v233
	v_fmac_f32_e32 v15, v97, v241
	v_fmac_f32_e32 v10, v98, v210
	v_fmac_f32_e32 v11, v98, v218
	v_fmac_f32_e32 v12, v98, v226
	v_fmac_f32_e32 v13, v98, v234
	v_fmac_f32_e32 v15, v98, v242
	v_fmac_f32_e32 v10, v99, v211
	v_fmac_f32_e32 v11, v99, v219
	v_fmac_f32_e32 v12, v99, v227
	v_fmac_f32_e32 v13, v99, v235
	v_fmac_f32_e32 v15, v99, v243
	v_fmac_f32_e32 v10, v100, v212
	v_fmac_f32_e32 v11, v100, v220
	v_fmac_f32_e32 v12, v100, v228
	v_fmac_f32_e32 v13, v100, v236
	v_fmac_f32_e32 v15, v100, v244
	v_fmac_f32_e32 v10, v101, v213
	v_fmac_f32_e32 v11, v101, v221
	v_fmac_f32_e32 v12, v101, v229
	v_fmac_f32_e32 v13, v101, v237
	v_fmac_f32_e32 v15, v101, v245
	v_fmac_f32_e32 v10, v102, v214
	v_fmac_f32_e32 v11, v102, v222
	v_fmac_f32_e32 v12, v102, v230
	v_fmac_f32_e32 v13, v102, v238
	v_fmac_f32_e32 v15, v102, v246
	v_fmac_f32_e32 v10, v103, v215
	v_fmac_f32_e32 v11, v103, v223
	v_fmac_f32_e32 v12, v103, v231
	v_fmac_f32_e32 v13, v103, v239
	v_fmac_f32_e32 v15, v103, v247
	s_waitcnt vmcnt(40)
	s_waitcnt lgkmcnt(0)
	ds_read_b128 v[208:211], v14 offset:96
	ds_read_b128 v[212:215], v14 offset:112
	ds_read_b128 v[216:219], v14 offset:8288
	ds_read_b128 v[220:223], v14 offset:8304
	ds_read_b128 v[224:227], v14 offset:16480
	ds_read_b128 v[228:231], v14 offset:16496
	ds_read_b128 v[232:235], v14 offset:24672
	ds_read_b128 v[236:239], v14 offset:24688
	ds_read_b128 v[240:243], v14 offset:32864
	ds_read_b128 v[244:247], v14 offset:32880
	v_fmac_f32_e32 v10, v104, v168
	v_fmac_f32_e32 v11, v104, v176
	v_fmac_f32_e32 v12, v104, v184
	v_fmac_f32_e32 v13, v104, v192
	v_fmac_f32_e32 v15, v104, v200
	v_fmac_f32_e32 v10, v105, v169
	v_fmac_f32_e32 v11, v105, v177
	v_fmac_f32_e32 v12, v105, v185
	v_fmac_f32_e32 v13, v105, v193
	v_fmac_f32_e32 v15, v105, v201
	v_fmac_f32_e32 v10, v106, v170
	v_fmac_f32_e32 v11, v106, v178
	v_fmac_f32_e32 v12, v106, v186
	v_fmac_f32_e32 v13, v106, v194
	v_fmac_f32_e32 v15, v106, v202
	v_fmac_f32_e32 v10, v107, v171
	v_fmac_f32_e32 v11, v107, v179
	v_fmac_f32_e32 v12, v107, v187
	v_fmac_f32_e32 v13, v107, v195
	v_fmac_f32_e32 v15, v107, v203
	v_fmac_f32_e32 v10, v108, v172
	v_fmac_f32_e32 v11, v108, v180
	v_fmac_f32_e32 v12, v108, v188
	v_fmac_f32_e32 v13, v108, v196
	v_fmac_f32_e32 v15, v108, v204
	v_fmac_f32_e32 v10, v109, v173
	v_fmac_f32_e32 v11, v109, v181
	v_fmac_f32_e32 v12, v109, v189
	v_fmac_f32_e32 v13, v109, v197
	v_fmac_f32_e32 v15, v109, v205
	v_fmac_f32_e32 v10, v110, v174
	v_fmac_f32_e32 v11, v110, v182
	v_fmac_f32_e32 v12, v110, v190
	v_fmac_f32_e32 v13, v110, v198
	v_fmac_f32_e32 v15, v110, v206
	v_fmac_f32_e32 v10, v111, v175
	v_fmac_f32_e32 v11, v111, v183
	v_fmac_f32_e32 v12, v111, v191
	v_fmac_f32_e32 v13, v111, v199
	v_fmac_f32_e32 v15, v111, v207
	s_waitcnt vmcnt(32)
	s_waitcnt lgkmcnt(0)
	ds_read_b128 v[168:171], v14 offset:128
	ds_read_b128 v[172:175], v14 offset:144
	ds_read_b128 v[176:179], v14 offset:8320
	ds_read_b128 v[180:183], v14 offset:8336
	ds_read_b128 v[184:187], v14 offset:16512
	ds_read_b128 v[188:191], v14 offset:16528
	ds_read_b128 v[192:195], v14 offset:24704
	ds_read_b128 v[196:199], v14 offset:24720
	ds_read_b128 v[200:203], v14 offset:32896
	ds_read_b128 v[204:207], v14 offset:32912
	v_fmac_f32_e32 v10, v112, v208
	v_fmac_f32_e32 v11, v112, v216
	v_fmac_f32_e32 v12, v112, v224
	v_fmac_f32_e32 v13, v112, v232
	v_fmac_f32_e32 v15, v112, v240
	v_fmac_f32_e32 v10, v113, v209
	v_fmac_f32_e32 v11, v113, v217
	v_fmac_f32_e32 v12, v113, v225
	v_fmac_f32_e32 v13, v113, v233
	v_fmac_f32_e32 v15, v113, v241
	v_fmac_f32_e32 v10, v114, v210
	v_fmac_f32_e32 v11, v114, v218
	v_fmac_f32_e32 v12, v114, v226
	v_fmac_f32_e32 v13, v114, v234
	v_fmac_f32_e32 v15, v114, v242
	v_fmac_f32_e32 v10, v115, v211
	v_fmac_f32_e32 v11, v115, v219
	v_fmac_f32_e32 v12, v115, v227
	v_fmac_f32_e32 v13, v115, v235
	v_fmac_f32_e32 v15, v115, v243
	v_fmac_f32_e32 v10, v116, v212
	v_fmac_f32_e32 v11, v116, v220
	v_fmac_f32_e32 v12, v116, v228
	v_fmac_f32_e32 v13, v116, v236
	v_fmac_f32_e32 v15, v116, v244
	v_fmac_f32_e32 v10, v117, v213
	v_fmac_f32_e32 v11, v117, v221
	v_fmac_f32_e32 v12, v117, v229
	v_fmac_f32_e32 v13, v117, v237
	v_fmac_f32_e32 v15, v117, v245
	v_fmac_f32_e32 v10, v118, v214
	v_fmac_f32_e32 v11, v118, v222
	v_fmac_f32_e32 v12, v118, v230
	v_fmac_f32_e32 v13, v118, v238
	v_fmac_f32_e32 v15, v118, v246
	v_fmac_f32_e32 v10, v119, v215
	v_fmac_f32_e32 v11, v119, v223
	v_fmac_f32_e32 v12, v119, v231
	v_fmac_f32_e32 v13, v119, v239
	v_fmac_f32_e32 v15, v119, v247
	s_waitcnt vmcnt(24)
	s_waitcnt lgkmcnt(0)
	ds_read_b128 v[208:211], v14 offset:160
	ds_read_b128 v[212:215], v14 offset:176
	ds_read_b128 v[216:219], v14 offset:8352
	ds_read_b128 v[220:223], v14 offset:8368
	ds_read_b128 v[224:227], v14 offset:16544
	ds_read_b128 v[228:231], v14 offset:16560
	ds_read_b128 v[232:235], v14 offset:24736
	ds_read_b128 v[236:239], v14 offset:24752
	ds_read_b128 v[240:243], v14 offset:32928
	ds_read_b128 v[244:247], v14 offset:32944
	v_fmac_f32_e32 v10, v120, v168
	v_fmac_f32_e32 v11, v120, v176
	v_fmac_f32_e32 v12, v120, v184
	v_fmac_f32_e32 v13, v120, v192
	v_fmac_f32_e32 v15, v120, v200
	v_fmac_f32_e32 v10, v121, v169
	v_fmac_f32_e32 v11, v121, v177
	v_fmac_f32_e32 v12, v121, v185
	v_fmac_f32_e32 v13, v121, v193
	v_fmac_f32_e32 v15, v121, v201
	v_fmac_f32_e32 v10, v122, v170
	v_fmac_f32_e32 v11, v122, v178
	v_fmac_f32_e32 v12, v122, v186
	v_fmac_f32_e32 v13, v122, v194
	v_fmac_f32_e32 v15, v122, v202
	v_fmac_f32_e32 v10, v123, v171
	v_fmac_f32_e32 v11, v123, v179
	v_fmac_f32_e32 v12, v123, v187
	v_fmac_f32_e32 v13, v123, v195
	v_fmac_f32_e32 v15, v123, v203
	v_fmac_f32_e32 v10, v124, v172
	v_fmac_f32_e32 v11, v124, v180
	v_fmac_f32_e32 v12, v124, v188
	v_fmac_f32_e32 v13, v124, v196
	v_fmac_f32_e32 v15, v124, v204
	v_fmac_f32_e32 v10, v125, v173
	v_fmac_f32_e32 v11, v125, v181
	v_fmac_f32_e32 v12, v125, v189
	v_fmac_f32_e32 v13, v125, v197
	v_fmac_f32_e32 v15, v125, v205
	v_fmac_f32_e32 v10, v126, v174
	v_fmac_f32_e32 v11, v126, v182
	v_fmac_f32_e32 v12, v126, v190
	v_fmac_f32_e32 v13, v126, v198
	v_fmac_f32_e32 v15, v126, v206
	v_fmac_f32_e32 v10, v127, v175
	v_fmac_f32_e32 v11, v127, v183
	v_fmac_f32_e32 v12, v127, v191
	v_fmac_f32_e32 v13, v127, v199
	v_fmac_f32_e32 v15, v127, v207
	s_waitcnt vmcnt(16)
	s_waitcnt lgkmcnt(0)
	ds_read_b128 v[168:171], v14 offset:192
	ds_read_b128 v[172:175], v14 offset:208
	ds_read_b128 v[176:179], v14 offset:8384
	ds_read_b128 v[180:183], v14 offset:8400
	ds_read_b128 v[184:187], v14 offset:16576
	ds_read_b128 v[188:191], v14 offset:16592
	ds_read_b128 v[192:195], v14 offset:24768
	ds_read_b128 v[196:199], v14 offset:24784
	ds_read_b128 v[200:203], v14 offset:32960
	ds_read_b128 v[204:207], v14 offset:32976
	v_fmac_f32_e32 v10, v128, v208
	v_fmac_f32_e32 v11, v128, v216
	v_fmac_f32_e32 v12, v128, v224
	v_fmac_f32_e32 v13, v128, v232
	v_fmac_f32_e32 v15, v128, v240
	v_fmac_f32_e32 v10, v129, v209
	v_fmac_f32_e32 v11, v129, v217
	v_fmac_f32_e32 v12, v129, v225
	v_fmac_f32_e32 v13, v129, v233
	v_fmac_f32_e32 v15, v129, v241
	v_fmac_f32_e32 v10, v130, v210
	v_fmac_f32_e32 v11, v130, v218
	v_fmac_f32_e32 v12, v130, v226
	v_fmac_f32_e32 v13, v130, v234
	v_fmac_f32_e32 v15, v130, v242
	v_fmac_f32_e32 v10, v131, v211
	v_fmac_f32_e32 v11, v131, v219
	v_fmac_f32_e32 v12, v131, v227
	v_fmac_f32_e32 v13, v131, v235
	v_fmac_f32_e32 v15, v131, v243
	v_fmac_f32_e32 v10, v132, v212
	v_fmac_f32_e32 v11, v132, v220
	v_fmac_f32_e32 v12, v132, v228
	v_fmac_f32_e32 v13, v132, v236
	v_fmac_f32_e32 v15, v132, v244
	v_fmac_f32_e32 v10, v133, v213
	v_fmac_f32_e32 v11, v133, v221
	v_fmac_f32_e32 v12, v133, v229
	v_fmac_f32_e32 v13, v133, v237
	v_fmac_f32_e32 v15, v133, v245
	v_fmac_f32_e32 v10, v134, v214
	v_fmac_f32_e32 v11, v134, v222
	v_fmac_f32_e32 v12, v134, v230
	v_fmac_f32_e32 v13, v134, v238
	v_fmac_f32_e32 v15, v134, v246
	v_fmac_f32_e32 v10, v135, v215
	v_fmac_f32_e32 v11, v135, v223
	v_fmac_f32_e32 v12, v135, v231
	v_fmac_f32_e32 v13, v135, v239
	v_fmac_f32_e32 v15, v135, v247
	s_waitcnt vmcnt(8)
	s_waitcnt lgkmcnt(0)
	ds_read_b128 v[208:211], v14 offset:224
	ds_read_b128 v[212:215], v14 offset:240
	ds_read_b128 v[216:219], v14 offset:8416
	ds_read_b128 v[220:223], v14 offset:8432
	ds_read_b128 v[224:227], v14 offset:16608
	ds_read_b128 v[228:231], v14 offset:16624
	ds_read_b128 v[232:235], v14 offset:24800
	ds_read_b128 v[236:239], v14 offset:24816
	ds_read_b128 v[240:243], v14 offset:32992
	ds_read_b128 v[244:247], v14 offset:33008
	v_fmac_f32_e32 v10, v136, v168
	v_fmac_f32_e32 v11, v136, v176
	v_fmac_f32_e32 v12, v136, v184
	v_fmac_f32_e32 v13, v136, v192
	v_fmac_f32_e32 v15, v136, v200
	v_fmac_f32_e32 v10, v137, v169
	v_fmac_f32_e32 v11, v137, v177
	v_fmac_f32_e32 v12, v137, v185
	v_fmac_f32_e32 v13, v137, v193
	v_fmac_f32_e32 v15, v137, v201
	v_fmac_f32_e32 v10, v138, v170
	v_fmac_f32_e32 v11, v138, v178
	v_fmac_f32_e32 v12, v138, v186
	v_fmac_f32_e32 v13, v138, v194
	v_fmac_f32_e32 v15, v138, v202
	v_fmac_f32_e32 v10, v139, v171
	v_fmac_f32_e32 v11, v139, v179
	v_fmac_f32_e32 v12, v139, v187
	v_fmac_f32_e32 v13, v139, v195
	v_fmac_f32_e32 v15, v139, v203
	v_fmac_f32_e32 v10, v140, v172
	v_fmac_f32_e32 v11, v140, v180
	v_fmac_f32_e32 v12, v140, v188
	v_fmac_f32_e32 v13, v140, v196
	v_fmac_f32_e32 v15, v140, v204
	v_fmac_f32_e32 v10, v141, v173
	v_fmac_f32_e32 v11, v141, v181
	v_fmac_f32_e32 v12, v141, v189
	v_fmac_f32_e32 v13, v141, v197
	v_fmac_f32_e32 v15, v141, v205
	v_fmac_f32_e32 v10, v142, v174
	v_fmac_f32_e32 v11, v142, v182
	v_fmac_f32_e32 v12, v142, v190
	v_fmac_f32_e32 v13, v142, v198
	v_fmac_f32_e32 v15, v142, v206
	v_fmac_f32_e32 v10, v143, v175
	v_fmac_f32_e32 v11, v143, v183
	v_fmac_f32_e32 v12, v143, v191
	v_fmac_f32_e32 v13, v143, v199
	v_fmac_f32_e32 v15, v143, v207
	s_waitcnt vmcnt(0)
	s_waitcnt lgkmcnt(0)
	v_fmac_f32_e32 v10, v144, v208
	v_fmac_f32_e32 v11, v144, v216
	v_fmac_f32_e32 v12, v144, v224
	v_fmac_f32_e32 v13, v144, v232
	v_fmac_f32_e32 v15, v144, v240
	v_fmac_f32_e32 v10, v145, v209
	v_fmac_f32_e32 v11, v145, v217
	v_fmac_f32_e32 v12, v145, v225
	v_fmac_f32_e32 v13, v145, v233
	v_fmac_f32_e32 v15, v145, v241
	v_fmac_f32_e32 v10, v146, v210
	v_fmac_f32_e32 v11, v146, v218
	v_fmac_f32_e32 v12, v146, v226
	v_fmac_f32_e32 v13, v146, v234
	v_fmac_f32_e32 v15, v146, v242
	v_fmac_f32_e32 v10, v147, v211
	v_fmac_f32_e32 v11, v147, v219
	v_fmac_f32_e32 v12, v147, v227
	v_fmac_f32_e32 v13, v147, v235
	v_fmac_f32_e32 v15, v147, v243
	v_fmac_f32_e32 v10, v148, v212
	v_fmac_f32_e32 v11, v148, v220
	v_fmac_f32_e32 v12, v148, v228
	v_fmac_f32_e32 v13, v148, v236
	v_fmac_f32_e32 v15, v148, v244
	v_fmac_f32_e32 v10, v149, v213
	v_fmac_f32_e32 v11, v149, v221
	v_fmac_f32_e32 v12, v149, v229
	v_fmac_f32_e32 v13, v149, v237
	v_fmac_f32_e32 v15, v149, v245
	v_fmac_f32_e32 v10, v150, v214
	v_fmac_f32_e32 v11, v150, v222
	v_fmac_f32_e32 v12, v150, v230
	v_fmac_f32_e32 v13, v150, v238
	v_fmac_f32_e32 v15, v150, v246
	v_fmac_f32_e32 v10, v151, v215
	v_fmac_f32_e32 v11, v151, v223
	v_fmac_f32_e32 v12, v151, v231
	v_fmac_f32_e32 v13, v151, v239
	v_fmac_f32_e32 v15, v151, v247
	s_movk_i32 s7, 0x500
	v_mul_lo_u32 v5, v5, s7
	v_lshlrev_b32_e32 v8, 2, v2
	v_add3_u32 v5, s33, v5, v8
	v_readfirstlane_b32 s7, v167
	ds_write2st64_b32 v5, v10, v11 offset0:160 offset1:161
	ds_write2st64_b32 v5, v12, v13 offset0:162 offset1:163
	ds_write_b32 v5, v15 offset:41984
	s_waitcnt lgkmcnt(0)
	s_and_saveexec_b64 s[8:9], s[4:5]
	s_cbranch_execz .LBB0_295
	s_mov_b64 s[10:11], exec
	s_lshr_b32 s7, s7, 4
	s_and_b32 s7, s7, 0xffffff0
	v_mbcnt_lo_u32_b32 v5, s10, 0
	s_add_i32 s7, s7, 0
	v_mbcnt_hi_u32_b32 v5, s11, v5
	s_add_i32 s7, s7, 0x220c0
	v_cmp_eq_u32_e32 vcc, 0, v5
	s_and_saveexec_b64 s[12:13], vcc
	s_bcnt1_i32_b64 s10, s[10:11]
	v_mov_b32_e32 v8, s7
	v_mov_b32_e32 v9, s10
	ds_add_rtn_u32 v8, v8, v9
	s_or_b64 exec, exec, s[12:13]
	v_mov_b32_e32 v9, s7
	ds_read_b32 v9, v9
	s_waitcnt lgkmcnt(1)
	v_readfirstlane_b32 s10, v8
	s_nop 1
	v_add_u32_e32 v5, s10, v5
	v_bitop3_b32 v5, v5, -4, v5 bitop3:0xc
	s_waitcnt lgkmcnt(0)
	v_add_u32_e32 v8, v5, v9
	v_cmp_gt_i32_e32 vcc, 0, v8
	s_and_b64 exec, exec, vcc
	s_cbranch_execz .LBB0_295
	s_mov_b64 s[10:11], 0

.LBB0_759:
	s_or_b64 exec, exec, s[2:3]
	v_readlane_b32 s0, v254, 3
	v_readlane_b32 s1, v254, 4
	s_waitcnt lgkmcnt(0)
	s_barrier
	s_load_dword s0, s[0:1], 0x10
	v_ashrrev_i32_e32 v3, 31, v2
	v_mov_b32_e32 v34, 0
	v_readfirstlane_b32 s8, v167
	s_mov_b64 s[2:3], 0
	s_waitcnt lgkmcnt(0)
	s_lshr_b32 s9, s0, 16
	v_readlane_b32 s0, v255, 38
	v_readlane_b32 s1, v255, 39
	v_mov_b32_e32 v35, v34
	v_mov_b32_e32 v28, v34
	v_lshl_add_u64 v[32:33], v[2:3], 1, s[0:1]
	v_readlane_b32 s0, v254, 41
	v_mov_b32_e32 v29, v34
	v_mov_b32_e32 v24, v34
	v_mov_b32_e32 v25, v34
	v_mov_b32_e32 v20, v34
	v_mov_b32_e32 v21, v34
	v_mov_b32_e32 v16, v34
	v_mov_b32_e32 v17, v34
	v_mov_b32_e32 v12, v34
	v_mov_b32_e32 v13, v34
	v_mov_b32_e32 v8, v34
	v_mov_b32_e32 v9, v34
	v_mov_b32_e32 v4, v34
	v_mov_b32_e32 v5, v34
	v_mov_b32_e32 v36, v34
	v_mov_b32_e32 v37, v34
	v_mov_b32_e32 v30, v34
	v_mov_b32_e32 v31, v34
	v_mov_b32_e32 v26, v34
	v_mov_b32_e32 v27, v34
	v_mov_b32_e32 v22, v34
	v_mov_b32_e32 v23, v34
	v_mov_b32_e32 v18, v34
	v_mov_b32_e32 v19, v34
	v_mov_b32_e32 v14, v34
	v_mov_b32_e32 v15, v34
	v_mov_b32_e32 v10, v34
	v_mov_b32_e32 v11, v34
	v_mov_b32_e32 v6, v34
	v_mov_b32_e32 v7, v34
	v_readlane_b32 s2, v255, 38
	v_readlane_b32 s3, v255, 39
	v_lshlrev_b32_e32 v1, 1, v2
	s_add_i32 s1, s0, 0xfffffefc
	v_mov_b32_e32 v62, s1
	s_nop 3
	global_load_dwordx4 v[194:197], v1, s[2:3]
	global_load_dwordx4 v[198:201], v1, s[2:3] offset:16
	s_add_u32 s2, s2, 0x2000
	s_addc_u32 s3, s3, 0
	global_load_dwordx4 v[202:205], v1, s[2:3]
	global_load_dwordx4 v[206:209], v1, s[2:3] offset:16
	s_add_u32 s2, s2, 0x2000
	s_addc_u32 s3, s3, 0
	global_load_dwordx4 v[210:213], v1, s[2:3]
	global_load_dwordx4 v[214:217], v1, s[2:3] offset:16
	s_add_u32 s2, s2, 0x2000
	s_addc_u32 s3, s3, 0
	global_load_dwordx4 v[218:221], v1, s[2:3]
	global_load_dwordx4 v[222:225], v1, s[2:3] offset:16
	s_add_u32 s2, s2, 0x2000
	s_addc_u32 s3, s3, 0
	global_load_dwordx4 v[226:229], v1, s[2:3]
	global_load_dwordx4 v[230:233], v1, s[2:3] offset:16
	s_add_u32 s2, s2, 0x2000
	s_addc_u32 s3, s3, 0
	global_load_dwordx4 v[234:237], v1, s[2:3]
	global_load_dwordx4 v[238:241], v1, s[2:3] offset:16
	s_add_u32 s2, s2, 0x2000
	s_addc_u32 s3, s3, 0
	global_load_dwordx4 v[242:245], v1, s[2:3]
	global_load_dwordx4 v[246:249], v1, s[2:3] offset:16
	s_add_u32 s2, s2, 0x2000
	s_addc_u32 s3, s3, 0
	global_load_dwordx4 v[250:253], v1, s[2:3]
	global_load_dwordx4 v[42:45], v1, s[2:3] offset:16
	s_add_u32 s2, s2, 0x2000
	s_addc_u32 s3, s3, 0
	s_mov_b32 s0, 0
.Lhy_tap_loop:
	ds_read_b64 v[40:41], v62
	ds_read_b64 v[38:39], v62 offset:256
	s_waitcnt vmcnt(12)
	v_lshlrev_b32_e32 v46, 16, v194
	v_and_b32_e32 v47, 0xffff0000, v194
	v_lshlrev_b32_e32 v48, 16, v195
	v_and_b32_e32 v49, 0xffff0000, v195
	v_lshlrev_b32_e32 v50, 16, v196
	v_and_b32_e32 v51, 0xffff0000, v196
	v_lshlrev_b32_e32 v52, 16, v197
	v_and_b32_e32 v53, 0xffff0000, v197
	v_lshlrev_b32_e32 v54, 16, v198
	v_and_b32_e32 v55, 0xffff0000, v198
	v_lshlrev_b32_e32 v56, 16, v199
	v_and_b32_e32 v57, 0xffff0000, v199
	v_lshlrev_b32_e32 v58, 16, v200
	v_and_b32_e32 v59, 0xffff0000, v200
	v_lshlrev_b32_e32 v60, 16, v201
	v_and_b32_e32 v61, 0xffff0000, v201
	s_waitcnt lgkmcnt(0)
	v_pk_fma_f32 v[34:35], v[40:41], v[46:47], v[34:35] op_sel_hi:[0,1,1]
	v_pk_fma_f32 v[28:29], v[40:41], v[48:49], v[28:29] op_sel_hi:[0,1,1]
	v_pk_fma_f32 v[24:25], v[40:41], v[50:51], v[24:25] op_sel_hi:[0,1,1]
	v_pk_fma_f32 v[20:21], v[40:41], v[52:53], v[20:21] op_sel_hi:[0,1,1]
	v_pk_fma_f32 v[16:17], v[40:41], v[54:55], v[16:17] op_sel_hi:[0,1,1]
	v_pk_fma_f32 v[12:13], v[40:41], v[56:57], v[12:13] op_sel_hi:[0,1,1]
	v_pk_fma_f32 v[8:9], v[40:41], v[58:59], v[8:9] op_sel_hi:[0,1,1]
	v_pk_fma_f32 v[4:5], v[40:41], v[60:61], v[4:5] op_sel_hi:[0,1,1]
	v_pk_fma_f32 v[36:37], v[38:39], v[46:47], v[36:37] op_sel_hi:[0,1,1]
	v_pk_fma_f32 v[30:31], v[38:39], v[48:49], v[30:31] op_sel_hi:[0,1,1]
	v_pk_fma_f32 v[26:27], v[38:39], v[50:51], v[26:27] op_sel_hi:[0,1,1]
	v_pk_fma_f32 v[22:23], v[38:39], v[52:53], v[22:23] op_sel_hi:[0,1,1]
	v_pk_fma_f32 v[18:19], v[38:39], v[54:55], v[18:19] op_sel_hi:[0,1,1]
	v_pk_fma_f32 v[14:15], v[38:39], v[56:57], v[14:15] op_sel_hi:[0,1,1]
	v_pk_fma_f32 v[10:11], v[38:39], v[58:59], v[10:11] op_sel_hi:[0,1,1]
	v_pk_fma_f32 v[6:7], v[38:39], v[60:61], v[6:7] op_sel_hi:[0,1,1]
	v_lshlrev_b32_e32 v46, 16, v202
	v_and_b32_e32 v47, 0xffff0000, v202
	v_lshlrev_b32_e32 v48, 16, v203
	v_and_b32_e32 v49, 0xffff0000, v203
	v_lshlrev_b32_e32 v50, 16, v204
	v_and_b32_e32 v51, 0xffff0000, v204
	v_lshlrev_b32_e32 v52, 16, v205
	v_and_b32_e32 v53, 0xffff0000, v205
	v_lshlrev_b32_e32 v54, 16, v206
	v_and_b32_e32 v55, 0xffff0000, v206
	v_lshlrev_b32_e32 v56, 16, v207
	v_and_b32_e32 v57, 0xffff0000, v207
	v_lshlrev_b32_e32 v58, 16, v208
	v_and_b32_e32 v59, 0xffff0000, v208
	v_lshlrev_b32_e32 v60, 16, v209
	v_and_b32_e32 v61, 0xffff0000, v209
	global_load_dwordx4 v[194:197], v1, s[2:3]
	global_load_dwordx4 v[198:201], v1, s[2:3] offset:16
	s_add_u32 s2, s2, 0x2000
	s_addc_u32 s3, s3, 0
	global_load_dwordx4 v[202:205], v1, s[2:3]
	global_load_dwordx4 v[206:209], v1, s[2:3] offset:16
	s_add_u32 s2, s2, 0x2000
	s_addc_u32 s3, s3, 0
	v_pk_fma_f32 v[34:35], v[40:41], v[46:47], v[34:35] op_sel:[1,0,0]
	v_pk_fma_f32 v[28:29], v[40:41], v[48:49], v[28:29] op_sel:[1,0,0]
	v_pk_fma_f32 v[24:25], v[40:41], v[50:51], v[24:25] op_sel:[1,0,0]
	v_pk_fma_f32 v[20:21], v[40:41], v[52:53], v[20:21] op_sel:[1,0,0]
	v_pk_fma_f32 v[16:17], v[40:41], v[54:55], v[16:17] op_sel:[1,0,0]
	v_pk_fma_f32 v[12:13], v[40:41], v[56:57], v[12:13] op_sel:[1,0,0]
	v_pk_fma_f32 v[8:9], v[40:41], v[58:59], v[8:9] op_sel:[1,0,0]
	v_pk_fma_f32 v[4:5], v[40:41], v[60:61], v[4:5] op_sel:[1,0,0]
	v_pk_fma_f32 v[36:37], v[38:39], v[46:47], v[36:37] op_sel:[1,0,0]
	v_pk_fma_f32 v[30:31], v[38:39], v[48:49], v[30:31] op_sel:[1,0,0]
	v_pk_fma_f32 v[26:27], v[38:39], v[50:51], v[26:27] op_sel:[1,0,0]
	v_pk_fma_f32 v[22:23], v[38:39], v[52:53], v[22:23] op_sel:[1,0,0]
	v_pk_fma_f32 v[18:19], v[38:39], v[54:55], v[18:19] op_sel:[1,0,0]
	v_pk_fma_f32 v[14:15], v[38:39], v[56:57], v[14:15] op_sel:[1,0,0]
	v_pk_fma_f32 v[10:11], v[38:39], v[58:59], v[10:11] op_sel:[1,0,0]
	v_pk_fma_f32 v[6:7], v[38:39], v[60:61], v[6:7] op_sel:[1,0,0]
	ds_read_b64 v[40:41], v62 offset:8
	ds_read_b64 v[38:39], v62 offset:264
	s_waitcnt vmcnt(12)
	v_lshlrev_b32_e32 v46, 16, v210
	v_and_b32_e32 v47, 0xffff0000, v210
	v_lshlrev_b32_e32 v48, 16, v211
	v_and_b32_e32 v49, 0xffff0000, v211
	v_lshlrev_b32_e32 v50, 16, v212
	v_and_b32_e32 v51, 0xffff0000, v212
	v_lshlrev_b32_e32 v52, 16, v213
	v_and_b32_e32 v53, 0xffff0000, v213
	v_lshlrev_b32_e32 v54, 16, v214
	v_and_b32_e32 v55, 0xffff0000, v214
	v_lshlrev_b32_e32 v56, 16, v215
	v_and_b32_e32 v57, 0xffff0000, v215
	v_lshlrev_b32_e32 v58, 16, v216
	v_and_b32_e32 v59, 0xffff0000, v216
	v_lshlrev_b32_e32 v60, 16, v217
	v_and_b32_e32 v61, 0xffff0000, v217
	s_waitcnt lgkmcnt(0)
	v_pk_fma_f32 v[34:35], v[40:41], v[46:47], v[34:35] op_sel_hi:[0,1,1]
	v_pk_fma_f32 v[28:29], v[40:41], v[48:49], v[28:29] op_sel_hi:[0,1,1]
	v_pk_fma_f32 v[24:25], v[40:41], v[50:51], v[24:25] op_sel_hi:[0,1,1]
	v_pk_fma_f32 v[20:21], v[40:41], v[52:53], v[20:21] op_sel_hi:[0,1,1]
	v_pk_fma_f32 v[16:17], v[40:41], v[54:55], v[16:17] op_sel_hi:[0,1,1]
	v_pk_fma_f32 v[12:13], v[40:41], v[56:57], v[12:13] op_sel_hi:[0,1,1]
	v_pk_fma_f32 v[8:9], v[40:41], v[58:59], v[8:9] op_sel_hi:[0,1,1]
	v_pk_fma_f32 v[4:5], v[40:41], v[60:61], v[4:5] op_sel_hi:[0,1,1]
	v_pk_fma_f32 v[36:37], v[38:39], v[46:47], v[36:37] op_sel_hi:[0,1,1]
	v_pk_fma_f32 v[30:31], v[38:39], v[48:49], v[30:31] op_sel_hi:[0,1,1]
	v_pk_fma_f32 v[26:27], v[38:39], v[50:51], v[26:27] op_sel_hi:[0,1,1]
	v_pk_fma_f32 v[22:23], v[38:39], v[52:53], v[22:23] op_sel_hi:[0,1,1]
	v_pk_fma_f32 v[18:19], v[38:39], v[54:55], v[18:19] op_sel_hi:[0,1,1]
	v_pk_fma_f32 v[14:15], v[38:39], v[56:57], v[14:15] op_sel_hi:[0,1,1]
	v_pk_fma_f32 v[10:11], v[38:39], v[58:59], v[10:11] op_sel_hi:[0,1,1]
	v_pk_fma_f32 v[6:7], v[38:39], v[60:61], v[6:7] op_sel_hi:[0,1,1]
	v_lshlrev_b32_e32 v46, 16, v218
	v_and_b32_e32 v47, 0xffff0000, v218
	v_lshlrev_b32_e32 v48, 16, v219
	v_and_b32_e32 v49, 0xffff0000, v219
	v_lshlrev_b32_e32 v50, 16, v220
	v_and_b32_e32 v51, 0xffff0000, v220
	v_lshlrev_b32_e32 v52, 16, v221
	v_and_b32_e32 v53, 0xffff0000, v221
	v_lshlrev_b32_e32 v54, 16, v222
	v_and_b32_e32 v55, 0xffff0000, v222
	v_lshlrev_b32_e32 v56, 16, v223
	v_and_b32_e32 v57, 0xffff0000, v223
	v_lshlrev_b32_e32 v58, 16, v224
	v_and_b32_e32 v59, 0xffff0000, v224
	v_lshlrev_b32_e32 v60, 16, v225
	v_and_b32_e32 v61, 0xffff0000, v225
	global_load_dwordx4 v[210:213], v1, s[2:3]
	global_load_dwordx4 v[214:217], v1, s[2:3] offset:16
	s_add_u32 s2, s2, 0x2000
	s_addc_u32 s3, s3, 0
	global_load_dwordx4 v[218:221], v1, s[2:3]
	global_load_dwordx4 v[222:225], v1, s[2:3] offset:16
	s_add_u32 s2, s2, 0x2000
	s_addc_u32 s3, s3, 0
	v_pk_fma_f32 v[34:35], v[40:41], v[46:47], v[34:35] op_sel:[1,0,0]
	v_pk_fma_f32 v[28:29], v[40:41], v[48:49], v[28:29] op_sel:[1,0,0]
	v_pk_fma_f32 v[24:25], v[40:41], v[50:51], v[24:25] op_sel:[1,0,0]
	v_pk_fma_f32 v[20:21], v[40:41], v[52:53], v[20:21] op_sel:[1,0,0]
	v_pk_fma_f32 v[16:17], v[40:41], v[54:55], v[16:17] op_sel:[1,0,0]
	v_pk_fma_f32 v[12:13], v[40:41], v[56:57], v[12:13] op_sel:[1,0,0]
	v_pk_fma_f32 v[8:9], v[40:41], v[58:59], v[8:9] op_sel:[1,0,0]
	v_pk_fma_f32 v[4:5], v[40:41], v[60:61], v[4:5] op_sel:[1,0,0]
	v_pk_fma_f32 v[36:37], v[38:39], v[46:47], v[36:37] op_sel:[1,0,0]
	v_pk_fma_f32 v[30:31], v[38:39], v[48:49], v[30:31] op_sel:[1,0,0]
	v_pk_fma_f32 v[26:27], v[38:39], v[50:51], v[26:27] op_sel:[1,0,0]
	v_pk_fma_f32 v[22:23], v[38:39], v[52:53], v[22:23] op_sel:[1,0,0]
	v_pk_fma_f32 v[18:19], v[38:39], v[54:55], v[18:19] op_sel:[1,0,0]
	v_pk_fma_f32 v[14:15], v[38:39], v[56:57], v[14:15] op_sel:[1,0,0]
	v_pk_fma_f32 v[10:11], v[38:39], v[58:59], v[10:11] op_sel:[1,0,0]
	v_pk_fma_f32 v[6:7], v[38:39], v[60:61], v[6:7] op_sel:[1,0,0]
	ds_read_b64 v[40:41], v62 offset:16
	ds_read_b64 v[38:39], v62 offset:272
	s_waitcnt vmcnt(12)
	v_lshlrev_b32_e32 v46, 16, v226
	v_and_b32_e32 v47, 0xffff0000, v226
	v_lshlrev_b32_e32 v48, 16, v227
	v_and_b32_e32 v49, 0xffff0000, v227
	v_lshlrev_b32_e32 v50, 16, v228
	v_and_b32_e32 v51, 0xffff0000, v228
	v_lshlrev_b32_e32 v52, 16, v229
	v_and_b32_e32 v53, 0xffff0000, v229
	v_lshlrev_b32_e32 v54, 16, v230
	v_and_b32_e32 v55, 0xffff0000, v230
	v_lshlrev_b32_e32 v56, 16, v231
	v_and_b32_e32 v57, 0xffff0000, v231
	v_lshlrev_b32_e32 v58, 16, v232
	v_and_b32_e32 v59, 0xffff0000, v232
	v_lshlrev_b32_e32 v60, 16, v233
	v_and_b32_e32 v61, 0xffff0000, v233
	s_waitcnt lgkmcnt(0)
	v_pk_fma_f32 v[34:35], v[40:41], v[46:47], v[34:35] op_sel_hi:[0,1,1]
	v_pk_fma_f32 v[28:29], v[40:41], v[48:49], v[28:29] op_sel_hi:[0,1,1]
	v_pk_fma_f32 v[24:25], v[40:41], v[50:51], v[24:25] op_sel_hi:[0,1,1]
	v_pk_fma_f32 v[20:21], v[40:41], v[52:53], v[20:21] op_sel_hi:[0,1,1]
	v_pk_fma_f32 v[16:17], v[40:41], v[54:55], v[16:17] op_sel_hi:[0,1,1]
	v_pk_fma_f32 v[12:13], v[40:41], v[56:57], v[12:13] op_sel_hi:[0,1,1]
	v_pk_fma_f32 v[8:9], v[40:41], v[58:59], v[8:9] op_sel_hi:[0,1,1]
	v_pk_fma_f32 v[4:5], v[40:41], v[60:61], v[4:5] op_sel_hi:[0,1,1]
	v_pk_fma_f32 v[36:37], v[38:39], v[46:47], v[36:37] op_sel_hi:[0,1,1]
	v_pk_fma_f32 v[30:31], v[38:39], v[48:49], v[30:31] op_sel_hi:[0,1,1]
	v_pk_fma_f32 v[26:27], v[38:39], v[50:51], v[26:27] op_sel_hi:[0,1,1]
	v_pk_fma_f32 v[22:23], v[38:39], v[52:53], v[22:23] op_sel_hi:[0,1,1]
	v_pk_fma_f32 v[18:19], v[38:39], v[54:55], v[18:19] op_sel_hi:[0,1,1]
	v_pk_fma_f32 v[14:15], v[38:39], v[56:57], v[14:15] op_sel_hi:[0,1,1]
	v_pk_fma_f32 v[10:11], v[38:39], v[58:59], v[10:11] op_sel_hi:[0,1,1]
	v_pk_fma_f32 v[6:7], v[38:39], v[60:61], v[6:7] op_sel_hi:[0,1,1]
	v_lshlrev_b32_e32 v46, 16, v234
	v_and_b32_e32 v47, 0xffff0000, v234
	v_lshlrev_b32_e32 v48, 16, v235
	v_and_b32_e32 v49, 0xffff0000, v235
	v_lshlrev_b32_e32 v50, 16, v236
	v_and_b32_e32 v51, 0xffff0000, v236
	v_lshlrev_b32_e32 v52, 16, v237
	v_and_b32_e32 v53, 0xffff0000, v237
	v_lshlrev_b32_e32 v54, 16, v238
	v_and_b32_e32 v55, 0xffff0000, v238
	v_lshlrev_b32_e32 v56, 16, v239
	v_and_b32_e32 v57, 0xffff0000, v239
	v_lshlrev_b32_e32 v58, 16, v240
	v_and_b32_e32 v59, 0xffff0000, v240
	v_lshlrev_b32_e32 v60, 16, v241
	v_and_b32_e32 v61, 0xffff0000, v241
	global_load_dwordx4 v[226:229], v1, s[2:3]
	global_load_dwordx4 v[230:233], v1, s[2:3] offset:16
	s_add_u32 s2, s2, 0x2000
	s_addc_u32 s3, s3, 0
	global_load_dwordx4 v[234:237], v1, s[2:3]
	global_load_dwordx4 v[238:241], v1, s[2:3] offset:16
	s_add_u32 s2, s2, 0x2000
	s_addc_u32 s3, s3, 0
	v_pk_fma_f32 v[34:35], v[40:41], v[46:47], v[34:35] op_sel:[1,0,0]
	v_pk_fma_f32 v[28:29], v[40:41], v[48:49], v[28:29] op_sel:[1,0,0]
	v_pk_fma_f32 v[24:25], v[40:41], v[50:51], v[24:25] op_sel:[1,0,0]
	v_pk_fma_f32 v[20:21], v[40:41], v[52:53], v[20:21] op_sel:[1,0,0]
	v_pk_fma_f32 v[16:17], v[40:41], v[54:55], v[16:17] op_sel:[1,0,0]
	v_pk_fma_f32 v[12:13], v[40:41], v[56:57], v[12:13] op_sel:[1,0,0]
	v_pk_fma_f32 v[8:9], v[40:41], v[58:59], v[8:9] op_sel:[1,0,0]
	v_pk_fma_f32 v[4:5], v[40:41], v[60:61], v[4:5] op_sel:[1,0,0]
	v_pk_fma_f32 v[36:37], v[38:39], v[46:47], v[36:37] op_sel:[1,0,0]
	v_pk_fma_f32 v[30:31], v[38:39], v[48:49], v[30:31] op_sel:[1,0,0]
	v_pk_fma_f32 v[26:27], v[38:39], v[50:51], v[26:27] op_sel:[1,0,0]
	v_pk_fma_f32 v[22:23], v[38:39], v[52:53], v[22:23] op_sel:[1,0,0]
	v_pk_fma_f32 v[18:19], v[38:39], v[54:55], v[18:19] op_sel:[1,0,0]
	v_pk_fma_f32 v[14:15], v[38:39], v[56:57], v[14:15] op_sel:[1,0,0]
	v_pk_fma_f32 v[10:11], v[38:39], v[58:59], v[10:11] op_sel:[1,0,0]
	v_pk_fma_f32 v[6:7], v[38:39], v[60:61], v[6:7] op_sel:[1,0,0]
	ds_read_b64 v[40:41], v62 offset:24
	ds_read_b64 v[38:39], v62 offset:280
	s_waitcnt vmcnt(12)
	v_lshlrev_b32_e32 v46, 16, v242
	v_and_b32_e32 v47, 0xffff0000, v242
	v_lshlrev_b32_e32 v48, 16, v243
	v_and_b32_e32 v49, 0xffff0000, v243
	v_lshlrev_b32_e32 v50, 16, v244
	v_and_b32_e32 v51, 0xffff0000, v244
	v_lshlrev_b32_e32 v52, 16, v245
	v_and_b32_e32 v53, 0xffff0000, v245
	v_lshlrev_b32_e32 v54, 16, v246
	v_and_b32_e32 v55, 0xffff0000, v246
	v_lshlrev_b32_e32 v56, 16, v247
	v_and_b32_e32 v57, 0xffff0000, v247
	v_lshlrev_b32_e32 v58, 16, v248
	v_and_b32_e32 v59, 0xffff0000, v248
	v_lshlrev_b32_e32 v60, 16, v249
	v_and_b32_e32 v61, 0xffff0000, v249
	s_waitcnt lgkmcnt(0)
	v_pk_fma_f32 v[34:35], v[40:41], v[46:47], v[34:35] op_sel_hi:[0,1,1]
	v_pk_fma_f32 v[28:29], v[40:41], v[48:49], v[28:29] op_sel_hi:[0,1,1]
	v_pk_fma_f32 v[24:25], v[40:41], v[50:51], v[24:25] op_sel_hi:[0,1,1]
	v_pk_fma_f32 v[20:21], v[40:41], v[52:53], v[20:21] op_sel_hi:[0,1,1]
	v_pk_fma_f32 v[16:17], v[40:41], v[54:55], v[16:17] op_sel_hi:[0,1,1]
	v_pk_fma_f32 v[12:13], v[40:41], v[56:57], v[12:13] op_sel_hi:[0,1,1]
	v_pk_fma_f32 v[8:9], v[40:41], v[58:59], v[8:9] op_sel_hi:[0,1,1]
	v_pk_fma_f32 v[4:5], v[40:41], v[60:61], v[4:5] op_sel_hi:[0,1,1]
	v_pk_fma_f32 v[36:37], v[38:39], v[46:47], v[36:37] op_sel_hi:[0,1,1]
	v_pk_fma_f32 v[30:31], v[38:39], v[48:49], v[30:31] op_sel_hi:[0,1,1]
	v_pk_fma_f32 v[26:27], v[38:39], v[50:51], v[26:27] op_sel_hi:[0,1,1]
	v_pk_fma_f32 v[22:23], v[38:39], v[52:53], v[22:23] op_sel_hi:[0,1,1]
	v_pk_fma_f32 v[18:19], v[38:39], v[54:55], v[18:19] op_sel_hi:[0,1,1]
	v_pk_fma_f32 v[14:15], v[38:39], v[56:57], v[14:15] op_sel_hi:[0,1,1]
	v_pk_fma_f32 v[10:11], v[38:39], v[58:59], v[10:11] op_sel_hi:[0,1,1]
	v_pk_fma_f32 v[6:7], v[38:39], v[60:61], v[6:7] op_sel_hi:[0,1,1]
	v_lshlrev_b32_e32 v46, 16, v250
	v_and_b32_e32 v47, 0xffff0000, v250
	v_lshlrev_b32_e32 v48, 16, v251
	v_and_b32_e32 v49, 0xffff0000, v251
	v_lshlrev_b32_e32 v50, 16, v252
	v_and_b32_e32 v51, 0xffff0000, v252
	v_lshlrev_b32_e32 v52, 16, v253
	v_and_b32_e32 v53, 0xffff0000, v253
	v_lshlrev_b32_e32 v54, 16, v42
	v_and_b32_e32 v55, 0xffff0000, v42
	v_lshlrev_b32_e32 v56, 16, v43
	v_and_b32_e32 v57, 0xffff0000, v43
	v_lshlrev_b32_e32 v58, 16, v44
	v_and_b32_e32 v59, 0xffff0000, v44
	v_lshlrev_b32_e32 v60, 16, v45
	v_and_b32_e32 v61, 0xffff0000, v45
	global_load_dwordx4 v[242:245], v1, s[2:3]
	global_load_dwordx4 v[246:249], v1, s[2:3] offset:16
	s_add_u32 s2, s2, 0x2000
	s_addc_u32 s3, s3, 0
	global_load_dwordx4 v[250:253], v1, s[2:3]
	global_load_dwordx4 v[42:45], v1, s[2:3] offset:16
	s_add_u32 s2, s2, 0x2000
	s_addc_u32 s3, s3, 0
	v_pk_fma_f32 v[34:35], v[40:41], v[46:47], v[34:35] op_sel:[1,0,0]
	v_pk_fma_f32 v[28:29], v[40:41], v[48:49], v[28:29] op_sel:[1,0,0]
	v_pk_fma_f32 v[24:25], v[40:41], v[50:51], v[24:25] op_sel:[1,0,0]
	v_pk_fma_f32 v[20:21], v[40:41], v[52:53], v[20:21] op_sel:[1,0,0]
	v_pk_fma_f32 v[16:17], v[40:41], v[54:55], v[16:17] op_sel:[1,0,0]
	v_pk_fma_f32 v[12:13], v[40:41], v[56:57], v[12:13] op_sel:[1,0,0]
	v_pk_fma_f32 v[8:9], v[40:41], v[58:59], v[8:9] op_sel:[1,0,0]
	v_pk_fma_f32 v[4:5], v[40:41], v[60:61], v[4:5] op_sel:[1,0,0]
	v_pk_fma_f32 v[36:37], v[38:39], v[46:47], v[36:37] op_sel:[1,0,0]
	v_pk_fma_f32 v[30:31], v[38:39], v[48:49], v[30:31] op_sel:[1,0,0]
	v_pk_fma_f32 v[26:27], v[38:39], v[50:51], v[26:27] op_sel:[1,0,0]
	v_pk_fma_f32 v[22:23], v[38:39], v[52:53], v[22:23] op_sel:[1,0,0]
	v_pk_fma_f32 v[18:19], v[38:39], v[54:55], v[18:19] op_sel:[1,0,0]
	v_pk_fma_f32 v[14:15], v[38:39], v[56:57], v[14:15] op_sel:[1,0,0]
	v_pk_fma_f32 v[10:11], v[38:39], v[58:59], v[10:11] op_sel:[1,0,0]
	v_pk_fma_f32 v[6:7], v[38:39], v[60:61], v[6:7] op_sel:[1,0,0]
	v_add_u32_e32 v62, 32, v62
	s_add_u32 s0, s0, 1
	s_cmp_lt_u32 s0, 7
	s_cbranch_scc1 .Lhy_tap_loop
	ds_read_b64 v[40:41], v62
	ds_read_b64 v[38:39], v62 offset:256
	s_waitcnt vmcnt(12)
	v_lshlrev_b32_e32 v46, 16, v194
	v_and_b32_e32 v47, 0xffff0000, v194
	v_lshlrev_b32_e32 v48, 16, v195
	v_and_b32_e32 v49, 0xffff0000, v195
	v_lshlrev_b32_e32 v50, 16, v196
	v_and_b32_e32 v51, 0xffff0000, v196
	v_lshlrev_b32_e32 v52, 16, v197
	v_and_b32_e32 v53, 0xffff0000, v197
	v_lshlrev_b32_e32 v54, 16, v198
	v_and_b32_e32 v55, 0xffff0000, v198
	v_lshlrev_b32_e32 v56, 16, v199
	v_and_b32_e32 v57, 0xffff0000, v199
	v_lshlrev_b32_e32 v58, 16, v200
	v_and_b32_e32 v59, 0xffff0000, v200
	v_lshlrev_b32_e32 v60, 16, v201
	v_and_b32_e32 v61, 0xffff0000, v201
	s_waitcnt lgkmcnt(0)
	v_pk_fma_f32 v[34:35], v[40:41], v[46:47], v[34:35] op_sel_hi:[0,1,1]
	v_pk_fma_f32 v[28:29], v[40:41], v[48:49], v[28:29] op_sel_hi:[0,1,1]
	v_pk_fma_f32 v[24:25], v[40:41], v[50:51], v[24:25] op_sel_hi:[0,1,1]
	v_pk_fma_f32 v[20:21], v[40:41], v[52:53], v[20:21] op_sel_hi:[0,1,1]
	v_pk_fma_f32 v[16:17], v[40:41], v[54:55], v[16:17] op_sel_hi:[0,1,1]
	v_pk_fma_f32 v[12:13], v[40:41], v[56:57], v[12:13] op_sel_hi:[0,1,1]
	v_pk_fma_f32 v[8:9], v[40:41], v[58:59], v[8:9] op_sel_hi:[0,1,1]
	v_pk_fma_f32 v[4:5], v[40:41], v[60:61], v[4:5] op_sel_hi:[0,1,1]
	v_pk_fma_f32 v[36:37], v[38:39], v[46:47], v[36:37] op_sel_hi:[0,1,1]
	v_pk_fma_f32 v[30:31], v[38:39], v[48:49], v[30:31] op_sel_hi:[0,1,1]
	v_pk_fma_f32 v[26:27], v[38:39], v[50:51], v[26:27] op_sel_hi:[0,1,1]
	v_pk_fma_f32 v[22:23], v[38:39], v[52:53], v[22:23] op_sel_hi:[0,1,1]
	v_pk_fma_f32 v[18:19], v[38:39], v[54:55], v[18:19] op_sel_hi:[0,1,1]
	v_pk_fma_f32 v[14:15], v[38:39], v[56:57], v[14:15] op_sel_hi:[0,1,1]
	v_pk_fma_f32 v[10:11], v[38:39], v[58:59], v[10:11] op_sel_hi:[0,1,1]
	v_pk_fma_f32 v[6:7], v[38:39], v[60:61], v[6:7] op_sel_hi:[0,1,1]
	v_lshlrev_b32_e32 v46, 16, v202
	v_and_b32_e32 v47, 0xffff0000, v202
	v_lshlrev_b32_e32 v48, 16, v203
	v_and_b32_e32 v49, 0xffff0000, v203
	v_lshlrev_b32_e32 v50, 16, v204
	v_and_b32_e32 v51, 0xffff0000, v204
	v_lshlrev_b32_e32 v52, 16, v205
	v_and_b32_e32 v53, 0xffff0000, v205
	v_lshlrev_b32_e32 v54, 16, v206
	v_and_b32_e32 v55, 0xffff0000, v206
	v_lshlrev_b32_e32 v56, 16, v207
	v_and_b32_e32 v57, 0xffff0000, v207
	v_lshlrev_b32_e32 v58, 16, v208
	v_and_b32_e32 v59, 0xffff0000, v208
	v_lshlrev_b32_e32 v60, 16, v209
	v_and_b32_e32 v61, 0xffff0000, v209
	v_pk_fma_f32 v[34:35], v[40:41], v[46:47], v[34:35] op_sel:[1,0,0]
	v_pk_fma_f32 v[28:29], v[40:41], v[48:49], v[28:29] op_sel:[1,0,0]
	v_pk_fma_f32 v[24:25], v[40:41], v[50:51], v[24:25] op_sel:[1,0,0]
	v_pk_fma_f32 v[20:21], v[40:41], v[52:53], v[20:21] op_sel:[1,0,0]
	v_pk_fma_f32 v[16:17], v[40:41], v[54:55], v[16:17] op_sel:[1,0,0]
	v_pk_fma_f32 v[12:13], v[40:41], v[56:57], v[12:13] op_sel:[1,0,0]
	v_pk_fma_f32 v[8:9], v[40:41], v[58:59], v[8:9] op_sel:[1,0,0]
	v_pk_fma_f32 v[4:5], v[40:41], v[60:61], v[4:5] op_sel:[1,0,0]
	v_pk_fma_f32 v[36:37], v[38:39], v[46:47], v[36:37] op_sel:[1,0,0]
	v_pk_fma_f32 v[30:31], v[38:39], v[48:49], v[30:31] op_sel:[1,0,0]
	v_pk_fma_f32 v[26:27], v[38:39], v[50:51], v[26:27] op_sel:[1,0,0]
	v_pk_fma_f32 v[22:23], v[38:39], v[52:53], v[22:23] op_sel:[1,0,0]
	v_pk_fma_f32 v[18:19], v[38:39], v[54:55], v[18:19] op_sel:[1,0,0]
	v_pk_fma_f32 v[14:15], v[38:39], v[56:57], v[14:15] op_sel:[1,0,0]
	v_pk_fma_f32 v[10:11], v[38:39], v[58:59], v[10:11] op_sel:[1,0,0]
	v_pk_fma_f32 v[6:7], v[38:39], v[60:61], v[6:7] op_sel:[1,0,0]
	ds_read_b64 v[40:41], v62 offset:8
	ds_read_b64 v[38:39], v62 offset:264
	s_waitcnt vmcnt(8)
	v_lshlrev_b32_e32 v46, 16, v210
	v_and_b32_e32 v47, 0xffff0000, v210
	v_lshlrev_b32_e32 v48, 16, v211
	v_and_b32_e32 v49, 0xffff0000, v211
	v_lshlrev_b32_e32 v50, 16, v212
	v_and_b32_e32 v51, 0xffff0000, v212
	v_lshlrev_b32_e32 v52, 16, v213
	v_and_b32_e32 v53, 0xffff0000, v213
	v_lshlrev_b32_e32 v54, 16, v214
	v_and_b32_e32 v55, 0xffff0000, v214
	v_lshlrev_b32_e32 v56, 16, v215
	v_and_b32_e32 v57, 0xffff0000, v215
	v_lshlrev_b32_e32 v58, 16, v216
	v_and_b32_e32 v59, 0xffff0000, v216
	v_lshlrev_b32_e32 v60, 16, v217
	v_and_b32_e32 v61, 0xffff0000, v217
	s_waitcnt lgkmcnt(0)
	v_pk_fma_f32 v[34:35], v[40:41], v[46:47], v[34:35] op_sel_hi:[0,1,1]
	v_pk_fma_f32 v[28:29], v[40:41], v[48:49], v[28:29] op_sel_hi:[0,1,1]
	v_pk_fma_f32 v[24:25], v[40:41], v[50:51], v[24:25] op_sel_hi:[0,1,1]
	v_pk_fma_f32 v[20:21], v[40:41], v[52:53], v[20:21] op_sel_hi:[0,1,1]
	v_pk_fma_f32 v[16:17], v[40:41], v[54:55], v[16:17] op_sel_hi:[0,1,1]
	v_pk_fma_f32 v[12:13], v[40:41], v[56:57], v[12:13] op_sel_hi:[0,1,1]
	v_pk_fma_f32 v[8:9], v[40:41], v[58:59], v[8:9] op_sel_hi:[0,1,1]
	v_pk_fma_f32 v[4:5], v[40:41], v[60:61], v[4:5] op_sel_hi:[0,1,1]
	v_pk_fma_f32 v[36:37], v[38:39], v[46:47], v[36:37] op_sel_hi:[0,1,1]
	v_pk_fma_f32 v[30:31], v[38:39], v[48:49], v[30:31] op_sel_hi:[0,1,1]
	v_pk_fma_f32 v[26:27], v[38:39], v[50:51], v[26:27] op_sel_hi:[0,1,1]
	v_pk_fma_f32 v[22:23], v[38:39], v[52:53], v[22:23] op_sel_hi:[0,1,1]
	v_pk_fma_f32 v[18:19], v[38:39], v[54:55], v[18:19] op_sel_hi:[0,1,1]
	v_pk_fma_f32 v[14:15], v[38:39], v[56:57], v[14:15] op_sel_hi:[0,1,1]
	v_pk_fma_f32 v[10:11], v[38:39], v[58:59], v[10:11] op_sel_hi:[0,1,1]
	v_pk_fma_f32 v[6:7], v[38:39], v[60:61], v[6:7] op_sel_hi:[0,1,1]
	v_lshlrev_b32_e32 v46, 16, v218
	v_and_b32_e32 v47, 0xffff0000, v218
	v_lshlrev_b32_e32 v48, 16, v219
	v_and_b32_e32 v49, 0xffff0000, v219
	v_lshlrev_b32_e32 v50, 16, v220
	v_and_b32_e32 v51, 0xffff0000, v220
	v_lshlrev_b32_e32 v52, 16, v221
	v_and_b32_e32 v53, 0xffff0000, v221
	v_lshlrev_b32_e32 v54, 16, v222
	v_and_b32_e32 v55, 0xffff0000, v222
	v_lshlrev_b32_e32 v56, 16, v223
	v_and_b32_e32 v57, 0xffff0000, v223
	v_lshlrev_b32_e32 v58, 16, v224
	v_and_b32_e32 v59, 0xffff0000, v224
	v_lshlrev_b32_e32 v60, 16, v225
	v_and_b32_e32 v61, 0xffff0000, v225
	v_pk_fma_f32 v[34:35], v[40:41], v[46:47], v[34:35] op_sel:[1,0,0]
	v_pk_fma_f32 v[28:29], v[40:41], v[48:49], v[28:29] op_sel:[1,0,0]
	v_pk_fma_f32 v[24:25], v[40:41], v[50:51], v[24:25] op_sel:[1,0,0]
	v_pk_fma_f32 v[20:21], v[40:41], v[52:53], v[20:21] op_sel:[1,0,0]
	v_pk_fma_f32 v[16:17], v[40:41], v[54:55], v[16:17] op_sel:[1,0,0]
	v_pk_fma_f32 v[12:13], v[40:41], v[56:57], v[12:13] op_sel:[1,0,0]
	v_pk_fma_f32 v[8:9], v[40:41], v[58:59], v[8:9] op_sel:[1,0,0]
	v_pk_fma_f32 v[4:5], v[40:41], v[60:61], v[4:5] op_sel:[1,0,0]
	v_pk_fma_f32 v[36:37], v[38:39], v[46:47], v[36:37] op_sel:[1,0,0]
	v_pk_fma_f32 v[30:31], v[38:39], v[48:49], v[30:31] op_sel:[1,0,0]
	v_pk_fma_f32 v[26:27], v[38:39], v[50:51], v[26:27] op_sel:[1,0,0]
	v_pk_fma_f32 v[22:23], v[38:39], v[52:53], v[22:23] op_sel:[1,0,0]
	v_pk_fma_f32 v[18:19], v[38:39], v[54:55], v[18:19] op_sel:[1,0,0]
	v_pk_fma_f32 v[14:15], v[38:39], v[56:57], v[14:15] op_sel:[1,0,0]
	v_pk_fma_f32 v[10:11], v[38:39], v[58:59], v[10:11] op_sel:[1,0,0]
	v_pk_fma_f32 v[6:7], v[38:39], v[60:61], v[6:7] op_sel:[1,0,0]
	ds_read_b64 v[40:41], v62 offset:16
	ds_read_b64 v[38:39], v62 offset:272
	s_waitcnt vmcnt(4)
	v_lshlrev_b32_e32 v46, 16, v226
	v_and_b32_e32 v47, 0xffff0000, v226
	v_lshlrev_b32_e32 v48, 16, v227
	v_and_b32_e32 v49, 0xffff0000, v227
	v_lshlrev_b32_e32 v50, 16, v228
	v_and_b32_e32 v51, 0xffff0000, v228
	v_lshlrev_b32_e32 v52, 16, v229
	v_and_b32_e32 v53, 0xffff0000, v229
	v_lshlrev_b32_e32 v54, 16, v230
	v_and_b32_e32 v55, 0xffff0000, v230
	v_lshlrev_b32_e32 v56, 16, v231
	v_and_b32_e32 v57, 0xffff0000, v231
	v_lshlrev_b32_e32 v58, 16, v232
	v_and_b32_e32 v59, 0xffff0000, v232
	v_lshlrev_b32_e32 v60, 16, v233
	v_and_b32_e32 v61, 0xffff0000, v233
	s_waitcnt lgkmcnt(0)
	v_pk_fma_f32 v[34:35], v[40:41], v[46:47], v[34:35] op_sel_hi:[0,1,1]
	v_pk_fma_f32 v[28:29], v[40:41], v[48:49], v[28:29] op_sel_hi:[0,1,1]
	v_pk_fma_f32 v[24:25], v[40:41], v[50:51], v[24:25] op_sel_hi:[0,1,1]
	v_pk_fma_f32 v[20:21], v[40:41], v[52:53], v[20:21] op_sel_hi:[0,1,1]
	v_pk_fma_f32 v[16:17], v[40:41], v[54:55], v[16:17] op_sel_hi:[0,1,1]
	v_pk_fma_f32 v[12:13], v[40:41], v[56:57], v[12:13] op_sel_hi:[0,1,1]
	v_pk_fma_f32 v[8:9], v[40:41], v[58:59], v[8:9] op_sel_hi:[0,1,1]
	v_pk_fma_f32 v[4:5], v[40:41], v[60:61], v[4:5] op_sel_hi:[0,1,1]
	v_pk_fma_f32 v[36:37], v[38:39], v[46:47], v[36:37] op_sel_hi:[0,1,1]
	v_pk_fma_f32 v[30:31], v[38:39], v[48:49], v[30:31] op_sel_hi:[0,1,1]
	v_pk_fma_f32 v[26:27], v[38:39], v[50:51], v[26:27] op_sel_hi:[0,1,1]
	v_pk_fma_f32 v[22:23], v[38:39], v[52:53], v[22:23] op_sel_hi:[0,1,1]
	v_pk_fma_f32 v[18:19], v[38:39], v[54:55], v[18:19] op_sel_hi:[0,1,1]
	v_pk_fma_f32 v[14:15], v[38:39], v[56:57], v[14:15] op_sel_hi:[0,1,1]
	v_pk_fma_f32 v[10:11], v[38:39], v[58:59], v[10:11] op_sel_hi:[0,1,1]
	v_pk_fma_f32 v[6:7], v[38:39], v[60:61], v[6:7] op_sel_hi:[0,1,1]
	v_lshlrev_b32_e32 v46, 16, v234
	v_and_b32_e32 v47, 0xffff0000, v234
	v_lshlrev_b32_e32 v48, 16, v235
	v_and_b32_e32 v49, 0xffff0000, v235
	v_lshlrev_b32_e32 v50, 16, v236
	v_and_b32_e32 v51, 0xffff0000, v236
	v_lshlrev_b32_e32 v52, 16, v237
	v_and_b32_e32 v53, 0xffff0000, v237
	v_lshlrev_b32_e32 v54, 16, v238
	v_and_b32_e32 v55, 0xffff0000, v238
	v_lshlrev_b32_e32 v56, 16, v239
	v_and_b32_e32 v57, 0xffff0000, v239
	v_lshlrev_b32_e32 v58, 16, v240
	v_and_b32_e32 v59, 0xffff0000, v240
	v_lshlrev_b32_e32 v60, 16, v241
	v_and_b32_e32 v61, 0xffff0000, v241
	v_pk_fma_f32 v[34:35], v[40:41], v[46:47], v[34:35] op_sel:[1,0,0]
	v_pk_fma_f32 v[28:29], v[40:41], v[48:49], v[28:29] op_sel:[1,0,0]
	v_pk_fma_f32 v[24:25], v[40:41], v[50:51], v[24:25] op_sel:[1,0,0]
	v_pk_fma_f32 v[20:21], v[40:41], v[52:53], v[20:21] op_sel:[1,0,0]
	v_pk_fma_f32 v[16:17], v[40:41], v[54:55], v[16:17] op_sel:[1,0,0]
	v_pk_fma_f32 v[12:13], v[40:41], v[56:57], v[12:13] op_sel:[1,0,0]
	v_pk_fma_f32 v[8:9], v[40:41], v[58:59], v[8:9] op_sel:[1,0,0]
	v_pk_fma_f32 v[4:5], v[40:41], v[60:61], v[4:5] op_sel:[1,0,0]
	v_pk_fma_f32 v[36:37], v[38:39], v[46:47], v[36:37] op_sel:[1,0,0]
	v_pk_fma_f32 v[30:31], v[38:39], v[48:49], v[30:31] op_sel:[1,0,0]
	v_pk_fma_f32 v[26:27], v[38:39], v[50:51], v[26:27] op_sel:[1,0,0]
	v_pk_fma_f32 v[22:23], v[38:39], v[52:53], v[22:23] op_sel:[1,0,0]
	v_pk_fma_f32 v[18:19], v[38:39], v[54:55], v[18:19] op_sel:[1,0,0]
	v_pk_fma_f32 v[14:15], v[38:39], v[56:57], v[14:15] op_sel:[1,0,0]
	v_pk_fma_f32 v[10:11], v[38:39], v[58:59], v[10:11] op_sel:[1,0,0]
	v_pk_fma_f32 v[6:7], v[38:39], v[60:61], v[6:7] op_sel:[1,0,0]
	ds_read_b64 v[40:41], v62 offset:24
	ds_read_b64 v[38:39], v62 offset:280
	s_waitcnt vmcnt(0)
	v_lshlrev_b32_e32 v46, 16, v242
	v_and_b32_e32 v47, 0xffff0000, v242
	v_lshlrev_b32_e32 v48, 16, v243
	v_and_b32_e32 v49, 0xffff0000, v243
	v_lshlrev_b32_e32 v50, 16, v244
	v_and_b32_e32 v51, 0xffff0000, v244
	v_lshlrev_b32_e32 v52, 16, v245
	v_and_b32_e32 v53, 0xffff0000, v245
	v_lshlrev_b32_e32 v54, 16, v246
	v_and_b32_e32 v55, 0xffff0000, v246
	v_lshlrev_b32_e32 v56, 16, v247
	v_and_b32_e32 v57, 0xffff0000, v247
	v_lshlrev_b32_e32 v58, 16, v248
	v_and_b32_e32 v59, 0xffff0000, v248
	v_lshlrev_b32_e32 v60, 16, v249
	v_and_b32_e32 v61, 0xffff0000, v249
	s_waitcnt lgkmcnt(0)
	v_pk_fma_f32 v[34:35], v[40:41], v[46:47], v[34:35] op_sel_hi:[0,1,1]
	v_pk_fma_f32 v[28:29], v[40:41], v[48:49], v[28:29] op_sel_hi:[0,1,1]
	v_pk_fma_f32 v[24:25], v[40:41], v[50:51], v[24:25] op_sel_hi:[0,1,1]
	v_pk_fma_f32 v[20:21], v[40:41], v[52:53], v[20:21] op_sel_hi:[0,1,1]
	v_pk_fma_f32 v[16:17], v[40:41], v[54:55], v[16:17] op_sel_hi:[0,1,1]
	v_pk_fma_f32 v[12:13], v[40:41], v[56:57], v[12:13] op_sel_hi:[0,1,1]
	v_pk_fma_f32 v[8:9], v[40:41], v[58:59], v[8:9] op_sel_hi:[0,1,1]
	v_pk_fma_f32 v[4:5], v[40:41], v[60:61], v[4:5] op_sel_hi:[0,1,1]
	v_pk_fma_f32 v[36:37], v[38:39], v[46:47], v[36:37] op_sel_hi:[0,1,1]
	v_pk_fma_f32 v[30:31], v[38:39], v[48:49], v[30:31] op_sel_hi:[0,1,1]
	v_pk_fma_f32 v[26:27], v[38:39], v[50:51], v[26:27] op_sel_hi:[0,1,1]
	v_pk_fma_f32 v[22:23], v[38:39], v[52:53], v[22:23] op_sel_hi:[0,1,1]
	v_pk_fma_f32 v[18:19], v[38:39], v[54:55], v[18:19] op_sel_hi:[0,1,1]
	v_pk_fma_f32 v[14:15], v[38:39], v[56:57], v[14:15] op_sel_hi:[0,1,1]
	v_pk_fma_f32 v[10:11], v[38:39], v[58:59], v[10:11] op_sel_hi:[0,1,1]
	v_pk_fma_f32 v[6:7], v[38:39], v[60:61], v[6:7] op_sel_hi:[0,1,1]
	v_lshlrev_b32_e32 v46, 16, v250
	v_and_b32_e32 v47, 0xffff0000, v250
	v_lshlrev_b32_e32 v48, 16, v251
	v_and_b32_e32 v49, 0xffff0000, v251
	v_lshlrev_b32_e32 v50, 16, v252
	v_and_b32_e32 v51, 0xffff0000, v252
	v_lshlrev_b32_e32 v52, 16, v253
	v_and_b32_e32 v53, 0xffff0000, v253
	v_lshlrev_b32_e32 v54, 16, v42
	v_and_b32_e32 v55, 0xffff0000, v42
	v_lshlrev_b32_e32 v56, 16, v43
	v_and_b32_e32 v57, 0xffff0000, v43
	v_lshlrev_b32_e32 v58, 16, v44
	v_and_b32_e32 v59, 0xffff0000, v44
	v_lshlrev_b32_e32 v60, 16, v45
	v_and_b32_e32 v61, 0xffff0000, v45
	v_pk_fma_f32 v[34:35], v[40:41], v[46:47], v[34:35] op_sel:[1,0,0]
	v_pk_fma_f32 v[28:29], v[40:41], v[48:49], v[28:29] op_sel:[1,0,0]
	v_pk_fma_f32 v[24:25], v[40:41], v[50:51], v[24:25] op_sel:[1,0,0]
	v_pk_fma_f32 v[20:21], v[40:41], v[52:53], v[20:21] op_sel:[1,0,0]
	v_pk_fma_f32 v[16:17], v[40:41], v[54:55], v[16:17] op_sel:[1,0,0]
	v_pk_fma_f32 v[12:13], v[40:41], v[56:57], v[12:13] op_sel:[1,0,0]
	v_pk_fma_f32 v[8:9], v[40:41], v[58:59], v[8:9] op_sel:[1,0,0]
	v_pk_fma_f32 v[4:5], v[40:41], v[60:61], v[4:5] op_sel:[1,0,0]
	v_pk_fma_f32 v[36:37], v[38:39], v[46:47], v[36:37] op_sel:[1,0,0]
	v_pk_fma_f32 v[30:31], v[38:39], v[48:49], v[30:31] op_sel:[1,0,0]
	v_pk_fma_f32 v[26:27], v[38:39], v[50:51], v[26:27] op_sel:[1,0,0]
	v_pk_fma_f32 v[22:23], v[38:39], v[52:53], v[22:23] op_sel:[1,0,0]
	v_pk_fma_f32 v[18:19], v[38:39], v[54:55], v[18:19] op_sel:[1,0,0]
	v_pk_fma_f32 v[14:15], v[38:39], v[56:57], v[14:15] op_sel:[1,0,0]
	v_pk_fma_f32 v[10:11], v[38:39], v[58:59], v[10:11] op_sel:[1,0,0]
	v_pk_fma_f32 v[6:7], v[38:39], v[60:61], v[6:7] op_sel:[1,0,0]
	s_mov_b32 s2, 0x80000
	s_mov_b32 s3, 0
	v_cvt_f32_i32_e32 v1, s88
	s_mov_b32 s0, 0x3fb8aa3b
	s_mov_b32 s1, 0xc2ce8ed0
	s_mov_b32 s2, 0x42b17218
	v_fmamk_f32 v3, v1, 0x3c44ade8, v186
	v_cvt_f32_i32_e32 v1, v2
	v_mul_f32_e32 v1, 0xb9800801, v1
	v_mul_f32_e64 v1, |v3|, v1
	v_mul_f32_e32 v32, 0x3fb8aa3b, v1
	v_fma_f32 v33, v1, s0, -v32
	v_rndne_f32_e32 v38, v32
	v_fmac_f32_e32 v33, 0x32a5705f, v1
	v_sub_f32_e32 v32, v32, v38
	v_add_f32_e32 v32, v32, v33
	v_exp_f32_e32 v32, v32
	v_cvt_i32_f32_e32 v33, v38
	v_cmp_ngt_f32_e32 vcc, s1, v1
	v_ldexp_f32 v32, v32, v33
	s_nop 0
	v_cndmask_b32_e32 v32, 0, v32, vcc
	v_cmp_nlt_f32_e32 vcc, s2, v1
	v_lshl_add_u32 v1, v2, 2, s33
	s_nop 0
	v_cndmask_b32_e32 v38, v190, v32, vcc
	v_or_b32_e32 v32, 1, v2
	v_cvt_f32_i32_e32 v32, v32
	v_mul_f32_e32 v32, 0xb9800801, v32
	v_mul_f32_e64 v32, |v3|, v32
	v_mul_f32_e32 v33, 0x3fb8aa3b, v32
	v_fma_f32 v39, v32, s0, -v33
	v_rndne_f32_e32 v40, v33
	v_fmac_f32_e32 v39, 0x32a5705f, v32
	v_sub_f32_e32 v33, v33, v40
	v_add_f32_e32 v33, v33, v39
	v_exp_f32_e32 v33, v33
	v_cvt_i32_f32_e32 v39, v40
	v_cmp_ngt_f32_e32 vcc, s1, v32
	v_ldexp_f32 v33, v33, v39
	s_nop 0
	v_cndmask_b32_e32 v33, 0, v33, vcc
	v_cmp_nlt_f32_e32 vcc, s2, v32
	s_nop 1
	v_cndmask_b32_e32 v39, v190, v33, vcc
	v_pk_mul_f32 v[32:33], v[38:39], v[34:35]
	v_or_b32_e32 v34, 2, v2
	v_cvt_f32_i32_e32 v34, v34
	v_pk_mul_f32 v[36:37], v[38:39], v[36:37]
	v_mul_f32_e32 v34, 0xb9800801, v34
	v_mul_f32_e64 v34, |v3|, v34
	v_mul_f32_e32 v35, 0x3fb8aa3b, v34
	v_fma_f32 v38, v34, s0, -v35
	v_rndne_f32_e32 v39, v35
	v_fmac_f32_e32 v38, 0x32a5705f, v34
	v_sub_f32_e32 v35, v35, v39
	v_add_f32_e32 v35, v35, v38
	v_exp_f32_e32 v35, v35
	v_cvt_i32_f32_e32 v38, v39
	v_cmp_ngt_f32_e32 vcc, s1, v34
	v_ldexp_f32 v35, v35, v38
	s_nop 0
	v_cndmask_b32_e32 v35, 0, v35, vcc
	v_cmp_nlt_f32_e32 vcc, s2, v34
	v_or_b32_e32 v34, 3, v2
	v_cvt_f32_i32_e32 v34, v34
	v_cndmask_b32_e32 v38, v190, v35, vcc
	v_mul_f32_e32 v34, 0xb9800801, v34
	v_mul_f32_e64 v34, |v3|, v34
	v_mul_f32_e32 v35, 0x3fb8aa3b, v34
	v_fma_f32 v39, v34, s0, -v35
	v_rndne_f32_e32 v40, v35
	v_fmac_f32_e32 v39, 0x32a5705f, v34
	v_sub_f32_e32 v35, v35, v40
	v_add_f32_e32 v35, v35, v39
	v_exp_f32_e32 v35, v35
	v_cvt_i32_f32_e32 v39, v40
	v_cmp_ngt_f32_e32 vcc, s1, v34
	v_ldexp_f32 v35, v35, v39
	s_nop 0
	v_cndmask_b32_e32 v35, 0, v35, vcc
	v_cmp_nlt_f32_e32 vcc, s2, v34
	s_nop 1
	v_cndmask_b32_e32 v39, v190, v35, vcc
	v_pk_mul_f32 v[34:35], v[38:39], v[28:29]
	v_or_b32_e32 v28, 4, v2
	v_cvt_f32_i32_e32 v28, v28
	v_pk_mul_f32 v[38:39], v[38:39], v[30:31]
	ds_write_b128 v1, v[32:35] offset:34816
	ds_write_b128 v1, v[36:39] offset:51200
	v_mul_f32_e32 v28, 0xb9800801, v28
	v_mul_f32_e64 v28, |v3|, v28
	v_mul_f32_e32 v29, 0x3fb8aa3b, v28
	v_fma_f32 v30, v28, s0, -v29
	v_rndne_f32_e32 v31, v29
	v_fmac_f32_e32 v30, 0x32a5705f, v28
	v_sub_f32_e32 v29, v29, v31
	v_add_f32_e32 v29, v29, v30
	v_exp_f32_e32 v29, v29
	v_cvt_i32_f32_e32 v30, v31
	v_cmp_ngt_f32_e32 vcc, s1, v28
	v_ldexp_f32 v29, v29, v30
	s_nop 0
	v_cndmask_b32_e32 v29, 0, v29, vcc
	v_cmp_nlt_f32_e32 vcc, s2, v28
	s_nop 1
	v_cndmask_b32_e32 v28, v190, v29, vcc
	v_or_b32_e32 v29, 5, v2
	v_cvt_f32_i32_e32 v29, v29
	v_mul_f32_e32 v29, 0xb9800801, v29
	v_mul_f32_e64 v29, |v3|, v29
	v_mul_f32_e32 v30, 0x3fb8aa3b, v29
	v_fma_f32 v31, v29, s0, -v30
	v_rndne_f32_e32 v32, v30
	v_fmac_f32_e32 v31, 0x32a5705f, v29
	v_sub_f32_e32 v30, v30, v32
	v_add_f32_e32 v30, v30, v31
	v_exp_f32_e32 v30, v30
	v_cvt_i32_f32_e32 v31, v32
	v_cmp_ngt_f32_e32 vcc, s1, v29
	v_ldexp_f32 v30, v30, v31
	s_nop 0
	v_cndmask_b32_e32 v30, 0, v30, vcc
	v_cmp_nlt_f32_e32 vcc, s2, v29
	s_nop 1
	v_cndmask_b32_e32 v29, v190, v30, vcc
	v_pk_mul_f32 v[24:25], v[28:29], v[24:25]
	v_pk_mul_f32 v[28:29], v[28:29], v[26:27]
	v_or_b32_e32 v26, 6, v2
	v_cvt_f32_i32_e32 v26, v26
	v_mul_f32_e32 v26, 0xb9800801, v26
	v_mul_f32_e64 v26, |v3|, v26
	v_mul_f32_e32 v27, 0x3fb8aa3b, v26
	v_fma_f32 v30, v26, s0, -v27
	v_rndne_f32_e32 v31, v27
	v_fmac_f32_e32 v30, 0x32a5705f, v26
	v_sub_f32_e32 v27, v27, v31
	v_add_f32_e32 v27, v27, v30
	v_exp_f32_e32 v27, v27
	v_cvt_i32_f32_e32 v30, v31
	v_cmp_ngt_f32_e32 vcc, s1, v26
	v_ldexp_f32 v27, v27, v30
	s_nop 0
	v_cndmask_b32_e32 v27, 0, v27, vcc
	v_cmp_nlt_f32_e32 vcc, s2, v26
	v_or_b32_e32 v26, 7, v2
	v_cvt_f32_i32_e32 v26, v26
	v_cndmask_b32_e32 v30, v190, v27, vcc
	v_mul_f32_e32 v26, 0xb9800801, v26
	v_mul_f32_e64 v26, |v3|, v26
	v_mul_f32_e32 v27, 0x3fb8aa3b, v26
	v_fma_f32 v31, v26, s0, -v27
	v_rndne_f32_e32 v32, v27
	v_fmac_f32_e32 v31, 0x32a5705f, v26
	v_sub_f32_e32 v27, v27, v32
	v_add_f32_e32 v27, v27, v31
	v_exp_f32_e32 v27, v27
	v_cvt_i32_f32_e32 v31, v32
	v_cmp_ngt_f32_e32 vcc, s1, v26
	v_ldexp_f32 v27, v27, v31
	s_nop 0
	v_cndmask_b32_e32 v27, 0, v27, vcc
	v_cmp_nlt_f32_e32 vcc, s2, v26
	s_nop 1
	v_cndmask_b32_e32 v31, v190, v27, vcc
	v_pk_mul_f32 v[26:27], v[30:31], v[20:21]
	v_or_b32_e32 v20, 8, v2
	v_cvt_f32_i32_e32 v20, v20
	v_pk_mul_f32 v[30:31], v[30:31], v[22:23]
	ds_write_b128 v1, v[24:27] offset:34832
	ds_write_b128 v1, v[28:31] offset:51216
	v_mul_f32_e32 v20, 0xb9800801, v20
	v_mul_f32_e64 v20, |v3|, v20
	v_mul_f32_e32 v21, 0x3fb8aa3b, v20
	v_fma_f32 v22, v20, s0, -v21
	v_rndne_f32_e32 v23, v21
	v_fmac_f32_e32 v22, 0x32a5705f, v20
	v_sub_f32_e32 v21, v21, v23
	v_add_f32_e32 v21, v21, v22
	v_exp_f32_e32 v21, v21
	v_cvt_i32_f32_e32 v22, v23
	v_cmp_ngt_f32_e32 vcc, s1, v20
	v_ldexp_f32 v21, v21, v22
	s_nop 0
	v_cndmask_b32_e32 v21, 0, v21, vcc
	v_cmp_nlt_f32_e32 vcc, s2, v20
	s_nop 1
	v_cndmask_b32_e32 v20, v190, v21, vcc
	v_or_b32_e32 v21, 9, v2
	v_cvt_f32_i32_e32 v21, v21
	v_mul_f32_e32 v21, 0xb9800801, v21
	v_mul_f32_e64 v21, |v3|, v21
	v_mul_f32_e32 v22, 0x3fb8aa3b, v21
	v_fma_f32 v23, v21, s0, -v22
	v_rndne_f32_e32 v24, v22
	v_fmac_f32_e32 v23, 0x32a5705f, v21
	v_sub_f32_e32 v22, v22, v24
	v_add_f32_e32 v22, v22, v23
	v_exp_f32_e32 v22, v22
	v_cvt_i32_f32_e32 v23, v24
	v_cmp_ngt_f32_e32 vcc, s1, v21
	v_ldexp_f32 v22, v22, v23
	s_nop 0
	v_cndmask_b32_e32 v22, 0, v22, vcc
	v_cmp_nlt_f32_e32 vcc, s2, v21
	s_nop 1
	v_cndmask_b32_e32 v21, v190, v22, vcc
	v_pk_mul_f32 v[16:17], v[20:21], v[16:17]
	v_pk_mul_f32 v[20:21], v[20:21], v[18:19]
	v_or_b32_e32 v18, 10, v2
	v_cvt_f32_i32_e32 v18, v18
	v_mul_f32_e32 v18, 0xb9800801, v18
	v_mul_f32_e64 v18, |v3|, v18
	v_mul_f32_e32 v19, 0x3fb8aa3b, v18
	v_fma_f32 v22, v18, s0, -v19
	v_rndne_f32_e32 v23, v19
	v_fmac_f32_e32 v22, 0x32a5705f, v18
	v_sub_f32_e32 v19, v19, v23
	v_add_f32_e32 v19, v19, v22
	v_exp_f32_e32 v19, v19
	v_cvt_i32_f32_e32 v22, v23
	v_cmp_ngt_f32_e32 vcc, s1, v18
	v_ldexp_f32 v19, v19, v22
	s_nop 0
	v_cndmask_b32_e32 v19, 0, v19, vcc
	v_cmp_nlt_f32_e32 vcc, s2, v18
	v_or_b32_e32 v18, 11, v2
	v_cvt_f32_i32_e32 v18, v18
	v_cndmask_b32_e32 v22, v190, v19, vcc
	v_mul_f32_e32 v18, 0xb9800801, v18
	v_mul_f32_e64 v18, |v3|, v18
	v_mul_f32_e32 v19, 0x3fb8aa3b, v18
	v_fma_f32 v23, v18, s0, -v19
	v_rndne_f32_e32 v24, v19
	v_fmac_f32_e32 v23, 0x32a5705f, v18
	v_sub_f32_e32 v19, v19, v24
	v_add_f32_e32 v19, v19, v23
	v_exp_f32_e32 v19, v19
	v_cvt_i32_f32_e32 v23, v24
	v_cmp_ngt_f32_e32 vcc, s1, v18
	v_ldexp_f32 v19, v19, v23
	s_nop 0
	v_cndmask_b32_e32 v19, 0, v19, vcc
	v_cmp_nlt_f32_e32 vcc, s2, v18
	s_nop 1
	v_cndmask_b32_e32 v23, v190, v19, vcc
	v_pk_mul_f32 v[18:19], v[22:23], v[12:13]
	v_or_b32_e32 v12, 12, v2
	v_cvt_f32_i32_e32 v12, v12
	v_pk_mul_f32 v[22:23], v[22:23], v[14:15]
	ds_write_b128 v1, v[16:19] offset:34848
	ds_write_b128 v1, v[20:23] offset:51232
	v_mul_f32_e32 v12, 0xb9800801, v12
	v_mul_f32_e64 v12, |v3|, v12
	v_mul_f32_e32 v13, 0x3fb8aa3b, v12
	v_fma_f32 v14, v12, s0, -v13
	v_rndne_f32_e32 v15, v13
	v_fmac_f32_e32 v14, 0x32a5705f, v12
	v_sub_f32_e32 v13, v13, v15
	v_add_f32_e32 v13, v13, v14
	v_exp_f32_e32 v13, v13
	v_cvt_i32_f32_e32 v14, v15
	v_cmp_ngt_f32_e32 vcc, s1, v12
	v_mov_b32_e32 v18, 0
	v_ldexp_f32 v13, v13, v14
	v_cndmask_b32_e32 v13, 0, v13, vcc
	v_cmp_nlt_f32_e32 vcc, s2, v12
	s_nop 1
	v_cndmask_b32_e32 v12, v190, v13, vcc
	v_or_b32_e32 v13, 13, v2
	v_cvt_f32_i32_e32 v13, v13
	v_mul_f32_e32 v13, 0xb9800801, v13
	v_mul_f32_e64 v13, |v3|, v13
	v_mul_f32_e32 v14, 0x3fb8aa3b, v13
	v_fma_f32 v15, v13, s0, -v14
	v_rndne_f32_e32 v16, v14
	v_fmac_f32_e32 v15, 0x32a5705f, v13
	v_sub_f32_e32 v14, v14, v16
	v_add_f32_e32 v14, v14, v15
	v_exp_f32_e32 v14, v14
	v_cvt_i32_f32_e32 v15, v16
	v_cmp_ngt_f32_e32 vcc, s1, v13
	v_ldexp_f32 v14, v14, v15
	s_nop 0
	v_cndmask_b32_e32 v14, 0, v14, vcc
	v_cmp_nlt_f32_e32 vcc, s2, v13
	s_nop 1
	v_cndmask_b32_e32 v13, v190, v14, vcc
	v_pk_mul_f32 v[8:9], v[12:13], v[8:9]
	v_pk_mul_f32 v[12:13], v[12:13], v[10:11]
	v_or_b32_e32 v10, 14, v2
	v_cvt_f32_i32_e32 v10, v10
	v_or_b32_e32 v2, 15, v2
	v_cvt_f32_i32_e32 v2, v2
	v_mul_f32_e32 v10, 0xb9800801, v10
	v_mul_f32_e64 v10, |v3|, v10
	v_mul_f32_e32 v11, 0x3fb8aa3b, v10
	v_fma_f32 v14, v10, s0, -v11
	v_rndne_f32_e32 v15, v11
	v_fmac_f32_e32 v14, 0x32a5705f, v10
	v_sub_f32_e32 v11, v11, v15
	v_add_f32_e32 v11, v11, v14
	v_exp_f32_e32 v11, v11
	v_cvt_i32_f32_e32 v14, v15
	v_mul_f32_e32 v2, 0xb9800801, v2
	v_cmp_ngt_f32_e32 vcc, s1, v10
	v_mul_f32_e64 v2, |v3|, v2
	v_ldexp_f32 v11, v11, v14
	v_cndmask_b32_e32 v11, 0, v11, vcc
	v_cmp_nlt_f32_e32 vcc, s2, v10
	v_mul_f32_e32 v3, 0x3fb8aa3b, v2
	v_fma_f32 v10, v2, s0, -v3
	v_cndmask_b32_e32 v14, v190, v11, vcc
	v_rndne_f32_e32 v11, v3
	v_fmac_f32_e32 v10, 0x32a5705f, v2
	v_sub_f32_e32 v3, v3, v11
	v_add_f32_e32 v3, v3, v10
	v_exp_f32_e32 v3, v3
	v_cvt_i32_f32_e32 v10, v11
	v_cmp_ngt_f32_e32 vcc, s1, v2
	v_ldexp_f32 v3, v3, v10
	s_nop 0
	v_cndmask_b32_e32 v3, 0, v3, vcc
	v_cmp_nlt_f32_e32 vcc, s2, v2
	s_nop 1
	v_cndmask_b32_e32 v15, v190, v3, vcc
	v_pk_mul_f32 v[10:11], v[14:15], v[4:5]
	v_pk_mul_f32 v[14:15], v[14:15], v[6:7]
	ds_write_b128 v1, v[8:11] offset:34864
	ds_write_b128 v1, v[12:15] offset:51248
	v_lshl_add_u32 v1, v0, 2, s33
	s_waitcnt lgkmcnt(0)
	s_barrier
	ds_read_b32 v10, v1 offset:34816
	v_cmp_ne_u32_e32 vcc, 0, v0
	v_mov_b32_e32 v4, 0
	s_and_saveexec_b64 s[0:1], vcc
	s_cbranch_execz .LBB0_763
	v_sub_u32_e32 v2, 0x1000, v0
	v_readlane_b32 s2, v254, 32
	s_nop 1
	v_lshl_add_u32 v2, v2, 2, s2
	ds_read_b32 v18, v2

.Lat_item:
	s_and_b32 s0, s34, 7
	s_ashr_i32 s12, s34, 7
	s_lshl_b32 s13, s34, 5
	s_and_b32 s13, s13, 0xf00
	s_lshl_b32 s1, s12, 12
	s_or_b32 s13, s13, s1
	s_lshl_b32 s1, s12, 3
	s_or_b32 s1, s1, s0
	s_mul_i32 s1, s1, 0x110000
	s_add_u32 s36, s22, s1
	s_addc_u32 s37, s23, 0
	s_add_u32 s42, s26, s1
	s_addc_u32 s43, s27, 0
	s_mul_i32 s1, s12, 0x88000
	s_add_u32 s38, s24, s1
	s_addc_u32 s39, s25, 0
	v_and_b32_e32 v253, 15, v167
	v_bfe_u32 v199, v167, 4, 2
	v_lshrrev_b32_e32 v200, 4, v167
	v_lshrrev_b32_e32 v201, 3, v167
	v_and_b32_e32 v252, 7, v167
	v_lshlrev_b32_e32 v172, 8, v200
	v_lshl_add_u32 v172, v253, 4, v172
	v_add_u32_e32 v173, 0x2000, v172
	v_lshlrev_b32_e32 v174, 7, v201
	v_lshl_add_u32 v174, v252, 4, v174
	v_mul_u32_u24_e32 v175, 0x2200, v201
	v_lshl_add_u32 v175, v252, 4, v175
	v_add_u32_e32 v176, 0x88000, v175
	global_load_dwordx4 v[112:115], v172, s[36:37]
	global_load_dwordx4 v[116:119], v173, s[36:37]
	global_load_dwordx4 v[120:123], v174, s[38:39]
	global_load_dwordx4 v[124:127], v175, s[42:43]
	global_load_dwordx4 v[128:131], v176, s[42:43]
	s_mul_i32 s1, s13, 0xc00
	s_mul_i32 s0, s0, 0x180
	s_add_u32 s1, s1, s0
	s_add_u32 s0, s20, s1
	s_addc_u32 s1, s21, 0
	v_lshrrev_b32_e32 v193, 6, v167
	v_lshl_add_u32 v193, v193, 5, v253
	v_mul_u32_u24_e32 v193, 0xc00, v193
	v_lshl_add_u32 v193, v199, 4, v193
	v_add_u32_e32 v194, 0xc000, v193
	global_load_dwordx4 v[64:67], v193, s[0:1]
	global_load_dwordx4 v[68:71], v193, s[0:1] offset:64
	global_load_dwordx4 v[72:75], v193, s[0:1] offset:128
	global_load_dwordx4 v[76:79], v193, s[0:1] offset:192
	global_load_dwordx4 v[80:83], v193, s[0:1] offset:256
	global_load_dwordx4 v[84:87], v193, s[0:1] offset:320
	global_load_dwordx4 v[88:91], v194, s[0:1]
	global_load_dwordx4 v[92:95], v194, s[0:1] offset:64
	global_load_dwordx4 v[96:99], v194, s[0:1] offset:128
	global_load_dwordx4 v[100:103], v194, s[0:1] offset:192
	global_load_dwordx4 v[104:107], v194, s[0:1] offset:256
	global_load_dwordx4 v[108:111], v194, s[0:1] offset:320
	v_mul_u32_u24_e32 v164, 416, v253
	v_lshl_add_u32 v164, v199, 4, v164
	v_mul_u32_u24_e32 v168, 160, v253
	v_lshl_add_u32 v168, v199, 4, v168
	v_mul_u32_u24_e32 v169, 416, v200
	v_lshl_add_u32 v169, v253, 4, v169
	v_mul_u32_u24_e32 v170, 416, v201
	v_lshl_add_u32 v170, v252, 4, v170
	v_add_u32_e32 v170, 0x100, v170
	v_mul_u32_u24_e32 v171, 160, v201
	v_lshrrev_b32_e32 v200, 2, v252
	v_lshl_add_u32 v171, v200, 6, v171
	v_and_b32_e32 v200, 1, v252
	v_lshl_add_u32 v171, v200, 5, v171
	v_bfe_u32 v200, v252, 1, 1
	v_lshl_add_u32 v171, v200, 3, v171
	v_mov_b32_e32 v0, 0
	v_mov_b32_e32 v1, 0
	v_mov_b32_e32 v2, 0
	v_mov_b32_e32 v3, 0
	v_mov_b32_e32 v4, 0
	v_mov_b32_e32 v5, 0
	v_mov_b32_e32 v6, 0
	v_mov_b32_e32 v7, 0
	v_mov_b32_e32 v8, 0
	v_mov_b32_e32 v9, 0
	v_mov_b32_e32 v10, 0
	v_mov_b32_e32 v11, 0
	v_mov_b32_e32 v12, 0
	v_mov_b32_e32 v13, 0
	v_mov_b32_e32 v14, 0
	v_mov_b32_e32 v15, 0
	v_mov_b32_e32 v16, 0
	v_mov_b32_e32 v17, 0
	v_mov_b32_e32 v18, 0
	v_mov_b32_e32 v19, 0
	v_mov_b32_e32 v20, 0
	v_mov_b32_e32 v21, 0
	v_mov_b32_e32 v22, 0
	v_mov_b32_e32 v23, 0
	v_mov_b32_e32 v24, 0
	v_mov_b32_e32 v25, 0
	v_mov_b32_e32 v26, 0
	v_mov_b32_e32 v27, 0
	v_mov_b32_e32 v28, 0
	v_mov_b32_e32 v29, 0
	v_mov_b32_e32 v30, 0
	v_mov_b32_e32 v31, 0
	v_mov_b32_e32 v32, 0
	v_mov_b32_e32 v33, 0
	v_mov_b32_e32 v34, 0
	v_mov_b32_e32 v35, 0
	v_mov_b32_e32 v36, 0
	v_mov_b32_e32 v37, 0
	v_mov_b32_e32 v38, 0
	v_mov_b32_e32 v39, 0
	v_mov_b32_e32 v40, 0
	v_mov_b32_e32 v41, 0
	v_mov_b32_e32 v42, 0
	v_mov_b32_e32 v43, 0
	v_mov_b32_e32 v44, 0
	v_mov_b32_e32 v45, 0
	v_mov_b32_e32 v46, 0
	v_mov_b32_e32 v47, 0
	v_mov_b32_e32 v48, 0
	v_mov_b32_e32 v49, 0
	v_mov_b32_e32 v50, 0
	v_mov_b32_e32 v51, 0
	v_mov_b32_e32 v52, 0
	v_mov_b32_e32 v53, 0
	v_mov_b32_e32 v54, 0
	v_mov_b32_e32 v55, 0
	v_mov_b32_e32 v56, 0
	v_mov_b32_e32 v57, 0
	v_mov_b32_e32 v58, 0
	v_mov_b32_e32 v59, 0
	v_mov_b32_e32 v60, 0
	v_mov_b32_e32 v61, 0
	v_mov_b32_e32 v62, 0
	v_mov_b32_e32 v63, 0
	v_mov_b32_e32 v177, 0xf149f2ca
	v_mov_b32_e32 v178, 0xf149f2ca
	v_mov_b32_e32 v179, 0
	v_mov_b32_e32 v180, 0
	s_mov_b32 s35, 0
	s_mov_b32 s44, 0
	s_mov_b32 s0, 94208
	s_mov_b32 s1, 53248
	s_mov_b32 s13, 73728
	s_waitcnt vmcnt(12)
	ds_write_b128 v169, v[112:115]
	ds_write_b128 v169, v[116:119] offset:13312
	ds_write_b128 v170, v[120:123]
	v_add_u32_e32 v197, 53248, v171
	v_add_u32_e32 v198, 10240, v197
	ds_write2_b64 v197, v[124:125], v[126:127] offset1:2
	ds_write2_b64 v198, v[128:129], v[130:131] offset1:2
	v_readfirstlane_b32 s12, v167
	s_waitcnt vmcnt(0) lgkmcnt(0)
	s_barrier
	s_cmpk_lt_u32 s12, 256
	s_cbranch_scc0 .Lat_B_entry

.Lat_noload_A:
	v_add_u32_e32 v193, s44, v164
	v_add_u32_e32 v194, s1, v168
	s_setprio 1
	ds_read_b128 v[204:207], v193
	ds_read_b128 v[208:211], v193 offset:6656
	ds_read_b128 v[212:215], v193 offset:13312
	ds_read_b128 v[216:219], v193 offset:19968
	ds_read_b128 v[220:223], v193 offset:64
	ds_read_b128 v[224:227], v193 offset:6720
	ds_read_b128 v[228:231], v193 offset:13376
	ds_read_b128 v[232:235], v193 offset:20032
	s_waitcnt lgkmcnt(7)
	v_mfma_f32_16x16x32_bf16 v[132:135], v[204:207], v[64:67], 0
	v_mfma_f32_16x16x32_bf16 v[136:139], v[204:207], v[88:91], 0
	ds_read_b128 v[204:207], v193 offset:128
	s_waitcnt lgkmcnt(7)
	v_mfma_f32_16x16x32_bf16 v[140:143], v[208:211], v[64:67], 0
	v_mfma_f32_16x16x32_bf16 v[144:147], v[208:211], v[88:91], 0
	ds_read_b128 v[208:211], v193 offset:6784
	s_waitcnt lgkmcnt(7)
	v_mfma_f32_16x16x32_bf16 v[148:151], v[212:215], v[64:67], 0
	v_mfma_f32_16x16x32_bf16 v[152:155], v[212:215], v[88:91], 0
	ds_read_b128 v[212:215], v193 offset:13440
	s_waitcnt lgkmcnt(7)
	v_mfma_f32_16x16x32_bf16 v[156:159], v[216:219], v[64:67], 0
	v_mfma_f32_16x16x32_bf16 v[160:163], v[216:219], v[88:91], 0
	ds_read_b128 v[216:219], v193 offset:20096
	s_waitcnt lgkmcnt(7)
	v_mfma_f32_16x16x32_bf16 v[132:135], v[220:223], v[68:71], v[132:135]
	v_mfma_f32_16x16x32_bf16 v[136:139], v[220:223], v[92:95], v[136:139]
	ds_read_b128 v[220:223], v193 offset:192
	s_waitcnt lgkmcnt(7)
	v_mfma_f32_16x16x32_bf16 v[140:143], v[224:227], v[68:71], v[140:143]
	v_mfma_f32_16x16x32_bf16 v[144:147], v[224:227], v[92:95], v[144:147]
	ds_read_b128 v[224:227], v193 offset:6848
	s_waitcnt lgkmcnt(7)
	v_mfma_f32_16x16x32_bf16 v[148:151], v[228:231], v[68:71], v[148:151]
	v_mfma_f32_16x16x32_bf16 v[152:155], v[228:231], v[92:95], v[152:155]
	ds_read_b128 v[228:231], v193 offset:13504
	s_waitcnt lgkmcnt(7)
	v_mfma_f32_16x16x32_bf16 v[156:159], v[232:235], v[68:71], v[156:159]
	v_mfma_f32_16x16x32_bf16 v[160:163], v[232:235], v[92:95], v[160:163]
	ds_read_b128 v[232:235], v193 offset:20160
	s_waitcnt lgkmcnt(7)
	v_mfma_f32_16x16x32_bf16 v[132:135], v[204:207], v[72:75], v[132:135]
	v_mfma_f32_16x16x32_bf16 v[136:139], v[204:207], v[96:99], v[136:139]
	ds_read_b128 v[204:207], v193 offset:256
	s_waitcnt lgkmcnt(7)
	v_mfma_f32_16x16x32_bf16 v[140:143], v[208:211], v[72:75], v[140:143]
	v_mfma_f32_16x16x32_bf16 v[144:147], v[208:211], v[96:99], v[144:147]
	ds_read_b128 v[208:211], v193 offset:6912
	s_waitcnt lgkmcnt(7)
	v_mfma_f32_16x16x32_bf16 v[148:151], v[212:215], v[72:75], v[148:151]
	v_mfma_f32_16x16x32_bf16 v[152:155], v[212:215], v[96:99], v[152:155]
	ds_read_b128 v[212:215], v193 offset:13568
	s_waitcnt lgkmcnt(7)
	v_mfma_f32_16x16x32_bf16 v[156:159], v[216:219], v[72:75], v[156:159]
	v_mfma_f32_16x16x32_bf16 v[160:163], v[216:219], v[96:99], v[160:163]
	ds_read_b128 v[216:219], v193 offset:20224
	s_waitcnt lgkmcnt(7)
	v_mfma_f32_16x16x32_bf16 v[132:135], v[220:223], v[76:79], v[132:135]
	v_mfma_f32_16x16x32_bf16 v[136:139], v[220:223], v[100:103], v[136:139]
	ds_read_b128 v[220:223], v193 offset:320
	s_waitcnt lgkmcnt(7)
	v_mfma_f32_16x16x32_bf16 v[140:143], v[224:227], v[76:79], v[140:143]
	v_mfma_f32_16x16x32_bf16 v[144:147], v[224:227], v[100:103], v[144:147]
	ds_read_b128 v[224:227], v193 offset:6976
	s_waitcnt lgkmcnt(7)
	v_mfma_f32_16x16x32_bf16 v[148:151], v[228:231], v[76:79], v[148:151]
	v_mfma_f32_16x16x32_bf16 v[152:155], v[228:231], v[100:103], v[152:155]
	ds_read_b128 v[228:231], v193 offset:13632
	s_waitcnt lgkmcnt(7)
	v_mfma_f32_16x16x32_bf16 v[156:159], v[232:235], v[76:79], v[156:159]
	v_mfma_f32_16x16x32_bf16 v[160:163], v[232:235], v[100:103], v[160:163]
	ds_read_b128 v[232:235], v193 offset:20288
	s_waitcnt lgkmcnt(7)
	v_mfma_f32_16x16x32_bf16 v[132:135], v[204:207], v[80:83], v[132:135]
	v_mfma_f32_16x16x32_bf16 v[136:139], v[204:207], v[104:107], v[136:139]
	ds_read_b128 v[204:207], v194
	s_waitcnt lgkmcnt(7)
	v_mfma_f32_16x16x32_bf16 v[140:143], v[208:211], v[80:83], v[140:143]
	v_mfma_f32_16x16x32_bf16 v[144:147], v[208:211], v[104:107], v[144:147]
	ds_read_b128 v[208:211], v194 offset:64
	s_waitcnt lgkmcnt(7)
	v_mfma_f32_16x16x32_bf16 v[148:151], v[212:215], v[80:83], v[148:151]
	v_mfma_f32_16x16x32_bf16 v[152:155], v[212:215], v[104:107], v[152:155]
	ds_read_b128 v[212:215], v194 offset:2560
	s_waitcnt lgkmcnt(7)
	v_mfma_f32_16x16x32_bf16 v[156:159], v[216:219], v[80:83], v[156:159]
	v_mfma_f32_16x16x32_bf16 v[160:163], v[216:219], v[104:107], v[160:163]
	ds_read_b128 v[216:219], v194 offset:2624
	s_waitcnt lgkmcnt(7)
	v_mfma_f32_16x16x32_bf16 v[132:135], v[220:223], v[84:87], v[132:135]
	v_mfma_f32_16x16x32_bf16 v[136:139], v[220:223], v[108:111], v[136:139]
	ds_read_b128 v[220:223], v194 offset:5120
	s_waitcnt lgkmcnt(7)
	v_mfma_f32_16x16x32_bf16 v[140:143], v[224:227], v[84:87], v[140:143]
	v_mfma_f32_16x16x32_bf16 v[144:147], v[224:227], v[108:111], v[144:147]
	ds_read_b128 v[224:227], v194 offset:5184
	s_waitcnt lgkmcnt(7)
	v_mfma_f32_16x16x32_bf16 v[148:151], v[228:231], v[84:87], v[148:151]
	v_mfma_f32_16x16x32_bf16 v[152:155], v[228:231], v[108:111], v[152:155]
	ds_read_b128 v[228:231], v194 offset:7680
	s_waitcnt lgkmcnt(7)
	v_mfma_f32_16x16x32_bf16 v[156:159], v[232:235], v[84:87], v[156:159]
	v_mfma_f32_16x16x32_bf16 v[160:163], v[232:235], v[108:111], v[160:163]
	ds_read_b128 v[232:235], v194 offset:7744
	s_setprio 0
	s_nop 6
	v_max3_f32 v199, v132, v133, v134
	v_max3_f32 v200, v136, v137, v138
	v_max3_f32 v199, v199, v135, v140
	v_max3_f32 v200, v200, v139, v144
	v_max3_f32 v199, v199, v141, v142
	v_max3_f32 v200, v200, v145, v146
	v_max3_f32 v199, v199, v143, v148
	v_max3_f32 v200, v200, v147, v152
	v_max3_f32 v199, v199, v149, v150
	v_max3_f32 v200, v200, v153, v154
	v_max3_f32 v199, v199, v151, v156
	v_max3_f32 v200, v200, v155, v160
	v_max3_f32 v199, v199, v157, v158
	v_max3_f32 v200, v200, v161, v162
	v_max_f32_e32 v199, v199, v159
	v_max_f32_e32 v200, v200, v163
	v_mov_b32_e32 v253, v199
	v_mov_b32_e32 v201, v200
	s_nop 1
	v_permlane16_swap_b32_e32 v199, v253
	v_permlane16_swap_b32_e32 v200, v201
	s_nop 0
	v_max_f32_e32 v199, v199, v253
	v_max_f32_e32 v200, v200, v201
	v_mov_b32_e32 v253, v199
	v_mov_b32_e32 v201, v200
	s_nop 1
	v_permlane32_swap_b32_e32 v199, v253
	v_permlane32_swap_b32_e32 v200, v201
	s_nop 0
	v_max_f32_e32 v199, v199, v253
	v_max_f32_e32 v200, v200, v201
	v_max_f32_e32 v199, v177, v199
	v_max_f32_e32 v200, v178, v200
	v_sub_f32_e32 v182, v177, v199
	v_sub_f32_e32 v202, v178, v200
	v_exp_f32_e32 v182, v182
	v_exp_f32_e32 v202, v202
	v_mov_b32_e32 v177, v199
	v_mov_b32_e32 v178, v200
	v_sub_f32_e32 v132, v132, v177
	v_sub_f32_e32 v136, v136, v178
	v_sub_f32_e32 v133, v133, v177
	v_sub_f32_e32 v137, v137, v178
	v_sub_f32_e32 v134, v134, v177
	v_sub_f32_e32 v138, v138, v178
	v_sub_f32_e32 v135, v135, v177
	v_sub_f32_e32 v139, v139, v178
	v_sub_f32_e32 v140, v140, v177
	v_sub_f32_e32 v144, v144, v178
	v_sub_f32_e32 v141, v141, v177
	v_sub_f32_e32 v145, v145, v178
	v_sub_f32_e32 v142, v142, v177
	v_sub_f32_e32 v146, v146, v178
	v_sub_f32_e32 v143, v143, v177
	v_sub_f32_e32 v147, v147, v178
	v_sub_f32_e32 v148, v148, v177
	v_sub_f32_e32 v152, v152, v178
	v_sub_f32_e32 v149, v149, v177
	v_sub_f32_e32 v153, v153, v178
	v_sub_f32_e32 v150, v150, v177
	v_sub_f32_e32 v154, v154, v178
	v_sub_f32_e32 v151, v151, v177
	v_sub_f32_e32 v155, v155, v178
	v_sub_f32_e32 v156, v156, v177
	v_sub_f32_e32 v160, v160, v178
	v_sub_f32_e32 v157, v157, v177
	v_sub_f32_e32 v161, v161, v178
	v_sub_f32_e32 v158, v158, v177
	v_sub_f32_e32 v162, v162, v178
	v_sub_f32_e32 v159, v159, v177
	v_sub_f32_e32 v163, v163, v178
	v_exp_f32_e32 v132, v132
	v_exp_f32_e32 v136, v136
	v_exp_f32_e32 v133, v133
	v_exp_f32_e32 v137, v137
	v_exp_f32_e32 v134, v134
	v_exp_f32_e32 v138, v138
	v_exp_f32_e32 v135, v135
	v_exp_f32_e32 v139, v139
	v_exp_f32_e32 v140, v140
	v_exp_f32_e32 v144, v144
	v_exp_f32_e32 v141, v141
	v_exp_f32_e32 v145, v145
	v_exp_f32_e32 v142, v142
	v_exp_f32_e32 v146, v146
	v_exp_f32_e32 v143, v143
	v_exp_f32_e32 v147, v147
	v_exp_f32_e32 v148, v148
	v_exp_f32_e32 v152, v152
	v_exp_f32_e32 v149, v149
	v_exp_f32_e32 v153, v153
	v_exp_f32_e32 v150, v150
	v_exp_f32_e32 v154, v154
	v_exp_f32_e32 v151, v151
	v_exp_f32_e32 v155, v155
	v_exp_f32_e32 v156, v156
	v_exp_f32_e32 v160, v160
	v_exp_f32_e32 v157, v157
	v_exp_f32_e32 v161, v161
	v_exp_f32_e32 v158, v158
	v_exp_f32_e32 v162, v162
	v_exp_f32_e32 v159, v159
	v_exp_f32_e32 v163, v163
	v_cmp_eq_f32_e32 vcc, 1.0, v182
	s_cmp_eq_u64 vcc, exec
	s_cbranch_scc1 .Lat_noscale0_A
	v_pk_mul_f32 v[0:1], v[0:1], v[182:183] op_sel_hi:[1,0]
	v_pk_mul_f32 v[2:3], v[2:3], v[182:183] op_sel_hi:[1,0]
	v_pk_mul_f32 v[8:9], v[8:9], v[182:183] op_sel_hi:[1,0]
	v_pk_mul_f32 v[10:11], v[10:11], v[182:183] op_sel_hi:[1,0]
	v_pk_mul_f32 v[16:17], v[16:17], v[182:183] op_sel_hi:[1,0]
	v_pk_mul_f32 v[18:19], v[18:19], v[182:183] op_sel_hi:[1,0]
	v_pk_mul_f32 v[24:25], v[24:25], v[182:183] op_sel_hi:[1,0]
	v_pk_mul_f32 v[26:27], v[26:27], v[182:183] op_sel_hi:[1,0]
	v_pk_mul_f32 v[32:33], v[32:33], v[182:183] op_sel_hi:[1,0]
	v_pk_mul_f32 v[34:35], v[34:35], v[182:183] op_sel_hi:[1,0]
	v_pk_mul_f32 v[40:41], v[40:41], v[182:183] op_sel_hi:[1,0]
	v_pk_mul_f32 v[42:43], v[42:43], v[182:183] op_sel_hi:[1,0]
	v_pk_mul_f32 v[48:49], v[48:49], v[182:183] op_sel_hi:[1,0]
	v_pk_mul_f32 v[50:51], v[50:51], v[182:183] op_sel_hi:[1,0]
	v_pk_mul_f32 v[56:57], v[56:57], v[182:183] op_sel_hi:[1,0]
	v_pk_mul_f32 v[58:59], v[58:59], v[182:183] op_sel_hi:[1,0]

.Lat_noscale1_A:
	v_add_f32_e32 v183, v132, v133
	v_add_f32_e32 v203, v136, v137
	v_add_f32_e32 v183, v183, v134
	v_add_f32_e32 v203, v203, v138
	v_add_f32_e32 v183, v183, v135
	v_add_f32_e32 v203, v203, v139
	v_add_f32_e32 v183, v183, v140
	v_add_f32_e32 v203, v203, v144
	v_add_f32_e32 v183, v183, v141
	v_add_f32_e32 v203, v203, v145
	v_add_f32_e32 v183, v183, v142
	v_add_f32_e32 v203, v203, v146
	v_add_f32_e32 v183, v183, v143
	v_add_f32_e32 v203, v203, v147
	v_add_f32_e32 v183, v183, v148
	v_add_f32_e32 v203, v203, v152
	v_add_f32_e32 v183, v183, v149
	v_add_f32_e32 v203, v203, v153
	v_add_f32_e32 v183, v183, v150
	v_add_f32_e32 v203, v203, v154
	v_add_f32_e32 v183, v183, v151
	v_add_f32_e32 v203, v203, v155
	v_add_f32_e32 v183, v183, v156
	v_add_f32_e32 v203, v203, v160
	v_add_f32_e32 v183, v183, v157
	v_add_f32_e32 v203, v203, v161
	v_add_f32_e32 v183, v183, v158
	v_add_f32_e32 v203, v203, v162
	v_add_f32_e32 v183, v183, v159
	v_add_f32_e32 v203, v203, v163
	v_fmac_f32_e32 v183, v179, v182
	v_fmac_f32_e32 v203, v180, v202
	v_mov_b32_e32 v179, v183
	v_mov_b32_e32 v180, v203
	v_cvt_pk_bf16_f32 v236, v132, v133
	v_cvt_pk_bf16_f32 v237, v134, v135
	v_cvt_pk_bf16_f32 v238, v140, v141
	v_cvt_pk_bf16_f32 v239, v142, v143
	v_cvt_pk_bf16_f32 v244, v136, v137
	v_cvt_pk_bf16_f32 v245, v138, v139
	v_cvt_pk_bf16_f32 v246, v144, v145
	v_cvt_pk_bf16_f32 v247, v146, v147
	v_cvt_pk_bf16_f32 v240, v148, v149
	v_cvt_pk_bf16_f32 v241, v150, v151
	v_cvt_pk_bf16_f32 v242, v156, v157
	v_cvt_pk_bf16_f32 v243, v158, v159
	v_cvt_pk_bf16_f32 v248, v152, v153
	v_cvt_pk_bf16_f32 v249, v154, v155
	v_cvt_pk_bf16_f32 v250, v160, v161
	v_cvt_pk_bf16_f32 v251, v162, v163
	s_setprio 1
	s_nop 0
	s_waitcnt lgkmcnt(7)
	v_mfma_f32_16x16x32_bf16 v[0:3], v[204:207], v[236:239], v[0:3]
	v_mfma_f32_16x16x32_bf16 v[4:7], v[204:207], v[244:247], v[4:7]
	ds_read_b128 v[204:207], v194 offset:10240
	s_waitcnt lgkmcnt(7)
	v_mfma_f32_16x16x32_bf16 v[0:3], v[208:211], v[240:243], v[0:3]
	v_mfma_f32_16x16x32_bf16 v[4:7], v[208:211], v[248:251], v[4:7]
	ds_read_b128 v[208:211], v194 offset:10304
	s_waitcnt lgkmcnt(7)
	v_mfma_f32_16x16x32_bf16 v[8:11], v[212:215], v[236:239], v[8:11]
	v_mfma_f32_16x16x32_bf16 v[12:15], v[212:215], v[244:247], v[12:15]
	ds_read_b128 v[212:215], v194 offset:12800
	s_waitcnt lgkmcnt(7)
	v_mfma_f32_16x16x32_bf16 v[8:11], v[216:219], v[240:243], v[8:11]
	v_mfma_f32_16x16x32_bf16 v[12:15], v[216:219], v[248:251], v[12:15]
	ds_read_b128 v[216:219], v194 offset:12864
	s_waitcnt lgkmcnt(7)
	v_mfma_f32_16x16x32_bf16 v[16:19], v[220:223], v[236:239], v[16:19]
	v_mfma_f32_16x16x32_bf16 v[20:23], v[220:223], v[244:247], v[20:23]
	ds_read_b128 v[220:223], v194 offset:15360
	s_waitcnt lgkmcnt(7)
	v_mfma_f32_16x16x32_bf16 v[16:19], v[224:227], v[240:243], v[16:19]
	v_mfma_f32_16x16x32_bf16 v[20:23], v[224:227], v[248:251], v[20:23]
	ds_read_b128 v[224:227], v194 offset:15424
	s_waitcnt lgkmcnt(7)
	v_mfma_f32_16x16x32_bf16 v[24:27], v[228:231], v[236:239], v[24:27]
	v_mfma_f32_16x16x32_bf16 v[28:31], v[228:231], v[244:247], v[28:31]
	ds_read_b128 v[228:231], v194 offset:17920
	s_waitcnt lgkmcnt(7)
	v_mfma_f32_16x16x32_bf16 v[24:27], v[232:235], v[240:243], v[24:27]
	v_mfma_f32_16x16x32_bf16 v[28:31], v[232:235], v[248:251], v[28:31]
	ds_read_b128 v[232:235], v194 offset:17984
	s_waitcnt lgkmcnt(7)
	v_mfma_f32_16x16x32_bf16 v[32:35], v[204:207], v[236:239], v[32:35]
	v_mfma_f32_16x16x32_bf16 v[36:39], v[204:207], v[244:247], v[36:39]
	s_waitcnt lgkmcnt(6)
	v_mfma_f32_16x16x32_bf16 v[32:35], v[208:211], v[240:243], v[32:35]
	v_mfma_f32_16x16x32_bf16 v[36:39], v[208:211], v[248:251], v[36:39]
	s_waitcnt lgkmcnt(5)
	v_mfma_f32_16x16x32_bf16 v[40:43], v[212:215], v[236:239], v[40:43]
	v_mfma_f32_16x16x32_bf16 v[44:47], v[212:215], v[244:247], v[44:47]
	s_waitcnt lgkmcnt(4)
	v_mfma_f32_16x16x32_bf16 v[40:43], v[216:219], v[240:243], v[40:43]
	v_mfma_f32_16x16x32_bf16 v[44:47], v[216:219], v[248:251], v[44:47]
	s_waitcnt lgkmcnt(3)
	v_mfma_f32_16x16x32_bf16 v[48:51], v[220:223], v[236:239], v[48:51]
	v_mfma_f32_16x16x32_bf16 v[52:55], v[220:223], v[244:247], v[52:55]
	s_waitcnt lgkmcnt(2)
	v_mfma_f32_16x16x32_bf16 v[48:51], v[224:227], v[240:243], v[48:51]
	v_mfma_f32_16x16x32_bf16 v[52:55], v[224:227], v[248:251], v[52:55]
	s_waitcnt lgkmcnt(1)
	v_mfma_f32_16x16x32_bf16 v[56:59], v[228:231], v[236:239], v[56:59]
	v_mfma_f32_16x16x32_bf16 v[60:63], v[228:231], v[244:247], v[60:63]
	s_waitcnt lgkmcnt(0)
	v_mfma_f32_16x16x32_bf16 v[56:59], v[232:235], v[240:243], v[56:59]
	v_mfma_f32_16x16x32_bf16 v[60:63], v[232:235], v[248:251], v[60:63]
	s_setprio 0
	s_cmpk_lt_u32 s35, 67
	s_cbranch_scc0 .Lat_nostage_A
	s_xor_b32 s12, s44, 26624
	v_add_u32_e32 v195, s12, v169
	v_add_u32_e32 v196, s12, v170
	v_add_u32_e32 v197, s13, v171
	v_add_u32_e32 v198, 10240, v197
	s_waitcnt vmcnt(0)
	ds_write_b128 v195, v[112:115]
	ds_write_b128 v195, v[116:119] offset:13312
	ds_write_b128 v196, v[120:123]
	ds_write2_b64 v197, v[124:125], v[126:127] offset1:2
	ds_write2_b64 v198, v[128:129], v[130:131] offset1:2
.Lat_nostage_A:
	s_xor_b32 s44, s44, 26624
	s_mov_b32 s12, s0
	s_mov_b32 s0, s1
	s_mov_b32 s1, s13
	s_mov_b32 s13, s12
	s_add_u32 s35, s35, 1
	s_waitcnt lgkmcnt(0)
	s_barrier
	s_cmpk_lt_u32 s35, 68
	s_cbranch_scc1 .Lat_A_loop
	s_branch .Lat_join

.Lat_noload_B0:
	v_add_u32_e32 v193, s44, v164
	v_add_u32_e32 v252, s1, v168
	s_setprio 1
	ds_read_b128 v[204:207], v193
	ds_read_b128 v[208:211], v193 offset:6656
	ds_read_b128 v[212:215], v193 offset:13312
	ds_read_b128 v[216:219], v193 offset:19968
	ds_read_b128 v[220:223], v193 offset:64
	ds_read_b128 v[224:227], v193 offset:6720
	ds_read_b128 v[228:231], v193 offset:13376
	ds_read_b128 v[232:235], v193 offset:20032
	s_waitcnt lgkmcnt(7)
	v_mfma_f32_16x16x32_bf16 v[132:135], v[204:207], v[64:67], 0
	v_mfma_f32_16x16x32_bf16 v[136:139], v[204:207], v[88:91], 0
	ds_read_b128 v[204:207], v193 offset:128
	s_waitcnt lgkmcnt(7)
	v_mfma_f32_16x16x32_bf16 v[140:143], v[208:211], v[64:67], 0
	v_mfma_f32_16x16x32_bf16 v[144:147], v[208:211], v[88:91], 0
	ds_read_b128 v[208:211], v193 offset:6784
	s_waitcnt lgkmcnt(7)
	v_mfma_f32_16x16x32_bf16 v[148:151], v[212:215], v[64:67], 0
	v_mfma_f32_16x16x32_bf16 v[152:155], v[212:215], v[88:91], 0
	ds_read_b128 v[212:215], v193 offset:13440
	s_waitcnt lgkmcnt(7)
	v_mfma_f32_16x16x32_bf16 v[156:159], v[216:219], v[64:67], 0
	v_mfma_f32_16x16x32_bf16 v[160:163], v[216:219], v[88:91], 0
	ds_read_b128 v[216:219], v193 offset:20096
	s_waitcnt lgkmcnt(7)
	v_mfma_f32_16x16x32_bf16 v[132:135], v[220:223], v[68:71], v[132:135]
	v_mfma_f32_16x16x32_bf16 v[136:139], v[220:223], v[92:95], v[136:139]
	ds_read_b128 v[220:223], v193 offset:192
	s_waitcnt lgkmcnt(7)
	v_mfma_f32_16x16x32_bf16 v[140:143], v[224:227], v[68:71], v[140:143]
	v_mfma_f32_16x16x32_bf16 v[144:147], v[224:227], v[92:95], v[144:147]
	ds_read_b128 v[224:227], v193 offset:6848
	s_waitcnt lgkmcnt(7)
	v_mfma_f32_16x16x32_bf16 v[148:151], v[228:231], v[68:71], v[148:151]
	v_mfma_f32_16x16x32_bf16 v[152:155], v[228:231], v[92:95], v[152:155]
	ds_read_b128 v[228:231], v193 offset:13504
	s_waitcnt lgkmcnt(7)
	v_mfma_f32_16x16x32_bf16 v[156:159], v[232:235], v[68:71], v[156:159]
	v_mfma_f32_16x16x32_bf16 v[160:163], v[232:235], v[92:95], v[160:163]
	ds_read_b128 v[232:235], v193 offset:20160
	s_waitcnt lgkmcnt(7)
	v_mfma_f32_16x16x32_bf16 v[132:135], v[204:207], v[72:75], v[132:135]
	v_mfma_f32_16x16x32_bf16 v[136:139], v[204:207], v[96:99], v[136:139]
	ds_read_b128 v[204:207], v193 offset:256
	s_waitcnt lgkmcnt(7)
	v_mfma_f32_16x16x32_bf16 v[140:143], v[208:211], v[72:75], v[140:143]
	v_mfma_f32_16x16x32_bf16 v[144:147], v[208:211], v[96:99], v[144:147]
	ds_read_b128 v[208:211], v193 offset:6912
	s_waitcnt lgkmcnt(7)
	v_mfma_f32_16x16x32_bf16 v[148:151], v[212:215], v[72:75], v[148:151]
	v_mfma_f32_16x16x32_bf16 v[152:155], v[212:215], v[96:99], v[152:155]
	ds_read_b128 v[212:215], v193 offset:13568
	s_waitcnt lgkmcnt(7)
	v_mfma_f32_16x16x32_bf16 v[156:159], v[216:219], v[72:75], v[156:159]
	v_mfma_f32_16x16x32_bf16 v[160:163], v[216:219], v[96:99], v[160:163]
	ds_read_b128 v[216:219], v193 offset:20224
	s_waitcnt lgkmcnt(7)
	v_mfma_f32_16x16x32_bf16 v[132:135], v[220:223], v[76:79], v[132:135]
	v_mfma_f32_16x16x32_bf16 v[136:139], v[220:223], v[100:103], v[136:139]
	ds_read_b128 v[220:223], v193 offset:320
	s_waitcnt lgkmcnt(7)
	v_mfma_f32_16x16x32_bf16 v[140:143], v[224:227], v[76:79], v[140:143]
	v_mfma_f32_16x16x32_bf16 v[144:147], v[224:227], v[100:103], v[144:147]
	ds_read_b128 v[224:227], v193 offset:6976
	s_waitcnt lgkmcnt(7)
	v_mfma_f32_16x16x32_bf16 v[148:151], v[228:231], v[76:79], v[148:151]
	v_mfma_f32_16x16x32_bf16 v[152:155], v[228:231], v[100:103], v[152:155]
	ds_read_b128 v[228:231], v193 offset:13632
	s_waitcnt lgkmcnt(7)
	v_mfma_f32_16x16x32_bf16 v[156:159], v[232:235], v[76:79], v[156:159]
	v_mfma_f32_16x16x32_bf16 v[160:163], v[232:235], v[100:103], v[160:163]
	ds_read_b128 v[232:235], v193 offset:20288
	s_waitcnt lgkmcnt(7)
	v_mfma_f32_16x16x32_bf16 v[132:135], v[204:207], v[80:83], v[132:135]
	v_mfma_f32_16x16x32_bf16 v[136:139], v[204:207], v[104:107], v[136:139]
	ds_read_b128 v[204:207], v252
	s_waitcnt lgkmcnt(7)
	v_mfma_f32_16x16x32_bf16 v[140:143], v[208:211], v[80:83], v[140:143]
	v_mfma_f32_16x16x32_bf16 v[144:147], v[208:211], v[104:107], v[144:147]
	ds_read_b128 v[208:211], v252 offset:64
	s_waitcnt lgkmcnt(7)
	v_mfma_f32_16x16x32_bf16 v[148:151], v[212:215], v[80:83], v[148:151]
	v_mfma_f32_16x16x32_bf16 v[152:155], v[212:215], v[104:107], v[152:155]
	ds_read_b128 v[212:215], v252 offset:2560
	s_waitcnt lgkmcnt(7)
	v_mfma_f32_16x16x32_bf16 v[156:159], v[216:219], v[80:83], v[156:159]
	v_mfma_f32_16x16x32_bf16 v[160:163], v[216:219], v[104:107], v[160:163]
	ds_read_b128 v[216:219], v252 offset:2624
	s_waitcnt lgkmcnt(7)
	v_mfma_f32_16x16x32_bf16 v[132:135], v[220:223], v[84:87], v[132:135]
	v_mfma_f32_16x16x32_bf16 v[136:139], v[220:223], v[108:111], v[136:139]
	ds_read_b128 v[220:223], v252 offset:5120
	s_waitcnt lgkmcnt(7)
	v_mfma_f32_16x16x32_bf16 v[140:143], v[224:227], v[84:87], v[140:143]
	v_mfma_f32_16x16x32_bf16 v[144:147], v[224:227], v[108:111], v[144:147]
	ds_read_b128 v[224:227], v252 offset:5184
	s_waitcnt lgkmcnt(7)
	v_mfma_f32_16x16x32_bf16 v[148:151], v[228:231], v[84:87], v[148:151]
	v_mfma_f32_16x16x32_bf16 v[152:155], v[228:231], v[108:111], v[152:155]
	ds_read_b128 v[228:231], v252 offset:7680
	s_waitcnt lgkmcnt(7)
	v_mfma_f32_16x16x32_bf16 v[156:159], v[232:235], v[84:87], v[156:159]
	v_mfma_f32_16x16x32_bf16 v[160:163], v[232:235], v[108:111], v[160:163]
	ds_read_b128 v[232:235], v252 offset:7744
	s_setprio 0
	s_nop 6
	v_max3_f32 v199, v132, v133, v134
	v_max3_f32 v200, v136, v137, v138
	v_max3_f32 v199, v199, v135, v140
	v_max3_f32 v200, v200, v139, v144
	v_max3_f32 v199, v199, v141, v142
	v_max3_f32 v200, v200, v145, v146
	v_max3_f32 v199, v199, v143, v148
	v_max3_f32 v200, v200, v147, v152
	v_max3_f32 v199, v199, v149, v150
	v_max3_f32 v200, v200, v153, v154
	v_max3_f32 v199, v199, v151, v156
	v_max3_f32 v200, v200, v155, v160
	v_max3_f32 v199, v199, v157, v158
	v_max3_f32 v200, v200, v161, v162
	v_max_f32_e32 v199, v199, v159
	v_max_f32_e32 v200, v200, v163
	v_mov_b32_e32 v253, v199
	v_mov_b32_e32 v201, v200
	s_nop 1
	v_permlane16_swap_b32_e32 v199, v253
	v_permlane16_swap_b32_e32 v200, v201
	s_nop 0
	v_max_f32_e32 v199, v199, v253
	v_max_f32_e32 v200, v200, v201
	v_mov_b32_e32 v253, v199
	v_mov_b32_e32 v201, v200
	s_nop 1
	v_permlane32_swap_b32_e32 v199, v253
	v_permlane32_swap_b32_e32 v200, v201
	s_nop 0
	v_max_f32_e32 v199, v199, v253
	v_max_f32_e32 v200, v200, v201
	v_max_f32_e32 v199, v177, v199
	v_max_f32_e32 v200, v178, v200
	v_sub_f32_e32 v182, v177, v199
	v_sub_f32_e32 v202, v178, v200
	v_exp_f32_e32 v182, v182
	v_exp_f32_e32 v202, v202
	v_mov_b32_e32 v177, v199
	v_mov_b32_e32 v178, v200
	v_sub_f32_e32 v132, v132, v177
	v_sub_f32_e32 v136, v136, v178
	v_sub_f32_e32 v133, v133, v177
	v_sub_f32_e32 v137, v137, v178
	v_sub_f32_e32 v134, v134, v177
	v_sub_f32_e32 v138, v138, v178
	v_sub_f32_e32 v135, v135, v177
	v_sub_f32_e32 v139, v139, v178
	v_sub_f32_e32 v140, v140, v177
	v_sub_f32_e32 v144, v144, v178
	v_sub_f32_e32 v141, v141, v177
	v_sub_f32_e32 v145, v145, v178
	v_sub_f32_e32 v142, v142, v177
	v_sub_f32_e32 v146, v146, v178
	v_sub_f32_e32 v143, v143, v177
	v_sub_f32_e32 v147, v147, v178
	v_sub_f32_e32 v148, v148, v177
	v_sub_f32_e32 v152, v152, v178
	v_sub_f32_e32 v149, v149, v177
	v_sub_f32_e32 v153, v153, v178
	v_sub_f32_e32 v150, v150, v177
	v_sub_f32_e32 v154, v154, v178
	v_sub_f32_e32 v151, v151, v177
	v_sub_f32_e32 v155, v155, v178
	v_sub_f32_e32 v156, v156, v177
	v_sub_f32_e32 v160, v160, v178
	v_sub_f32_e32 v157, v157, v177
	v_sub_f32_e32 v161, v161, v178
	v_sub_f32_e32 v158, v158, v177
	v_sub_f32_e32 v162, v162, v178
	v_sub_f32_e32 v159, v159, v177
	v_sub_f32_e32 v163, v163, v178
	v_exp_f32_e32 v132, v132
	v_exp_f32_e32 v136, v136
	v_exp_f32_e32 v133, v133
	v_exp_f32_e32 v137, v137
	v_exp_f32_e32 v134, v134
	v_exp_f32_e32 v138, v138
	v_exp_f32_e32 v135, v135
	v_exp_f32_e32 v139, v139
	v_exp_f32_e32 v140, v140
	v_exp_f32_e32 v144, v144
	v_exp_f32_e32 v141, v141
	v_exp_f32_e32 v145, v145
	v_exp_f32_e32 v142, v142
	v_exp_f32_e32 v146, v146
	v_exp_f32_e32 v143, v143
	v_exp_f32_e32 v147, v147
	v_exp_f32_e32 v148, v148
	v_exp_f32_e32 v152, v152
	v_exp_f32_e32 v149, v149
	v_exp_f32_e32 v153, v153
	v_exp_f32_e32 v150, v150
	v_exp_f32_e32 v154, v154
	v_exp_f32_e32 v151, v151
	v_exp_f32_e32 v155, v155
	v_exp_f32_e32 v156, v156
	v_exp_f32_e32 v160, v160
	v_exp_f32_e32 v157, v157
	v_exp_f32_e32 v161, v161
	v_exp_f32_e32 v158, v158
	v_exp_f32_e32 v162, v162
	v_exp_f32_e32 v159, v159
	v_exp_f32_e32 v163, v163
	v_cmp_eq_f32_e32 vcc, 1.0, v182
	s_cmp_eq_u64 vcc, exec
	s_cbranch_scc1 .Lat_noscale0_B0
	v_pk_mul_f32 v[0:1], v[0:1], v[182:183] op_sel_hi:[1,0]
	v_pk_mul_f32 v[2:3], v[2:3], v[182:183] op_sel_hi:[1,0]
	v_pk_mul_f32 v[8:9], v[8:9], v[182:183] op_sel_hi:[1,0]
	v_pk_mul_f32 v[10:11], v[10:11], v[182:183] op_sel_hi:[1,0]
	v_pk_mul_f32 v[16:17], v[16:17], v[182:183] op_sel_hi:[1,0]
	v_pk_mul_f32 v[18:19], v[18:19], v[182:183] op_sel_hi:[1,0]
	v_pk_mul_f32 v[24:25], v[24:25], v[182:183] op_sel_hi:[1,0]
	v_pk_mul_f32 v[26:27], v[26:27], v[182:183] op_sel_hi:[1,0]
	v_pk_mul_f32 v[32:33], v[32:33], v[182:183] op_sel_hi:[1,0]
	v_pk_mul_f32 v[34:35], v[34:35], v[182:183] op_sel_hi:[1,0]
	v_pk_mul_f32 v[40:41], v[40:41], v[182:183] op_sel_hi:[1,0]
	v_pk_mul_f32 v[42:43], v[42:43], v[182:183] op_sel_hi:[1,0]
	v_pk_mul_f32 v[48:49], v[48:49], v[182:183] op_sel_hi:[1,0]
	v_pk_mul_f32 v[50:51], v[50:51], v[182:183] op_sel_hi:[1,0]
	v_pk_mul_f32 v[56:57], v[56:57], v[182:183] op_sel_hi:[1,0]
	v_pk_mul_f32 v[58:59], v[58:59], v[182:183] op_sel_hi:[1,0]

.Lat_noscale1_B0:
	v_add_f32_e32 v183, v132, v133
	v_add_f32_e32 v203, v136, v137
	v_add_f32_e32 v183, v183, v134
	v_add_f32_e32 v203, v203, v138
	v_add_f32_e32 v183, v183, v135
	v_add_f32_e32 v203, v203, v139
	v_add_f32_e32 v183, v183, v140
	v_add_f32_e32 v203, v203, v144
	v_add_f32_e32 v183, v183, v141
	v_add_f32_e32 v203, v203, v145
	v_add_f32_e32 v183, v183, v142
	v_add_f32_e32 v203, v203, v146
	v_add_f32_e32 v183, v183, v143
	v_add_f32_e32 v203, v203, v147
	v_add_f32_e32 v183, v183, v148
	v_add_f32_e32 v203, v203, v152
	v_add_f32_e32 v183, v183, v149
	v_add_f32_e32 v203, v203, v153
	v_add_f32_e32 v183, v183, v150
	v_add_f32_e32 v203, v203, v154
	v_add_f32_e32 v183, v183, v151
	v_add_f32_e32 v203, v203, v155
	v_add_f32_e32 v183, v183, v156
	v_add_f32_e32 v203, v203, v160
	v_add_f32_e32 v183, v183, v157
	v_add_f32_e32 v203, v203, v161
	v_add_f32_e32 v183, v183, v158
	v_add_f32_e32 v203, v203, v162
	v_add_f32_e32 v183, v183, v159
	v_add_f32_e32 v203, v203, v163
	v_fmac_f32_e32 v183, v179, v182
	v_fmac_f32_e32 v203, v180, v202
	v_mov_b32_e32 v179, v183
	v_mov_b32_e32 v180, v203
	v_cvt_pk_bf16_f32 v236, v132, v133
	v_cvt_pk_bf16_f32 v237, v134, v135
	v_cvt_pk_bf16_f32 v238, v140, v141
	v_cvt_pk_bf16_f32 v239, v142, v143
	v_cvt_pk_bf16_f32 v244, v136, v137
	v_cvt_pk_bf16_f32 v245, v138, v139
	v_cvt_pk_bf16_f32 v246, v144, v145
	v_cvt_pk_bf16_f32 v247, v146, v147
	v_cvt_pk_bf16_f32 v240, v148, v149
	v_cvt_pk_bf16_f32 v241, v150, v151
	v_cvt_pk_bf16_f32 v242, v156, v157
	v_cvt_pk_bf16_f32 v243, v158, v159
	v_cvt_pk_bf16_f32 v248, v152, v153
	v_cvt_pk_bf16_f32 v249, v154, v155
	v_cvt_pk_bf16_f32 v250, v160, v161
	v_cvt_pk_bf16_f32 v251, v162, v163
	s_cmpk_lt_u32 s35, 67
	s_cbranch_scc0 .Lat_nostage_B0
	s_xor_b32 s12, s44, 26624
	v_add_u32_e32 v195, s12, v169
	v_add_u32_e32 v196, s12, v170
	v_add_u32_e32 v197, s13, v171
	v_add_u32_e32 v198, 10240, v197
	s_waitcnt vmcnt(0)
	ds_write_b128 v195, v[112:115]
	ds_write_b128 v195, v[116:119] offset:13312
	ds_write_b128 v196, v[120:123]
	ds_write2_b64 v197, v[124:125], v[126:127] offset1:2
	ds_write2_b64 v198, v[128:129], v[130:131] offset1:2
.Lat_nostage_B0:
	s_xor_b32 s44, s44, 26624
	s_mov_b32 s12, s0
	s_mov_b32 s0, s1
	s_mov_b32 s1, s13
	s_mov_b32 s13, s12
	s_add_u32 s35, s35, 1
	s_waitcnt lgkmcnt(0)
	s_barrier

.Lat_noload_B:
	v_add_u32_e32 v193, s44, v164
	v_add_u32_e32 v194, s0, v168
	v_add_u32_e32 v252, s1, v168
	s_setprio 1
	s_nop 0
	v_mfma_f32_16x16x32_bf16 v[0:3], v[204:207], v[236:239], v[0:3]
	v_mfma_f32_16x16x32_bf16 v[4:7], v[204:207], v[244:247], v[4:7]
	ds_read_b128 v[204:207], v194 offset:10240
	v_mfma_f32_16x16x32_bf16 v[0:3], v[208:211], v[240:243], v[0:3]
	v_mfma_f32_16x16x32_bf16 v[4:7], v[208:211], v[248:251], v[4:7]
	ds_read_b128 v[208:211], v194 offset:10304
	v_mfma_f32_16x16x32_bf16 v[8:11], v[212:215], v[236:239], v[8:11]
	v_mfma_f32_16x16x32_bf16 v[12:15], v[212:215], v[244:247], v[12:15]
	ds_read_b128 v[212:215], v194 offset:12800
	v_mfma_f32_16x16x32_bf16 v[8:11], v[216:219], v[240:243], v[8:11]
	v_mfma_f32_16x16x32_bf16 v[12:15], v[216:219], v[248:251], v[12:15]
	ds_read_b128 v[216:219], v194 offset:12864
	v_mfma_f32_16x16x32_bf16 v[16:19], v[220:223], v[236:239], v[16:19]
	v_mfma_f32_16x16x32_bf16 v[20:23], v[220:223], v[244:247], v[20:23]
	ds_read_b128 v[220:223], v194 offset:15360
	v_mfma_f32_16x16x32_bf16 v[16:19], v[224:227], v[240:243], v[16:19]
	v_mfma_f32_16x16x32_bf16 v[20:23], v[224:227], v[248:251], v[20:23]
	ds_read_b128 v[224:227], v194 offset:15424
	v_mfma_f32_16x16x32_bf16 v[24:27], v[228:231], v[236:239], v[24:27]
	v_mfma_f32_16x16x32_bf16 v[28:31], v[228:231], v[244:247], v[28:31]
	ds_read_b128 v[228:231], v194 offset:17920
	v_mfma_f32_16x16x32_bf16 v[24:27], v[232:235], v[240:243], v[24:27]
	v_mfma_f32_16x16x32_bf16 v[28:31], v[232:235], v[248:251], v[28:31]
	ds_read_b128 v[232:235], v194 offset:17984
	s_waitcnt lgkmcnt(7)
	v_mfma_f32_16x16x32_bf16 v[32:35], v[204:207], v[236:239], v[32:35]
	v_mfma_f32_16x16x32_bf16 v[36:39], v[204:207], v[244:247], v[36:39]
	ds_read_b128 v[204:207], v193
	s_waitcnt lgkmcnt(7)
	v_mfma_f32_16x16x32_bf16 v[32:35], v[208:211], v[240:243], v[32:35]
	v_mfma_f32_16x16x32_bf16 v[36:39], v[208:211], v[248:251], v[36:39]
	ds_read_b128 v[208:211], v193 offset:6656
	s_waitcnt lgkmcnt(7)
	v_mfma_f32_16x16x32_bf16 v[40:43], v[212:215], v[236:239], v[40:43]
	v_mfma_f32_16x16x32_bf16 v[44:47], v[212:215], v[244:247], v[44:47]
	ds_read_b128 v[212:215], v193 offset:13312
	s_waitcnt lgkmcnt(7)
	v_mfma_f32_16x16x32_bf16 v[40:43], v[216:219], v[240:243], v[40:43]
	v_mfma_f32_16x16x32_bf16 v[44:47], v[216:219], v[248:251], v[44:47]
	ds_read_b128 v[216:219], v193 offset:19968
	s_waitcnt lgkmcnt(7)
	v_mfma_f32_16x16x32_bf16 v[48:51], v[220:223], v[236:239], v[48:51]
	v_mfma_f32_16x16x32_bf16 v[52:55], v[220:223], v[244:247], v[52:55]
	ds_read_b128 v[220:223], v193 offset:64
	s_waitcnt lgkmcnt(7)
	v_mfma_f32_16x16x32_bf16 v[48:51], v[224:227], v[240:243], v[48:51]
	v_mfma_f32_16x16x32_bf16 v[52:55], v[224:227], v[248:251], v[52:55]
	ds_read_b128 v[224:227], v193 offset:6720
	s_waitcnt lgkmcnt(7)
	v_mfma_f32_16x16x32_bf16 v[56:59], v[228:231], v[236:239], v[56:59]
	v_mfma_f32_16x16x32_bf16 v[60:63], v[228:231], v[244:247], v[60:63]
	ds_read_b128 v[228:231], v193 offset:13376
	s_waitcnt lgkmcnt(7)
	v_mfma_f32_16x16x32_bf16 v[56:59], v[232:235], v[240:243], v[56:59]
	v_mfma_f32_16x16x32_bf16 v[60:63], v[232:235], v[248:251], v[60:63]
	ds_read_b128 v[232:235], v193 offset:20032
	s_setprio 0
	s_setprio 1
	s_waitcnt lgkmcnt(7)
	v_mfma_f32_16x16x32_bf16 v[132:135], v[204:207], v[64:67], 0
	v_mfma_f32_16x16x32_bf16 v[136:139], v[204:207], v[88:91], 0
	ds_read_b128 v[204:207], v193 offset:128
	s_waitcnt lgkmcnt(7)
	v_mfma_f32_16x16x32_bf16 v[140:143], v[208:211], v[64:67], 0
	v_mfma_f32_16x16x32_bf16 v[144:147], v[208:211], v[88:91], 0
	ds_read_b128 v[208:211], v193 offset:6784
	s_waitcnt lgkmcnt(7)
	v_mfma_f32_16x16x32_bf16 v[148:151], v[212:215], v[64:67], 0
	v_mfma_f32_16x16x32_bf16 v[152:155], v[212:215], v[88:91], 0
	ds_read_b128 v[212:215], v193 offset:13440
	s_waitcnt lgkmcnt(7)
	v_mfma_f32_16x16x32_bf16 v[156:159], v[216:219], v[64:67], 0
	v_mfma_f32_16x16x32_bf16 v[160:163], v[216:219], v[88:91], 0
	ds_read_b128 v[216:219], v193 offset:20096
	s_waitcnt lgkmcnt(7)
	v_mfma_f32_16x16x32_bf16 v[132:135], v[220:223], v[68:71], v[132:135]
	v_mfma_f32_16x16x32_bf16 v[136:139], v[220:223], v[92:95], v[136:139]
	ds_read_b128 v[220:223], v193 offset:192
	s_waitcnt lgkmcnt(7)
	v_mfma_f32_16x16x32_bf16 v[140:143], v[224:227], v[68:71], v[140:143]
	v_mfma_f32_16x16x32_bf16 v[144:147], v[224:227], v[92:95], v[144:147]
	ds_read_b128 v[224:227], v193 offset:6848
	s_waitcnt lgkmcnt(7)
	v_mfma_f32_16x16x32_bf16 v[148:151], v[228:231], v[68:71], v[148:151]
	v_mfma_f32_16x16x32_bf16 v[152:155], v[228:231], v[92:95], v[152:155]
	ds_read_b128 v[228:231], v193 offset:13504
	s_waitcnt lgkmcnt(7)
	v_mfma_f32_16x16x32_bf16 v[156:159], v[232:235], v[68:71], v[156:159]
	v_mfma_f32_16x16x32_bf16 v[160:163], v[232:235], v[92:95], v[160:163]
	ds_read_b128 v[232:235], v193 offset:20160
	s_waitcnt lgkmcnt(7)
	v_mfma_f32_16x16x32_bf16 v[132:135], v[204:207], v[72:75], v[132:135]
	v_mfma_f32_16x16x32_bf16 v[136:139], v[204:207], v[96:99], v[136:139]
	ds_read_b128 v[204:207], v193 offset:256
	s_waitcnt lgkmcnt(7)
	v_mfma_f32_16x16x32_bf16 v[140:143], v[208:211], v[72:75], v[140:143]
	v_mfma_f32_16x16x32_bf16 v[144:147], v[208:211], v[96:99], v[144:147]
	ds_read_b128 v[208:211], v193 offset:6912
	s_waitcnt lgkmcnt(7)
	v_mfma_f32_16x16x32_bf16 v[148:151], v[212:215], v[72:75], v[148:151]
	v_mfma_f32_16x16x32_bf16 v[152:155], v[212:215], v[96:99], v[152:155]
	ds_read_b128 v[212:215], v193 offset:13568
	s_waitcnt lgkmcnt(7)
	v_mfma_f32_16x16x32_bf16 v[156:159], v[216:219], v[72:75], v[156:159]
	v_mfma_f32_16x16x32_bf16 v[160:163], v[216:219], v[96:99], v[160:163]
	ds_read_b128 v[216:219], v193 offset:20224
	s_waitcnt lgkmcnt(7)
	v_mfma_f32_16x16x32_bf16 v[132:135], v[220:223], v[76:79], v[132:135]
	v_mfma_f32_16x16x32_bf16 v[136:139], v[220:223], v[100:103], v[136:139]
	ds_read_b128 v[220:223], v193 offset:320
	s_waitcnt lgkmcnt(7)
	v_mfma_f32_16x16x32_bf16 v[140:143], v[224:227], v[76:79], v[140:143]
	v_mfma_f32_16x16x32_bf16 v[144:147], v[224:227], v[100:103], v[144:147]
	ds_read_b128 v[224:227], v193 offset:6976
	s_waitcnt lgkmcnt(7)
	v_mfma_f32_16x16x32_bf16 v[148:151], v[228:231], v[76:79], v[148:151]
	v_mfma_f32_16x16x32_bf16 v[152:155], v[228:231], v[100:103], v[152:155]
	ds_read_b128 v[228:231], v193 offset:13632
	s_waitcnt lgkmcnt(7)
	v_mfma_f32_16x16x32_bf16 v[156:159], v[232:235], v[76:79], v[156:159]
	v_mfma_f32_16x16x32_bf16 v[160:163], v[232:235], v[100:103], v[160:163]
	ds_read_b128 v[232:235], v193 offset:20288
	s_waitcnt lgkmcnt(7)
	v_mfma_f32_16x16x32_bf16 v[132:135], v[204:207], v[80:83], v[132:135]
	v_mfma_f32_16x16x32_bf16 v[136:139], v[204:207], v[104:107], v[136:139]
	ds_read_b128 v[204:207], v252
	s_waitcnt lgkmcnt(7)
	v_mfma_f32_16x16x32_bf16 v[140:143], v[208:211], v[80:83], v[140:143]
	v_mfma_f32_16x16x32_bf16 v[144:147], v[208:211], v[104:107], v[144:147]
	ds_read_b128 v[208:211], v252 offset:64
	s_waitcnt lgkmcnt(7)
	v_mfma_f32_16x16x32_bf16 v[148:151], v[212:215], v[80:83], v[148:151]
	v_mfma_f32_16x16x32_bf16 v[152:155], v[212:215], v[104:107], v[152:155]
	ds_read_b128 v[212:215], v252 offset:2560
	s_waitcnt lgkmcnt(7)
	v_mfma_f32_16x16x32_bf16 v[156:159], v[216:219], v[80:83], v[156:159]
	v_mfma_f32_16x16x32_bf16 v[160:163], v[216:219], v[104:107], v[160:163]
	ds_read_b128 v[216:219], v252 offset:2624
	s_waitcnt lgkmcnt(7)
	v_mfma_f32_16x16x32_bf16 v[132:135], v[220:223], v[84:87], v[132:135]
	v_mfma_f32_16x16x32_bf16 v[136:139], v[220:223], v[108:111], v[136:139]
	ds_read_b128 v[220:223], v252 offset:5120
	s_waitcnt lgkmcnt(7)
	v_mfma_f32_16x16x32_bf16 v[140:143], v[224:227], v[84:87], v[140:143]
	v_mfma_f32_16x16x32_bf16 v[144:147], v[224:227], v[108:111], v[144:147]
	ds_read_b128 v[224:227], v252 offset:5184
	s_waitcnt lgkmcnt(7)
	v_mfma_f32_16x16x32_bf16 v[148:151], v[228:231], v[84:87], v[148:151]
	v_mfma_f32_16x16x32_bf16 v[152:155], v[228:231], v[108:111], v[152:155]
	ds_read_b128 v[228:231], v252 offset:7680
	s_waitcnt lgkmcnt(7)
	v_mfma_f32_16x16x32_bf16 v[156:159], v[232:235], v[84:87], v[156:159]
	v_mfma_f32_16x16x32_bf16 v[160:163], v[232:235], v[108:111], v[160:163]
	ds_read_b128 v[232:235], v252 offset:7744
	s_setprio 0
	s_nop 6
	v_max3_f32 v199, v132, v133, v134
	v_max3_f32 v200, v136, v137, v138
	v_max3_f32 v199, v199, v135, v140
	v_max3_f32 v200, v200, v139, v144
	v_max3_f32 v199, v199, v141, v142
	v_max3_f32 v200, v200, v145, v146
	v_max3_f32 v199, v199, v143, v148
	v_max3_f32 v200, v200, v147, v152
	v_max3_f32 v199, v199, v149, v150
	v_max3_f32 v200, v200, v153, v154
	v_max3_f32 v199, v199, v151, v156
	v_max3_f32 v200, v200, v155, v160
	v_max3_f32 v199, v199, v157, v158
	v_max3_f32 v200, v200, v161, v162
	v_max_f32_e32 v199, v199, v159
	v_max_f32_e32 v200, v200, v163
	v_mov_b32_e32 v253, v199
	v_mov_b32_e32 v201, v200
	s_nop 1
	v_permlane16_swap_b32_e32 v199, v253
	v_permlane16_swap_b32_e32 v200, v201
	s_nop 0
	v_max_f32_e32 v199, v199, v253
	v_max_f32_e32 v200, v200, v201
	v_mov_b32_e32 v253, v199
	v_mov_b32_e32 v201, v200
	s_nop 1
	v_permlane32_swap_b32_e32 v199, v253
	v_permlane32_swap_b32_e32 v200, v201
	s_nop 0
	v_max_f32_e32 v199, v199, v253
	v_max_f32_e32 v200, v200, v201
	v_max_f32_e32 v199, v177, v199
	v_max_f32_e32 v200, v178, v200
	v_sub_f32_e32 v182, v177, v199
	v_sub_f32_e32 v202, v178, v200
	v_exp_f32_e32 v182, v182
	v_exp_f32_e32 v202, v202
	v_mov_b32_e32 v177, v199
	v_mov_b32_e32 v178, v200
	v_sub_f32_e32 v132, v132, v177
	v_sub_f32_e32 v136, v136, v178
	v_sub_f32_e32 v133, v133, v177
	v_sub_f32_e32 v137, v137, v178
	v_sub_f32_e32 v134, v134, v177
	v_sub_f32_e32 v138, v138, v178
	v_sub_f32_e32 v135, v135, v177
	v_sub_f32_e32 v139, v139, v178
	v_sub_f32_e32 v140, v140, v177
	v_sub_f32_e32 v144, v144, v178
	v_sub_f32_e32 v141, v141, v177
	v_sub_f32_e32 v145, v145, v178
	v_sub_f32_e32 v142, v142, v177
	v_sub_f32_e32 v146, v146, v178
	v_sub_f32_e32 v143, v143, v177
	v_sub_f32_e32 v147, v147, v178
	v_sub_f32_e32 v148, v148, v177
	v_sub_f32_e32 v152, v152, v178
	v_sub_f32_e32 v149, v149, v177
	v_sub_f32_e32 v153, v153, v178
	v_sub_f32_e32 v150, v150, v177
	v_sub_f32_e32 v154, v154, v178
	v_sub_f32_e32 v151, v151, v177
	v_sub_f32_e32 v155, v155, v178
	v_sub_f32_e32 v156, v156, v177
	v_sub_f32_e32 v160, v160, v178
	v_sub_f32_e32 v157, v157, v177
	v_sub_f32_e32 v161, v161, v178
	v_sub_f32_e32 v158, v158, v177
	v_sub_f32_e32 v162, v162, v178
	v_sub_f32_e32 v159, v159, v177
	v_sub_f32_e32 v163, v163, v178
	v_exp_f32_e32 v132, v132
	v_exp_f32_e32 v136, v136
	v_exp_f32_e32 v133, v133
	v_exp_f32_e32 v137, v137
	v_exp_f32_e32 v134, v134
	v_exp_f32_e32 v138, v138
	v_exp_f32_e32 v135, v135
	v_exp_f32_e32 v139, v139
	v_exp_f32_e32 v140, v140
	v_exp_f32_e32 v144, v144
	v_exp_f32_e32 v141, v141
	v_exp_f32_e32 v145, v145
	v_exp_f32_e32 v142, v142
	v_exp_f32_e32 v146, v146
	v_exp_f32_e32 v143, v143
	v_exp_f32_e32 v147, v147
	v_exp_f32_e32 v148, v148
	v_exp_f32_e32 v152, v152
	v_exp_f32_e32 v149, v149
	v_exp_f32_e32 v153, v153
	v_exp_f32_e32 v150, v150
	v_exp_f32_e32 v154, v154
	v_exp_f32_e32 v151, v151
	v_exp_f32_e32 v155, v155
	v_exp_f32_e32 v156, v156
	v_exp_f32_e32 v160, v160
	v_exp_f32_e32 v157, v157
	v_exp_f32_e32 v161, v161
	v_exp_f32_e32 v158, v158
	v_exp_f32_e32 v162, v162
	v_exp_f32_e32 v159, v159
	v_exp_f32_e32 v163, v163
	v_cmp_eq_f32_e32 vcc, 1.0, v182
	s_cmp_eq_u64 vcc, exec
	s_cbranch_scc1 .Lat_noscale0_B
	v_pk_mul_f32 v[0:1], v[0:1], v[182:183] op_sel_hi:[1,0]
	v_pk_mul_f32 v[2:3], v[2:3], v[182:183] op_sel_hi:[1,0]
	v_pk_mul_f32 v[8:9], v[8:9], v[182:183] op_sel_hi:[1,0]
	v_pk_mul_f32 v[10:11], v[10:11], v[182:183] op_sel_hi:[1,0]
	v_pk_mul_f32 v[16:17], v[16:17], v[182:183] op_sel_hi:[1,0]
	v_pk_mul_f32 v[18:19], v[18:19], v[182:183] op_sel_hi:[1,0]
	v_pk_mul_f32 v[24:25], v[24:25], v[182:183] op_sel_hi:[1,0]
	v_pk_mul_f32 v[26:27], v[26:27], v[182:183] op_sel_hi:[1,0]
	v_pk_mul_f32 v[32:33], v[32:33], v[182:183] op_sel_hi:[1,0]
	v_pk_mul_f32 v[34:35], v[34:35], v[182:183] op_sel_hi:[1,0]
	v_pk_mul_f32 v[40:41], v[40:41], v[182:183] op_sel_hi:[1,0]
	v_pk_mul_f32 v[42:43], v[42:43], v[182:183] op_sel_hi:[1,0]
	v_pk_mul_f32 v[48:49], v[48:49], v[182:183] op_sel_hi:[1,0]
	v_pk_mul_f32 v[50:51], v[50:51], v[182:183] op_sel_hi:[1,0]
	v_pk_mul_f32 v[56:57], v[56:57], v[182:183] op_sel_hi:[1,0]
	v_pk_mul_f32 v[58:59], v[58:59], v[182:183] op_sel_hi:[1,0]

.Lat_nostage_B:
	s_xor_b32 s44, s44, 26624
	s_mov_b32 s12, s0
	s_mov_b32 s0, s1
	s_mov_b32 s1, s13
	s_mov_b32 s13, s12
	s_add_u32 s35, s35, 1
	s_waitcnt lgkmcnt(0)
	s_barrier
	s_cmpk_lt_u32 s35, 68
	s_cbranch_scc1 .Lat_B_loop
	v_add_u32_e32 v194, s0, v168
	s_setprio 1
	s_nop 0
	v_mfma_f32_16x16x32_bf16 v[0:3], v[204:207], v[236:239], v[0:3]
	v_mfma_f32_16x16x32_bf16 v[4:7], v[204:207], v[244:247], v[4:7]
	ds_read_b128 v[204:207], v194 offset:10240
	v_mfma_f32_16x16x32_bf16 v[0:3], v[208:211], v[240:243], v[0:3]
	v_mfma_f32_16x16x32_bf16 v[4:7], v[208:211], v[248:251], v[4:7]
	ds_read_b128 v[208:211], v194 offset:10304
	v_mfma_f32_16x16x32_bf16 v[8:11], v[212:215], v[236:239], v[8:11]
	v_mfma_f32_16x16x32_bf16 v[12:15], v[212:215], v[244:247], v[12:15]
	ds_read_b128 v[212:215], v194 offset:12800
	v_mfma_f32_16x16x32_bf16 v[8:11], v[216:219], v[240:243], v[8:11]
	v_mfma_f32_16x16x32_bf16 v[12:15], v[216:219], v[248:251], v[12:15]
	ds_read_b128 v[216:219], v194 offset:12864
	v_mfma_f32_16x16x32_bf16 v[16:19], v[220:223], v[236:239], v[16:19]
	v_mfma_f32_16x16x32_bf16 v[20:23], v[220:223], v[244:247], v[20:23]
	ds_read_b128 v[220:223], v194 offset:15360
	v_mfma_f32_16x16x32_bf16 v[16:19], v[224:227], v[240:243], v[16:19]
	v_mfma_f32_16x16x32_bf16 v[20:23], v[224:227], v[248:251], v[20:23]
	ds_read_b128 v[224:227], v194 offset:15424
	v_mfma_f32_16x16x32_bf16 v[24:27], v[228:231], v[236:239], v[24:27]
	v_mfma_f32_16x16x32_bf16 v[28:31], v[228:231], v[244:247], v[28:31]
	ds_read_b128 v[228:231], v194 offset:17920
	v_mfma_f32_16x16x32_bf16 v[24:27], v[232:235], v[240:243], v[24:27]
	v_mfma_f32_16x16x32_bf16 v[28:31], v[232:235], v[248:251], v[28:31]
	ds_read_b128 v[232:235], v194 offset:17984
	s_waitcnt lgkmcnt(7)
	v_mfma_f32_16x16x32_bf16 v[32:35], v[204:207], v[236:239], v[32:35]
	v_mfma_f32_16x16x32_bf16 v[36:39], v[204:207], v[244:247], v[36:39]
	s_waitcnt lgkmcnt(6)
	v_mfma_f32_16x16x32_bf16 v[32:35], v[208:211], v[240:243], v[32:35]
	v_mfma_f32_16x16x32_bf16 v[36:39], v[208:211], v[248:251], v[36:39]
	s_waitcnt lgkmcnt(5)
	v_mfma_f32_16x16x32_bf16 v[40:43], v[212:215], v[236:239], v[40:43]
	v_mfma_f32_16x16x32_bf16 v[44:47], v[212:215], v[244:247], v[44:47]
	s_waitcnt lgkmcnt(4)
	v_mfma_f32_16x16x32_bf16 v[40:43], v[216:219], v[240:243], v[40:43]
	v_mfma_f32_16x16x32_bf16 v[44:47], v[216:219], v[248:251], v[44:47]
	s_waitcnt lgkmcnt(3)
	v_mfma_f32_16x16x32_bf16 v[48:51], v[220:223], v[236:239], v[48:51]
	v_mfma_f32_16x16x32_bf16 v[52:55], v[220:223], v[244:247], v[52:55]
	s_waitcnt lgkmcnt(2)
	v_mfma_f32_16x16x32_bf16 v[48:51], v[224:227], v[240:243], v[48:51]
	v_mfma_f32_16x16x32_bf16 v[52:55], v[224:227], v[248:251], v[52:55]
	s_waitcnt lgkmcnt(1)
	v_mfma_f32_16x16x32_bf16 v[56:59], v[228:231], v[236:239], v[56:59]
	v_mfma_f32_16x16x32_bf16 v[60:63], v[228:231], v[244:247], v[60:63]
	s_waitcnt lgkmcnt(0)
	v_mfma_f32_16x16x32_bf16 v[56:59], v[232:235], v[240:243], v[56:59]
	v_mfma_f32_16x16x32_bf16 v[60:63], v[232:235], v[248:251], v[60:63]
	s_setprio 0
	s_waitcnt lgkmcnt(0)
.Lat_join:
	s_barrier
	v_mov_b32_e32 v253, v179
	v_mov_b32_e32 v201, v180
	s_nop 1
	v_permlane16_swap_b32_e32 v179, v253
	v_permlane16_swap_b32_e32 v180, v201
	s_nop 0
	v_add_f32_e32 v179, v179, v253
	v_add_f32_e32 v180, v180, v201
	v_mov_b32_e32 v253, v179
	v_mov_b32_e32 v201, v180
	s_nop 1
	v_permlane32_swap_b32_e32 v179, v253
	v_permlane32_swap_b32_e32 v180, v201
	s_nop 0
	v_add_f32_e32 v179, v179, v253
	v_add_f32_e32 v180, v180, v201
	v_div_scale_f32 v64, s[0:1], v179, v179, 1.0
	v_rcp_f32_e32 v65, v64
	s_nop 0
	v_fma_f32 v66, -v64, v65, 1.0
	v_fmac_f32_e32 v65, v66, v65
	v_div_scale_f32 v66, vcc, 1.0, v179, 1.0
	v_mul_f32_e32 v67, v66, v65
	v_fma_f32 v68, -v64, v67, v66
	v_fmac_f32_e32 v67, v68, v65
	v_fma_f32 v64, -v64, v67, v66
	s_nop 0
	v_div_fmas_f32 v64, v64, v65, v67
	v_div_fixup_f32 v199, v64, v179, 1.0
	v_div_scale_f32 v64, s[0:1], v180, v180, 1.0
	v_rcp_f32_e32 v65, v64
	s_nop 0
	v_fma_f32 v66, -v64, v65, 1.0
	v_fmac_f32_e32 v65, v66, v65
	v_div_scale_f32 v66, vcc, 1.0, v180, 1.0
	v_mul_f32_e32 v67, v66, v65
	v_fma_f32 v68, -v64, v67, v66
	v_fmac_f32_e32 v67, v68, v65
	v_fma_f32 v64, -v64, v67, v66
	s_nop 0
	v_div_fmas_f32 v64, v64, v65, v67
	v_div_fixup_f32 v200, v64, v180, 1.0
	s_and_b32 s0, s34, 7
	s_ashr_i32 s12, s34, 7
	s_lshl_b32 s13, s34, 5
	s_and_b32 s13, s13, 0xf00
	s_lshl_b32 s1, s12, 12
	s_or_b32 s13, s13, s1
	s_lshl_b32 s13, s13, 12
	s_lshl_b32 s0, s0, 8
	s_add_u32 s13, s13, s0
	s_add_u32 s0, s10, s13
	s_addc_u32 s1, s11, 0
	v_and_b32_e32 v73, 15, v167
	v_lshrrev_b32_e32 v72, 6, v167
	v_lshl_add_u32 v72, v72, 5, v73
	v_lshlrev_b32_e32 v72, 12, v72
	v_bfe_u32 v73, v167, 4, 2
	v_lshl_add_u32 v72, v73, 3, v72
	v_add_u32_e32 v73, 0x10000, v72
	v_mul_f32_e32 v0, v0, v199
	v_mul_f32_e32 v1, v1, v199
	v_mul_f32_e32 v2, v2, v199
	v_mul_f32_e32 v3, v3, v199
	v_cvt_pk_bf16_f32 v0, v0, v1
	v_cvt_pk_bf16_f32 v1, v2, v3
	global_store_dwordx2 v72, v[0:1], s[0:1]
	v_mul_f32_e32 v8, v8, v199
	v_mul_f32_e32 v9, v9, v199
	v_mul_f32_e32 v10, v10, v199
	v_mul_f32_e32 v11, v11, v199
	v_cvt_pk_bf16_f32 v8, v8, v9
	v_cvt_pk_bf16_f32 v9, v10, v11
	global_store_dwordx2 v72, v[8:9], s[0:1] offset:32
	v_mul_f32_e32 v16, v16, v199
	v_mul_f32_e32 v17, v17, v199
	v_mul_f32_e32 v18, v18, v199
	v_mul_f32_e32 v19, v19, v199
	v_cvt_pk_bf16_f32 v16, v16, v17
	v_cvt_pk_bf16_f32 v17, v18, v19
	global_store_dwordx2 v72, v[16:17], s[0:1] offset:64
	v_mul_f32_e32 v24, v24, v199
	v_mul_f32_e32 v25, v25, v199
	v_mul_f32_e32 v26, v26, v199
	v_mul_f32_e32 v27, v27, v199
	v_cvt_pk_bf16_f32 v24, v24, v25
	v_cvt_pk_bf16_f32 v25, v26, v27
	global_store_dwordx2 v72, v[24:25], s[0:1] offset:96
	v_mul_f32_e32 v32, v32, v199
	v_mul_f32_e32 v33, v33, v199
	v_mul_f32_e32 v34, v34, v199
	v_mul_f32_e32 v35, v35, v199
	v_cvt_pk_bf16_f32 v32, v32, v33
	v_cvt_pk_bf16_f32 v33, v34, v35
	global_store_dwordx2 v72, v[32:33], s[0:1] offset:128
	v_mul_f32_e32 v40, v40, v199
	v_mul_f32_e32 v41, v41, v199
	v_mul_f32_e32 v42, v42, v199
	v_mul_f32_e32 v43, v43, v199
	v_cvt_pk_bf16_f32 v40, v40, v41
	v_cvt_pk_bf16_f32 v41, v42, v43
	global_store_dwordx2 v72, v[40:41], s[0:1] offset:160
	v_mul_f32_e32 v48, v48, v199
	v_mul_f32_e32 v49, v49, v199
	v_mul_f32_e32 v50, v50, v199
	v_mul_f32_e32 v51, v51, v199
	v_cvt_pk_bf16_f32 v48, v48, v49
	v_cvt_pk_bf16_f32 v49, v50, v51
	global_store_dwordx2 v72, v[48:49], s[0:1] offset:192
	v_mul_f32_e32 v56, v56, v199
	v_mul_f32_e32 v57, v57, v199
	v_mul_f32_e32 v58, v58, v199
	v_mul_f32_e32 v59, v59, v199
	v_cvt_pk_bf16_f32 v56, v56, v57
	v_cvt_pk_bf16_f32 v57, v58, v59
	global_store_dwordx2 v72, v[56:57], s[0:1] offset:224
	v_mul_f32_e32 v4, v4, v200
	v_mul_f32_e32 v5, v5, v200
	v_mul_f32_e32 v6, v6, v200
	v_mul_f32_e32 v7, v7, v200
	v_cvt_pk_bf16_f32 v4, v4, v5
	v_cvt_pk_bf16_f32 v5, v6, v7
	global_store_dwordx2 v73, v[4:5], s[0:1]
	v_mul_f32_e32 v12, v12, v200
	v_mul_f32_e32 v13, v13, v200
	v_mul_f32_e32 v14, v14, v200
	v_mul_f32_e32 v15, v15, v200
	v_cvt_pk_bf16_f32 v12, v12, v13
	v_cvt_pk_bf16_f32 v13, v14, v15
	global_store_dwordx2 v73, v[12:13], s[0:1] offset:32
	v_mul_f32_e32 v20, v20, v200
	v_mul_f32_e32 v21, v21, v200
	v_mul_f32_e32 v22, v22, v200
	v_mul_f32_e32 v23, v23, v200
	v_cvt_pk_bf16_f32 v20, v20, v21
	v_cvt_pk_bf16_f32 v21, v22, v23
	global_store_dwordx2 v73, v[20:21], s[0:1] offset:64
	v_mul_f32_e32 v28, v28, v200
	v_mul_f32_e32 v29, v29, v200
	v_mul_f32_e32 v30, v30, v200
	v_mul_f32_e32 v31, v31, v200
	v_cvt_pk_bf16_f32 v28, v28, v29
	v_cvt_pk_bf16_f32 v29, v30, v31
	global_store_dwordx2 v73, v[28:29], s[0:1] offset:96
	v_mul_f32_e32 v36, v36, v200
	v_mul_f32_e32 v37, v37, v200
	v_mul_f32_e32 v38, v38, v200
	v_mul_f32_e32 v39, v39, v200
	v_cvt_pk_bf16_f32 v36, v36, v37
	v_cvt_pk_bf16_f32 v37, v38, v39
	global_store_dwordx2 v73, v[36:37], s[0:1] offset:128
	v_mul_f32_e32 v44, v44, v200
	v_mul_f32_e32 v45, v45, v200
	v_mul_f32_e32 v46, v46, v200
	v_mul_f32_e32 v47, v47, v200
	v_cvt_pk_bf16_f32 v44, v44, v45
	v_cvt_pk_bf16_f32 v45, v46, v47
	global_store_dwordx2 v73, v[44:45], s[0:1] offset:160
	v_mul_f32_e32 v52, v52, v200
	v_mul_f32_e32 v53, v53, v200
	v_mul_f32_e32 v54, v54, v200
	v_mul_f32_e32 v55, v55, v200
	v_cvt_pk_bf16_f32 v52, v52, v53
	v_cvt_pk_bf16_f32 v53, v54, v55
	global_store_dwordx2 v73, v[52:53], s[0:1] offset:192
	v_mul_f32_e32 v60, v60, v200
	v_mul_f32_e32 v61, v61, v200
	v_mul_f32_e32 v62, v62, v200
	v_mul_f32_e32 v63, v63, v200
	v_cvt_pk_bf16_f32 v60, v60, v61
	v_cvt_pk_bf16_f32 v61, v62, v63
	global_store_dwordx2 v73, v[60:61], s[0:1] offset:224
	v_readlane_b32 s0, v254, 1
	s_add_i32 s34, s34, s0
	s_add_i32 s9, s9, s0
	s_add_i32 s8, s8, s0
	s_cmp_lt_i32 s34, s40
	v_readlane_b32 s1, v254, 2
	s_cbranch_scc0 .LBB0_1033
	s_branch .LBB0_1008
